# GEMM K-loops: removed the duplicate s_waitcnt lgkmcnt(0) at the head of each MFMA cluster (already satisfied by the wait before the barrier; 32 sites)
# speedup vs baseline: 1.0053x; 1.0053x over previous
; #define PG8_STAGE(bufoff, gbase, voff) do { _Pragma("unroll") for (int _i = 0; _i < 2; ++_i) \
;         __builtin_amdgcn_global_load_lds((const unsigned*)((const char*)(gbase) + (voff)[_i]), (PG8_LAS unsigned*)(lds + (bufoff) + ldsw + _i * 8192), 16, 0, 0); } while (0)
; #define PG8_LDA(dst, b, h) do { _Pragma("unroll") for (int m = 0; m < 4; ++m) _Pragma("unroll") for (int k = 0; k < 2; ++k) dst[m][k] = *(const PG8_LAS bf16x8*)(lds + PG8_SA(b, h) + aoff + m * 2048 + k * 1024); } while (0)
; #define PG8_LDB(dst, b, h) do { _Pragma("unroll") for (int n = 0; n < 2; ++n) _Pragma("unroll") for (int k = 0; k < 2; ++k) dst[n][k] = *(const PG8_LAS bf16x8*)(lds + PG8_SB(b, h) + boff + n * 2048 + k * 1024); } while (0)
; template <class Epi, class Sched, bool ALIGN_EPI = false, bool SP2 = false>
; __device__ __forceinline__ void gemm_phase(PG8_LAS unsigned char* lds, const Gemm g, const Sched& S, const Epi& E) {
;     ...
;         for (int t = 0; t < ntc; t += 2) {
;             const bool last = (t == ntc - 2);
;             const char* a1 = cA + (size_t)(t + 1) * kstep;
;             const char* a2 = last ? nA : cA + (size_t)(t + 2) * kstep; const char* b2 = last ? nB : cB + (size_t)(t + 2) * kstep;
;             const char* a3 = a2 + kstep; const char* b3 = b2 + kstep;
;             if (last && has_next) S.a_ready(nxt);
;             if constexpr (SP2) {
;             PG8_LDB(B0, 0, 0); PG8_LDB(B1, 0, 1); PG8_SCHED; PG8_LDA(At, 0, 0); PG8_STAGE(PG8_SA(1, 1), a1 + hstepA, voffA);
;             PG8_WAIT_V(8); PG8_WAIT_L(0); PG8_BAR; PG8_MMA(0, 0, At, B0); PG8_MMA(0, 1, At, B1); PG8_BAR; PG8_SCHED;
;             PG8_LDA(At, 0, 1); PG8_STAGE(PG8_SB(0, 0), b2, voffB); PG8_STAGE(PG8_SB(0, 1), b2 + hstepB, voffB); PG8_STAGE(PG8_SA(0, 0), a2, voffA);
;             PG8_WAIT_V(8); PG8_WAIT_L(0); PG8_BAR; PG8_MMA(1, 0, At, B0); PG8_MMA(1, 1, At, B1); PG8_BAR; PG8_SCHED;
;             PG8_LDB(B0, 1, 0); PG8_LDB(B1, 1, 1); PG8_SCHED; PG8_LDA(At, 1, 0); PG8_STAGE(PG8_SA(0, 1), a2 + hstepA, voffA);
;             PG8_WAIT_V(8); PG8_WAIT_L(0); PG8_BAR; PG8_MMA(0, 0, At, B0); PG8_MMA(0, 1, At, B1); PG8_BAR; PG8_SCHED;
;             PG8_LDA(At, 1, 1); PG8_STAGE(PG8_SB(1, 0), b3, voffB); PG8_STAGE(PG8_SB(1, 1), b3 + hstepB, voffB); PG8_STAGE(PG8_SA(1, 0), a3, voffA);
;             PG8_WAIT_V(8); PG8_WAIT_L(0); PG8_BAR; PG8_MMA(1, 0, At, B0); PG8_MMA(1, 1, At, B1); PG8_BAR; PG8_SCHED;
.LBB0_200:
	s_add_i32 s47, s24, 2
	s_add_u32 s25, s4, 0xfffc0080
	s_addc_u32 s26, s5, -1
	s_add_i32 s48, 0, 0x10000
	s_cmp_eq_u32 s39, s24
	s_cselect_b32 s27, s17, s26
	s_cselect_b32 s26, s19, s25
	s_cselect_b32 s25, s43, s46
	s_cselect_b32 s24, s44, s45
	s_add_i32 s50, 0, 0x14000
	v_add_u32_e32 v102, s48, v177
	v_add_u32_e32 v126, s50, v177
	ds_read_b128 v[86:89], v102
	ds_read_b128 v[94:97], v102 offset:1024
	ds_read_b128 v[98:101], v102 offset:2048
	ds_read_b128 v[102:105], v102 offset:3072
	ds_read_b128 v[106:109], v126
	ds_read_b128 v[110:113], v126 offset:1024
	ds_read_b128 v[118:121], v126 offset:2048
	ds_read_b128 v[126:129], v126 offset:3072
	s_add_i32 m0, s30, 0xc000
	ds_read_b128 v[202:205], v179
	ds_read_b128 v[206:209], v179 offset:1024
	ds_read_b128 v[210:213], v179 offset:2048
	ds_read_b128 v[214:217], v179 offset:3072
	ds_read_b128 v[218:221], v179 offset:4096
	ds_read_b128 v[222:225], v179 offset:5120
	ds_read_b128 v[240:243], v179 offset:6144
	ds_read_b128 v[244:247], v179 offset:7168
	global_load_lds_dwordx4 v168, s[4:5]
	s_add_i32 m0, s30, 0xe000
	s_nop 0
	global_load_lds_dwordx4 v170, s[4:5]
	s_waitcnt vmcnt(8)
	s_waitcnt lgkmcnt(0)
	s_barrier
	s_setprio 1
	v_mfma_f32_16x16x32_bf16 v[158:161], v[86:89], v[202:205], v[158:161]
	v_mfma_f32_16x16x32_bf16 v[150:153], v[98:101], v[202:205], v[150:153]
	v_mfma_f32_16x16x32_bf16 v[142:145], v[86:89], v[210:213], v[142:145]
	v_mfma_f32_16x16x32_bf16 v[134:137], v[98:101], v[210:213], v[134:137]
	v_mfma_f32_16x16x32_bf16 v[122:125], v[86:89], v[218:221], v[122:125]
	v_mfma_f32_16x16x32_bf16 v[90:93], v[98:101], v[218:221], v[90:93]
	v_mfma_f32_16x16x32_bf16 v[78:81], v[86:89], v[240:243], v[78:81]
	v_mfma_f32_16x16x32_bf16 v[70:73], v[98:101], v[240:243], v[70:73]
	v_mfma_f32_16x16x32_bf16 v[158:161], v[94:97], v[206:209], v[158:161]
	v_mfma_f32_16x16x32_bf16 v[150:153], v[102:105], v[206:209], v[150:153]
	v_mfma_f32_16x16x32_bf16 v[142:145], v[94:97], v[214:217], v[142:145]
	v_mfma_f32_16x16x32_bf16 v[134:137], v[102:105], v[214:217], v[134:137]
	v_mfma_f32_16x16x32_bf16 v[122:125], v[94:97], v[222:225], v[122:125]
	v_mfma_f32_16x16x32_bf16 v[90:93], v[102:105], v[222:225], v[90:93]
	v_mfma_f32_16x16x32_bf16 v[78:81], v[94:97], v[244:247], v[78:81]
	v_mfma_f32_16x16x32_bf16 v[70:73], v[102:105], v[244:247], v[70:73]
	s_setprio 0
	s_setprio 1
	v_mfma_f32_16x16x32_bf16 v[154:157], v[106:109], v[202:205], v[154:157]
	v_mfma_f32_16x16x32_bf16 v[146:149], v[118:121], v[202:205], v[146:149]
	v_mfma_f32_16x16x32_bf16 v[138:141], v[106:109], v[210:213], v[138:141]
	v_mfma_f32_16x16x32_bf16 v[130:133], v[118:121], v[210:213], v[130:133]
	v_mfma_f32_16x16x32_bf16 v[114:117], v[106:109], v[218:221], v[114:117]
	v_mfma_f32_16x16x32_bf16 v[82:85], v[118:121], v[218:221], v[82:85]
	v_mfma_f32_16x16x32_bf16 v[74:77], v[106:109], v[240:243], v[74:77]
	v_mfma_f32_16x16x32_bf16 v[66:69], v[118:121], v[240:243], v[66:69]
	v_mfma_f32_16x16x32_bf16 v[154:157], v[110:113], v[206:209], v[154:157]
	v_mfma_f32_16x16x32_bf16 v[146:149], v[126:129], v[206:209], v[146:149]
	v_mfma_f32_16x16x32_bf16 v[138:141], v[110:113], v[214:217], v[138:141]
	v_mfma_f32_16x16x32_bf16 v[130:133], v[126:129], v[214:217], v[130:133]
	v_mfma_f32_16x16x32_bf16 v[114:117], v[110:113], v[222:225], v[114:117]
	v_mfma_f32_16x16x32_bf16 v[82:85], v[126:129], v[222:225], v[82:85]
	v_mfma_f32_16x16x32_bf16 v[74:77], v[110:113], v[244:247], v[74:77]
	v_mfma_f32_16x16x32_bf16 v[66:69], v[126:129], v[244:247], v[66:69]
	s_setprio 0
	s_barrier
	s_add_i32 s48, s48, s28
	s_mov_b32 m0, s48
	ds_read_b128 v[202:205], v179 offset:16384
	ds_read_b128 v[206:209], v179 offset:17408
	ds_read_b128 v[210:213], v179 offset:18432
	ds_read_b128 v[214:217], v179 offset:19456
	ds_read_b128 v[218:221], v179 offset:20480
	ds_read_b128 v[222:225], v179 offset:21504
	ds_read_b128 v[240:243], v179 offset:22528
	ds_read_b128 v[244:247], v179 offset:23552
	global_load_lds_dwordx4 v64, s[24:25]
	s_add_i32 m0, s48, 0x2000
	s_add_u32 s48, s24, 0x40000
	s_addc_u32 s49, s25, 0
	s_add_i32 s50, s50, s28
	global_load_lds_dwordx4 v162, s[24:25]
	s_mov_b32 m0, s50
	s_nop 0
	global_load_lds_dwordx4 v64, s[48:49]
	s_add_i32 m0, s50, 0x2000
	s_nop 0
	global_load_lds_dwordx4 v162, s[48:49]
	s_mov_b32 m0, s30
	s_nop 0
	global_load_lds_dwordx4 v166, s[26:27]
	s_mov_b32 m0, s31
	s_nop 0
	global_load_lds_dwordx4 v164, s[26:27]
	s_waitcnt vmcnt(8)
	s_waitcnt lgkmcnt(0)
	s_barrier
	s_setprio 1
	v_mfma_f32_16x16x32_bf16 v[60:63], v[86:89], v[202:205], v[60:63]
	v_mfma_f32_16x16x32_bf16 v[52:55], v[98:101], v[202:205], v[52:55]
	v_mfma_f32_16x16x32_bf16 v[44:47], v[86:89], v[210:213], v[44:47]
	v_mfma_f32_16x16x32_bf16 v[36:39], v[98:101], v[210:213], v[36:39]
	v_mfma_f32_16x16x32_bf16 v[28:31], v[86:89], v[218:221], v[28:31]
	v_mfma_f32_16x16x32_bf16 v[20:23], v[98:101], v[218:221], v[20:23]
	v_mfma_f32_16x16x32_bf16 v[12:15], v[86:89], v[240:243], v[12:15]
	v_mfma_f32_16x16x32_bf16 v[4:7], v[98:101], v[240:243], v[4:7]
	v_mfma_f32_16x16x32_bf16 v[60:63], v[94:97], v[206:209], v[60:63]
	v_mfma_f32_16x16x32_bf16 v[52:55], v[102:105], v[206:209], v[52:55]
	v_mfma_f32_16x16x32_bf16 v[44:47], v[94:97], v[214:217], v[44:47]
	v_mfma_f32_16x16x32_bf16 v[36:39], v[102:105], v[214:217], v[36:39]
	v_mfma_f32_16x16x32_bf16 v[28:31], v[94:97], v[222:225], v[28:31]
	v_mfma_f32_16x16x32_bf16 v[20:23], v[102:105], v[222:225], v[20:23]
	v_mfma_f32_16x16x32_bf16 v[12:15], v[94:97], v[244:247], v[12:15]
	v_mfma_f32_16x16x32_bf16 v[4:7], v[102:105], v[244:247], v[4:7]
	s_setprio 0
	s_setprio 1
	v_mfma_f32_16x16x32_bf16 v[56:59], v[106:109], v[202:205], v[56:59]
	v_mfma_f32_16x16x32_bf16 v[48:51], v[118:121], v[202:205], v[48:51]
	v_mfma_f32_16x16x32_bf16 v[40:43], v[106:109], v[210:213], v[40:43]
	v_mfma_f32_16x16x32_bf16 v[32:35], v[118:121], v[210:213], v[32:35]
	v_mfma_f32_16x16x32_bf16 v[24:27], v[106:109], v[218:221], v[24:27]
	v_mfma_f32_16x16x32_bf16 v[16:19], v[118:121], v[218:221], v[16:19]
	v_mfma_f32_16x16x32_bf16 v[8:11], v[106:109], v[240:243], v[8:11]
	v_mfma_f32_16x16x32_bf16 v[0:3], v[118:121], v[240:243], v[0:3]
	v_mfma_f32_16x16x32_bf16 v[56:59], v[110:113], v[206:209], v[56:59]
	v_mfma_f32_16x16x32_bf16 v[48:51], v[126:129], v[206:209], v[48:51]
	v_mfma_f32_16x16x32_bf16 v[40:43], v[110:113], v[214:217], v[40:43]
	v_mfma_f32_16x16x32_bf16 v[32:35], v[126:129], v[214:217], v[32:35]
	v_mfma_f32_16x16x32_bf16 v[24:27], v[110:113], v[222:225], v[24:27]
	v_mfma_f32_16x16x32_bf16 v[16:19], v[126:129], v[222:225], v[16:19]
	v_mfma_f32_16x16x32_bf16 v[8:11], v[110:113], v[244:247], v[8:11]
	v_mfma_f32_16x16x32_bf16 v[0:3], v[126:129], v[244:247], v[0:3]
	s_setprio 0
	s_barrier
; #define PG8_STAGE(bufoff, gbase, voff) do { _Pragma("unroll") for (int _i = 0; _i < 2; ++_i) \
;         __builtin_amdgcn_global_load_lds((const unsigned*)((const char*)(gbase) + (voff)[_i]), (PG8_LAS unsigned*)(lds + (bufoff) + ldsw + _i * 8192), 16, 0, 0); } while (0)
; #define PG8_LDA(dst, b, h) do { _Pragma("unroll") for (int m = 0; m < 4; ++m) _Pragma("unroll") for (int k = 0; k < 2; ++k) dst[m][k] = *(const PG8_LAS bf16x8*)(lds + PG8_SA(b, h) + aoff + m * 2048 + k * 1024); } while (0)
; #define PG8_LDB(dst, b, h) do { _Pragma("unroll") for (int n = 0; n < 2; ++n) _Pragma("unroll") for (int k = 0; k < 2; ++k) dst[n][k] = *(const PG8_LAS bf16x8*)(lds + PG8_SB(b, h) + boff + n * 2048 + k * 1024); } while (0)
; #define PG8_MMA(ai, bj, At, Bt) do { __builtin_amdgcn_s_setprio(1); _Pragma("unroll") for (int m = 0; m < 4; ++m) _Pragma("unroll") for (int n = 0; n < 2; ++n) _Pragma("unroll") for (int k = 0; k < 2; ++k) \
;         acc[ai][bj][m][n] = __builtin_amdgcn_mfma_f32_16x16x32_bf16(Bt[n][k], At[m][k], acc[ai][bj][m][n], 0, 0, 0); __builtin_amdgcn_s_setprio(0); } while (0)
; #define PG8_WAIT_V(n) asm volatile("s_waitcnt vmcnt(" #n ")" ::: "memory")
; #define PG8_WAIT_L(n) asm volatile("s_waitcnt lgkmcnt(" #n ")" ::: "memory")
; #define PG8_BAR __builtin_amdgcn_s_barrier()
; #define PG8_SCHED __builtin_amdgcn_sched_barrier(0)
; template <class Epi, class Sched, bool ALIGN_EPI = false, bool SP2 = false>
; __device__ __forceinline__ void gemm_phase(PG8_LAS unsigned char* lds, const Gemm g, const Sched& S, const Epi& E) {
;     ...
;             PG8_LDB(B0, 1, 0); PG8_LDB(B1, 1, 1); PG8_SCHED; PG8_LDA(At, 1, 0); PG8_STAGE(PG8_SA(0, 1), a2 + hstepA, voffA);
;             PG8_WAIT_V(8); PG8_WAIT_L(0); PG8_BAR; PG8_MMA(0, 0, At, B0); PG8_MMA(0, 1, At, B1); PG8_BAR; PG8_SCHED;
;             PG8_LDA(At, 1, 1); PG8_STAGE(PG8_SB(1, 0), b3, voffB); PG8_STAGE(PG8_SB(1, 1), b3 + hstepB, voffB); PG8_STAGE(PG8_SA(1, 0), a3, voffA);
;             PG8_WAIT_V(8); PG8_WAIT_L(0); PG8_BAR; PG8_MMA(1, 0, At, B0); PG8_MMA(1, 1, At, B1); PG8_BAR; PG8_SCHED;
	s_add_i32 s48, 0, 0x18000
	s_add_i32 s49, 0, 0x1c000
	v_add_u32_e32 v102, s48, v177
	v_add_u32_e32 v126, s49, v177
	ds_read_b128 v[86:89], v102
	ds_read_b128 v[94:97], v102 offset:1024
	ds_read_b128 v[98:101], v102 offset:2048
	ds_read_b128 v[102:105], v102 offset:3072
	ds_read_b128 v[106:109], v126
	ds_read_b128 v[110:113], v126 offset:1024
	ds_read_b128 v[118:121], v126 offset:2048
	ds_read_b128 v[126:129], v126 offset:3072
	s_add_u32 s26, s26, 0x40000
	s_addc_u32 s27, s27, 0
	s_add_u32 s100, s26, 0xfffc0080
	s_addc_u32 s101, s27, -1
	s_mov_b32 m0, s34
	ds_read_b128 v[202:205], v179 offset:32768
	ds_read_b128 v[206:209], v179 offset:33792
	ds_read_b128 v[210:213], v179 offset:34816
	ds_read_b128 v[214:217], v179 offset:35840
	ds_read_b128 v[218:221], v179 offset:36864
	ds_read_b128 v[222:225], v179 offset:37888
	ds_read_b128 v[240:243], v179 offset:38912
	ds_read_b128 v[244:247], v179 offset:39936
	global_load_lds_dwordx4 v166, s[26:27]
	s_mov_b32 m0, s35
	s_nop 0
	global_load_lds_dwordx4 v164, s[26:27]
	s_waitcnt vmcnt(8)
	s_waitcnt lgkmcnt(0)
	s_barrier
	s_setprio 1
	v_mfma_f32_16x16x32_bf16 v[158:161], v[86:89], v[202:205], v[158:161]
	v_mfma_f32_16x16x32_bf16 v[150:153], v[98:101], v[202:205], v[150:153]
	v_mfma_f32_16x16x32_bf16 v[142:145], v[86:89], v[210:213], v[142:145]
	v_mfma_f32_16x16x32_bf16 v[134:137], v[98:101], v[210:213], v[134:137]
	v_mfma_f32_16x16x32_bf16 v[122:125], v[86:89], v[218:221], v[122:125]
	v_mfma_f32_16x16x32_bf16 v[90:93], v[98:101], v[218:221], v[90:93]
	v_mfma_f32_16x16x32_bf16 v[78:81], v[86:89], v[240:243], v[78:81]
	v_mfma_f32_16x16x32_bf16 v[70:73], v[98:101], v[240:243], v[70:73]
	v_mfma_f32_16x16x32_bf16 v[158:161], v[94:97], v[206:209], v[158:161]
	v_mfma_f32_16x16x32_bf16 v[150:153], v[102:105], v[206:209], v[150:153]
	v_mfma_f32_16x16x32_bf16 v[142:145], v[94:97], v[214:217], v[142:145]
	v_mfma_f32_16x16x32_bf16 v[134:137], v[102:105], v[214:217], v[134:137]
	v_mfma_f32_16x16x32_bf16 v[122:125], v[94:97], v[222:225], v[122:125]
	v_mfma_f32_16x16x32_bf16 v[90:93], v[102:105], v[222:225], v[90:93]
	v_mfma_f32_16x16x32_bf16 v[78:81], v[94:97], v[244:247], v[78:81]
	v_mfma_f32_16x16x32_bf16 v[70:73], v[102:105], v[244:247], v[70:73]
	s_setprio 0
	s_setprio 1
	v_mfma_f32_16x16x32_bf16 v[154:157], v[106:109], v[202:205], v[154:157]
	v_mfma_f32_16x16x32_bf16 v[146:149], v[118:121], v[202:205], v[146:149]
	v_mfma_f32_16x16x32_bf16 v[138:141], v[106:109], v[210:213], v[138:141]
	v_mfma_f32_16x16x32_bf16 v[130:133], v[118:121], v[210:213], v[130:133]
	v_mfma_f32_16x16x32_bf16 v[114:117], v[106:109], v[218:221], v[114:117]
	v_mfma_f32_16x16x32_bf16 v[82:85], v[118:121], v[218:221], v[82:85]
	v_mfma_f32_16x16x32_bf16 v[74:77], v[106:109], v[240:243], v[74:77]
	v_mfma_f32_16x16x32_bf16 v[66:69], v[118:121], v[240:243], v[66:69]
	v_mfma_f32_16x16x32_bf16 v[154:157], v[110:113], v[206:209], v[154:157]
	v_mfma_f32_16x16x32_bf16 v[146:149], v[126:129], v[206:209], v[146:149]
	v_mfma_f32_16x16x32_bf16 v[138:141], v[110:113], v[214:217], v[138:141]
	v_mfma_f32_16x16x32_bf16 v[130:133], v[126:129], v[214:217], v[130:133]
	v_mfma_f32_16x16x32_bf16 v[114:117], v[110:113], v[222:225], v[114:117]
	v_mfma_f32_16x16x32_bf16 v[82:85], v[126:129], v[222:225], v[82:85]
	v_mfma_f32_16x16x32_bf16 v[74:77], v[110:113], v[244:247], v[74:77]
	v_mfma_f32_16x16x32_bf16 v[66:69], v[126:129], v[244:247], v[66:69]
	s_setprio 0
	s_barrier
	s_add_i32 s26, s48, s28
	s_add_u32 s24, s24, 0x80
	s_addc_u32 s25, s25, 0
	s_mov_b32 m0, s26
	ds_read_b128 v[202:205], v179 offset:49152
	ds_read_b128 v[206:209], v179 offset:50176
	ds_read_b128 v[210:213], v179 offset:51200
	ds_read_b128 v[214:217], v179 offset:52224
	ds_read_b128 v[218:221], v179 offset:53248
	ds_read_b128 v[222:225], v179 offset:54272
	ds_read_b128 v[240:243], v179 offset:55296
	ds_read_b128 v[244:247], v179 offset:56320
	global_load_lds_dwordx4 v64, s[24:25]
	s_add_i32 m0, s26, 0x2000
	s_add_i32 s26, s49, s28
	global_load_lds_dwordx4 v162, s[24:25]
	s_add_u32 s24, s24, 0x40000
	s_addc_u32 s25, s25, 0
	s_mov_b32 m0, s26
	s_nop 0
	global_load_lds_dwordx4 v64, s[24:25]
	s_add_i32 m0, s26, 0x2000
	s_nop 0
	global_load_lds_dwordx4 v162, s[24:25]
	s_mov_b32 m0, s37
	s_nop 0
	global_load_lds_dwordx4 v166, s[100:101]
	s_mov_b32 m0, s38
	s_nop 0
	global_load_lds_dwordx4 v164, s[100:101]
	s_waitcnt vmcnt(8)
	s_waitcnt lgkmcnt(0)
	s_barrier
	s_setprio 1
	v_mfma_f32_16x16x32_bf16 v[60:63], v[86:89], v[202:205], v[60:63]
	v_mfma_f32_16x16x32_bf16 v[52:55], v[98:101], v[202:205], v[52:55]
	v_mfma_f32_16x16x32_bf16 v[44:47], v[86:89], v[210:213], v[44:47]
	v_mfma_f32_16x16x32_bf16 v[36:39], v[98:101], v[210:213], v[36:39]
	v_mfma_f32_16x16x32_bf16 v[28:31], v[86:89], v[218:221], v[28:31]
	v_mfma_f32_16x16x32_bf16 v[20:23], v[98:101], v[218:221], v[20:23]
	v_mfma_f32_16x16x32_bf16 v[12:15], v[86:89], v[240:243], v[12:15]
	v_mfma_f32_16x16x32_bf16 v[4:7], v[98:101], v[240:243], v[4:7]
	v_mfma_f32_16x16x32_bf16 v[60:63], v[94:97], v[206:209], v[60:63]
	v_mfma_f32_16x16x32_bf16 v[52:55], v[102:105], v[206:209], v[52:55]
	v_mfma_f32_16x16x32_bf16 v[44:47], v[94:97], v[214:217], v[44:47]
	v_mfma_f32_16x16x32_bf16 v[36:39], v[102:105], v[214:217], v[36:39]
	v_mfma_f32_16x16x32_bf16 v[28:31], v[94:97], v[222:225], v[28:31]
	v_mfma_f32_16x16x32_bf16 v[20:23], v[102:105], v[222:225], v[20:23]
	v_mfma_f32_16x16x32_bf16 v[12:15], v[94:97], v[244:247], v[12:15]
	v_mfma_f32_16x16x32_bf16 v[4:7], v[102:105], v[244:247], v[4:7]
	s_setprio 0
	s_setprio 1
	v_mfma_f32_16x16x32_bf16 v[56:59], v[106:109], v[202:205], v[56:59]
	v_mfma_f32_16x16x32_bf16 v[48:51], v[118:121], v[202:205], v[48:51]
	v_mfma_f32_16x16x32_bf16 v[40:43], v[106:109], v[210:213], v[40:43]
	v_mfma_f32_16x16x32_bf16 v[32:35], v[118:121], v[210:213], v[32:35]
	v_mfma_f32_16x16x32_bf16 v[24:27], v[106:109], v[218:221], v[24:27]
	v_mfma_f32_16x16x32_bf16 v[16:19], v[118:121], v[218:221], v[16:19]
	v_mfma_f32_16x16x32_bf16 v[8:11], v[106:109], v[240:243], v[8:11]
	v_mfma_f32_16x16x32_bf16 v[0:3], v[118:121], v[240:243], v[0:3]
	v_mfma_f32_16x16x32_bf16 v[56:59], v[110:113], v[206:209], v[56:59]
	v_mfma_f32_16x16x32_bf16 v[48:51], v[126:129], v[206:209], v[48:51]
	v_mfma_f32_16x16x32_bf16 v[40:43], v[110:113], v[214:217], v[40:43]
	v_mfma_f32_16x16x32_bf16 v[32:35], v[126:129], v[214:217], v[32:35]
	v_mfma_f32_16x16x32_bf16 v[24:27], v[110:113], v[222:225], v[24:27]
	v_mfma_f32_16x16x32_bf16 v[16:19], v[126:129], v[222:225], v[16:19]
	v_mfma_f32_16x16x32_bf16 v[8:11], v[110:113], v[244:247], v[8:11]
	v_mfma_f32_16x16x32_bf16 v[0:3], v[126:129], v[244:247], v[0:3]
	s_setprio 0
	s_barrier
	s_add_u32 s4, s4, 0x100
	s_addc_u32 s5, s5, 0
	s_add_u32 s45, s45, 0x100
	s_addc_u32 s46, s46, 0
	s_cmp_ge_i32 s47, s36
	s_mov_b32 s24, s47
	s_cbranch_scc0 .LBB0_200

; #define PG8_STAGE(bufoff, gbase, voff) do { _Pragma("unroll") for (int _i = 0; _i < 2; ++_i) \
;         __builtin_amdgcn_global_load_lds((const unsigned*)((const char*)(gbase) + (voff)[_i]), (PG8_LAS unsigned*)(lds + (bufoff) + ldsw + _i * 8192), 16, 0, 0); } while (0)
; #define PG8_LDA(dst, b, h) do { _Pragma("unroll") for (int m = 0; m < 4; ++m) _Pragma("unroll") for (int k = 0; k < 2; ++k) dst[m][k] = *(const PG8_LAS bf16x8*)(lds + PG8_SA(b, h) + aoff + m * 2048 + k * 1024); } while (0)
; #define PG8_LDB(dst, b, h) do { _Pragma("unroll") for (int n = 0; n < 2; ++n) _Pragma("unroll") for (int k = 0; k < 2; ++k) dst[n][k] = *(const PG8_LAS bf16x8*)(lds + PG8_SB(b, h) + boff + n * 2048 + k * 1024); } while (0)
; #define PG8_MMA(ai, bj, At, Bt) do { __builtin_amdgcn_s_setprio(1); _Pragma("unroll") for (int m = 0; m < 4; ++m) _Pragma("unroll") for (int n = 0; n < 2; ++n) _Pragma("unroll") for (int k = 0; k < 2; ++k) \
;         acc[ai][bj][m][n] = __builtin_amdgcn_mfma_f32_16x16x32_bf16(Bt[n][k], At[m][k], acc[ai][bj][m][n], 0, 0, 0); __builtin_amdgcn_s_setprio(0); } while (0)
; #define PG8_WAIT_V(n) asm volatile("s_waitcnt vmcnt(" #n ")" ::: "memory")
; #define PG8_WAIT_L(n) asm volatile("s_waitcnt lgkmcnt(" #n ")" ::: "memory")
; #define PG8_BAR __builtin_amdgcn_s_barrier()
; #define PG8_SCHED __builtin_amdgcn_sched_barrier(0)
; template <class Epi, class Sched, bool ALIGN_EPI = false, bool SP2 = false>
; __device__ __forceinline__ void gemm_phase(PG8_LAS unsigned char* lds, const Gemm g, const Sched& S, const Epi& E) {
;     ...
;             PG8_LDB(B0, 0, 0); PG8_LDB(B1, 0, 1); PG8_SCHED; PG8_LDA(At, 0, 0); PG8_STAGE(PG8_SA(1, 1), a1 + hstepA, voffA);
;             PG8_WAIT_V(8); PG8_WAIT_L(0); PG8_BAR; PG8_MMA(0, 0, At, B0); PG8_MMA(0, 1, At, B1); PG8_BAR; PG8_SCHED;
;             PG8_LDA(At, 0, 1); PG8_STAGE(PG8_SB(0, 0), b2, voffB); PG8_STAGE(PG8_SB(0, 1), b2 + hstepB, voffB); PG8_STAGE(PG8_SA(0, 0), a2, voffA);
;             PG8_WAIT_V(8); PG8_WAIT_L(0); PG8_BAR; PG8_MMA(1, 0, At, B0); PG8_MMA(1, 1, At, B1); PG8_BAR; PG8_SCHED;
.LBB0_278:
	s_add_i32 s51, s10, 2
	s_add_u32 s8, s4, 0x100
	s_addc_u32 s9, s5, 0
	s_add_i32 s52, 0, 0x10000
	s_cmp_eq_u32 s45, s10
	s_cselect_b32 s29, s25, s9
	s_cselect_b32 s28, s24, s8
	s_cselect_b32 s11, s27, s50
	s_cselect_b32 s10, s26, s49
	s_add_i32 s53, 0, 0x14000
	v_add_u32_e32 v152, s52, v242
	v_add_u32_e32 v168, s53, v242
	ds_read_b128 v[140:143], v152
	ds_read_b128 v[144:147], v152 offset:1024
	ds_read_b128 v[148:151], v152 offset:2048
	ds_read_b128 v[152:155], v152 offset:3072
	ds_read_b128 v[156:159], v168
	ds_read_b128 v[160:163], v168 offset:1024
	ds_read_b128 v[164:167], v168 offset:2048
	ds_read_b128 v[168:171], v168 offset:3072
	v_lshl_add_u64 v[188:189], s[4:5], 0, v[136:137]
	s_add_i32 m0, s35, 0xc000
	ds_read_b128 v[172:175], v243
	ds_read_b128 v[176:179], v243 offset:1024
	ds_read_b128 v[180:183], v243 offset:2048
	ds_read_b128 v[184:187], v243 offset:3072
	ds_read_b128 v[202:205], v243 offset:4096
	ds_read_b128 v[206:209], v243 offset:5120
	ds_read_b128 v[210:213], v243 offset:6144
	ds_read_b128 v[214:217], v243 offset:7168
	global_load_lds_dwordx4 v[188:189], off
	v_lshl_add_u64 v[188:189], s[4:5], 0, v[138:139]
	s_add_i32 m0, s35, 0xe000
	s_nop 0
	global_load_lds_dwordx4 v[188:189], off
	s_waitcnt vmcnt(8)
	s_waitcnt lgkmcnt(0)
	s_barrier
	s_setprio 1
	v_mfma_f32_16x16x32_bf16 v[126:129], v[140:143], v[172:175], v[126:129]
	v_mfma_f32_16x16x32_bf16 v[122:125], v[148:151], v[172:175], v[122:125]
	v_mfma_f32_16x16x32_bf16 v[118:121], v[140:143], v[180:183], v[118:121]
	v_mfma_f32_16x16x32_bf16 v[114:117], v[148:151], v[180:183], v[114:117]
	v_mfma_f32_16x16x32_bf16 v[106:109], v[140:143], v[202:205], v[106:109]
	v_mfma_f32_16x16x32_bf16 v[98:101], v[148:151], v[202:205], v[98:101]
	v_mfma_f32_16x16x32_bf16 v[90:93], v[140:143], v[210:213], v[90:93]
	v_mfma_f32_16x16x32_bf16 v[82:85], v[148:151], v[210:213], v[82:85]
	v_mfma_f32_16x16x32_bf16 v[126:129], v[144:147], v[176:179], v[126:129]
	v_mfma_f32_16x16x32_bf16 v[122:125], v[152:155], v[176:179], v[122:125]
	v_mfma_f32_16x16x32_bf16 v[118:121], v[144:147], v[184:187], v[118:121]
	v_mfma_f32_16x16x32_bf16 v[114:117], v[152:155], v[184:187], v[114:117]
	v_mfma_f32_16x16x32_bf16 v[106:109], v[144:147], v[206:209], v[106:109]
	v_mfma_f32_16x16x32_bf16 v[98:101], v[152:155], v[206:209], v[98:101]
	v_mfma_f32_16x16x32_bf16 v[90:93], v[144:147], v[214:217], v[90:93]
	v_mfma_f32_16x16x32_bf16 v[82:85], v[152:155], v[214:217], v[82:85]
	s_setprio 0
	s_setprio 1
	v_mfma_f32_16x16x32_bf16 v[110:113], v[156:159], v[172:175], v[110:113]
	v_mfma_f32_16x16x32_bf16 v[102:105], v[164:167], v[172:175], v[102:105]
	v_mfma_f32_16x16x32_bf16 v[94:97], v[156:159], v[180:183], v[94:97]
	v_mfma_f32_16x16x32_bf16 v[86:89], v[164:167], v[180:183], v[86:89]
	v_mfma_f32_16x16x32_bf16 v[78:81], v[156:159], v[202:205], v[78:81]
	v_mfma_f32_16x16x32_bf16 v[74:77], v[164:167], v[202:205], v[74:77]
	v_mfma_f32_16x16x32_bf16 v[70:73], v[156:159], v[210:213], v[70:73]
	v_mfma_f32_16x16x32_bf16 v[66:69], v[164:167], v[210:213], v[66:69]
	v_mfma_f32_16x16x32_bf16 v[110:113], v[160:163], v[176:179], v[110:113]
	v_mfma_f32_16x16x32_bf16 v[102:105], v[168:171], v[176:179], v[102:105]
	v_mfma_f32_16x16x32_bf16 v[94:97], v[160:163], v[184:187], v[94:97]
	v_mfma_f32_16x16x32_bf16 v[86:89], v[168:171], v[184:187], v[86:89]
	v_mfma_f32_16x16x32_bf16 v[78:81], v[160:163], v[206:209], v[78:81]
	v_mfma_f32_16x16x32_bf16 v[74:77], v[168:171], v[206:209], v[74:77]
	v_mfma_f32_16x16x32_bf16 v[70:73], v[160:163], v[214:217], v[70:73]
	v_mfma_f32_16x16x32_bf16 v[66:69], v[168:171], v[214:217], v[66:69]
	s_setprio 0
	s_barrier
	s_add_i32 s4, s52, s30
	v_lshl_add_u64 v[188:189], s[10:11], 0, v[64:65]
	s_mov_b32 m0, s4
	ds_read_b128 v[172:175], v243 offset:16384
	ds_read_b128 v[176:179], v243 offset:17408
	ds_read_b128 v[180:183], v243 offset:18432
	ds_read_b128 v[184:187], v243 offset:19456
	ds_read_b128 v[202:205], v243 offset:20480
	ds_read_b128 v[206:209], v243 offset:21504
	ds_read_b128 v[210:213], v243 offset:22528
	ds_read_b128 v[214:217], v243 offset:23552
	global_load_lds_dwordx4 v[188:189], off
	s_add_i32 m0, s4, 0x2000
	s_add_u32 s4, s10, 0xb0000
	v_lshl_add_u64 v[218:219], s[10:11], 0, v[130:131]
	s_addc_u32 s5, s11, 0
	s_add_i32 s52, s53, s30
	global_load_lds_dwordx4 v[218:219], off
	v_lshl_add_u64 v[220:221], s[4:5], 0, v[64:65]
	s_mov_b32 m0, s52
	v_lshl_add_u64 v[222:223], s[28:29], 0, v[132:133]
	global_load_lds_dwordx4 v[220:221], off
	v_lshl_add_u64 v[220:221], s[4:5], 0, v[130:131]
	s_add_i32 m0, s52, 0x2000
	s_nop 0
	global_load_lds_dwordx4 v[220:221], off
	v_lshl_add_u64 v[220:221], s[28:29], 0, v[134:135]
	s_mov_b32 m0, s35
	s_nop 0
	global_load_lds_dwordx4 v[220:221], off
	s_mov_b32 m0, s36
	s_nop 0
	global_load_lds_dwordx4 v[222:223], off
	s_waitcnt vmcnt(8)
	s_waitcnt lgkmcnt(0)
	s_barrier
; #define PG8_STAGE(bufoff, gbase, voff) do { _Pragma("unroll") for (int _i = 0; _i < 2; ++_i) \
;         __builtin_amdgcn_global_load_lds((const unsigned*)((const char*)(gbase) + (voff)[_i]), (PG8_LAS unsigned*)(lds + (bufoff) + ldsw + _i * 8192), 16, 0, 0); } while (0)
; #define PG8_LDA(dst, b, h) do { _Pragma("unroll") for (int m = 0; m < 4; ++m) _Pragma("unroll") for (int k = 0; k < 2; ++k) dst[m][k] = *(const PG8_LAS bf16x8*)(lds + PG8_SA(b, h) + aoff + m * 2048 + k * 1024); } while (0)
; #define PG8_LDB(dst, b, h) do { _Pragma("unroll") for (int n = 0; n < 2; ++n) _Pragma("unroll") for (int k = 0; k < 2; ++k) dst[n][k] = *(const PG8_LAS bf16x8*)(lds + PG8_SB(b, h) + boff + n * 2048 + k * 1024); } while (0)
; #define PG8_MMA(ai, bj, At, Bt) do { __builtin_amdgcn_s_setprio(1); _Pragma("unroll") for (int m = 0; m < 4; ++m) _Pragma("unroll") for (int n = 0; n < 2; ++n) _Pragma("unroll") for (int k = 0; k < 2; ++k) \
;         acc[ai][bj][m][n] = __builtin_amdgcn_mfma_f32_16x16x32_bf16(Bt[n][k], At[m][k], acc[ai][bj][m][n], 0, 0, 0); __builtin_amdgcn_s_setprio(0); } while (0)
; #define PG8_WAIT_V(n) asm volatile("s_waitcnt vmcnt(" #n ")" ::: "memory")
; #define PG8_WAIT_L(n) asm volatile("s_waitcnt lgkmcnt(" #n ")" ::: "memory")
; #define PG8_BAR __builtin_amdgcn_s_barrier()
; #define PG8_SCHED __builtin_amdgcn_sched_barrier(0)
; template <class Epi, class Sched, bool ALIGN_EPI = false, bool SP2 = false>
; __device__ __forceinline__ void gemm_phase(PG8_LAS unsigned char* lds, const Gemm g, const Sched& S, const Epi& E) {
;     ...
;             PG8_WAIT_V(8); PG8_WAIT_L(0); PG8_BAR; PG8_MMA(0, 0, At, B0); PG8_MMA(0, 1, At, B1); PG8_BAR; PG8_SCHED;
;             PG8_LDA(At, 0, 1); PG8_STAGE(PG8_SB(0, 0), b2, voffB); PG8_STAGE(PG8_SB(0, 1), b2 + hstepB, voffB); PG8_STAGE(PG8_SA(0, 0), a2, voffA);
;             PG8_WAIT_V(8); PG8_WAIT_L(0); PG8_BAR; PG8_MMA(1, 0, At, B0); PG8_MMA(1, 1, At, B1); PG8_BAR; PG8_SCHED;
;             PG8_LDB(B0, 1, 0); PG8_LDB(B1, 1, 1); PG8_SCHED; PG8_LDA(At, 1, 0); PG8_STAGE(PG8_SA(0, 1), a2 + hstepA, voffA);
;             PG8_WAIT_V(8); PG8_WAIT_L(0); PG8_BAR; PG8_MMA(0, 0, At, B0); PG8_MMA(0, 1, At, B1); PG8_BAR; PG8_SCHED;
	s_setprio 1
	v_mfma_f32_16x16x32_bf16 v[60:63], v[140:143], v[172:175], v[60:63]
	v_mfma_f32_16x16x32_bf16 v[56:59], v[148:151], v[172:175], v[56:59]
	v_mfma_f32_16x16x32_bf16 v[52:55], v[140:143], v[180:183], v[52:55]
	v_mfma_f32_16x16x32_bf16 v[48:51], v[148:151], v[180:183], v[48:51]
	v_mfma_f32_16x16x32_bf16 v[40:43], v[140:143], v[202:205], v[40:43]
	v_mfma_f32_16x16x32_bf16 v[32:35], v[148:151], v[202:205], v[32:35]
	v_mfma_f32_16x16x32_bf16 v[24:27], v[140:143], v[210:213], v[24:27]
	v_mfma_f32_16x16x32_bf16 v[16:19], v[148:151], v[210:213], v[16:19]
	v_mfma_f32_16x16x32_bf16 v[60:63], v[144:147], v[176:179], v[60:63]
	v_mfma_f32_16x16x32_bf16 v[56:59], v[152:155], v[176:179], v[56:59]
	v_mfma_f32_16x16x32_bf16 v[52:55], v[144:147], v[184:187], v[52:55]
	v_mfma_f32_16x16x32_bf16 v[48:51], v[152:155], v[184:187], v[48:51]
	v_mfma_f32_16x16x32_bf16 v[40:43], v[144:147], v[206:209], v[40:43]
	v_mfma_f32_16x16x32_bf16 v[32:35], v[152:155], v[206:209], v[32:35]
	v_mfma_f32_16x16x32_bf16 v[24:27], v[144:147], v[214:217], v[24:27]
	v_mfma_f32_16x16x32_bf16 v[16:19], v[152:155], v[214:217], v[16:19]
	s_setprio 0
	s_setprio 1
	v_mfma_f32_16x16x32_bf16 v[44:47], v[156:159], v[172:175], v[44:47]
	v_mfma_f32_16x16x32_bf16 v[36:39], v[164:167], v[172:175], v[36:39]
	v_mfma_f32_16x16x32_bf16 v[28:31], v[156:159], v[180:183], v[28:31]
	v_mfma_f32_16x16x32_bf16 v[20:23], v[164:167], v[180:183], v[20:23]
	v_mfma_f32_16x16x32_bf16 v[12:15], v[156:159], v[202:205], v[12:15]
	v_mfma_f32_16x16x32_bf16 v[8:11], v[164:167], v[202:205], v[8:11]
	v_mfma_f32_16x16x32_bf16 v[4:7], v[156:159], v[210:213], v[4:7]
	v_mfma_f32_16x16x32_bf16 v[0:3], v[164:167], v[210:213], v[0:3]
	v_mfma_f32_16x16x32_bf16 v[44:47], v[160:163], v[176:179], v[44:47]
	v_mfma_f32_16x16x32_bf16 v[36:39], v[168:171], v[176:179], v[36:39]
	v_mfma_f32_16x16x32_bf16 v[28:31], v[160:163], v[184:187], v[28:31]
	v_mfma_f32_16x16x32_bf16 v[20:23], v[168:171], v[184:187], v[20:23]
	v_mfma_f32_16x16x32_bf16 v[12:15], v[160:163], v[206:209], v[12:15]
	v_mfma_f32_16x16x32_bf16 v[8:11], v[168:171], v[206:209], v[8:11]
	v_mfma_f32_16x16x32_bf16 v[4:7], v[160:163], v[214:217], v[4:7]
	v_mfma_f32_16x16x32_bf16 v[0:3], v[168:171], v[214:217], v[0:3]
	s_setprio 0
	s_barrier
	s_add_i32 s52, 0, 0x18000
	s_add_i32 s53, 0, 0x1c000
	v_add_u32_e32 v152, s52, v242
	v_add_u32_e32 v168, s53, v242
	ds_read_b128 v[140:143], v152
	ds_read_b128 v[144:147], v152 offset:1024
	ds_read_b128 v[148:151], v152 offset:2048
	ds_read_b128 v[152:155], v152 offset:3072
	ds_read_b128 v[156:159], v168
	ds_read_b128 v[160:163], v168 offset:1024
	ds_read_b128 v[164:167], v168 offset:2048
	ds_read_b128 v[168:171], v168 offset:3072
	s_add_u32 s4, s28, 0xb0000
	s_addc_u32 s5, s29, 0
	s_mov_b32 m0, s37
	v_lshl_add_u64 v[224:225], s[4:5], 0, v[134:135]
	ds_read_b128 v[172:175], v243 offset:32768
	ds_read_b128 v[176:179], v243 offset:33792
	ds_read_b128 v[180:183], v243 offset:34816
	ds_read_b128 v[184:187], v243 offset:35840
	ds_read_b128 v[202:205], v243 offset:36864
	ds_read_b128 v[206:209], v243 offset:37888
	ds_read_b128 v[210:213], v243 offset:38912
	ds_read_b128 v[214:217], v243 offset:39936
	global_load_lds_dwordx4 v[224:225], off
	v_lshl_add_u64 v[224:225], s[4:5], 0, v[132:133]
	s_mov_b32 m0, s38
	s_nop 0
	global_load_lds_dwordx4 v[224:225], off
	s_waitcnt vmcnt(8)
	s_waitcnt lgkmcnt(0)
	s_barrier
	s_setprio 1
	v_mfma_f32_16x16x32_bf16 v[126:129], v[140:143], v[172:175], v[126:129]
	v_mfma_f32_16x16x32_bf16 v[122:125], v[148:151], v[172:175], v[122:125]
	v_mfma_f32_16x16x32_bf16 v[118:121], v[140:143], v[180:183], v[118:121]
	v_mfma_f32_16x16x32_bf16 v[114:117], v[148:151], v[180:183], v[114:117]
	v_mfma_f32_16x16x32_bf16 v[106:109], v[140:143], v[202:205], v[106:109]
	v_mfma_f32_16x16x32_bf16 v[98:101], v[148:151], v[202:205], v[98:101]
	v_mfma_f32_16x16x32_bf16 v[90:93], v[140:143], v[210:213], v[90:93]
	v_mfma_f32_16x16x32_bf16 v[82:85], v[148:151], v[210:213], v[82:85]
	v_mfma_f32_16x16x32_bf16 v[126:129], v[144:147], v[176:179], v[126:129]
	v_mfma_f32_16x16x32_bf16 v[122:125], v[152:155], v[176:179], v[122:125]
	v_mfma_f32_16x16x32_bf16 v[118:121], v[144:147], v[184:187], v[118:121]
	v_mfma_f32_16x16x32_bf16 v[114:117], v[152:155], v[184:187], v[114:117]
	v_mfma_f32_16x16x32_bf16 v[106:109], v[144:147], v[206:209], v[106:109]
	v_mfma_f32_16x16x32_bf16 v[98:101], v[152:155], v[206:209], v[98:101]
	v_mfma_f32_16x16x32_bf16 v[90:93], v[144:147], v[214:217], v[90:93]
	v_mfma_f32_16x16x32_bf16 v[82:85], v[152:155], v[214:217], v[82:85]
	s_setprio 0
	s_setprio 1
	v_mfma_f32_16x16x32_bf16 v[110:113], v[156:159], v[172:175], v[110:113]
	v_mfma_f32_16x16x32_bf16 v[102:105], v[164:167], v[172:175], v[102:105]
	v_mfma_f32_16x16x32_bf16 v[94:97], v[156:159], v[180:183], v[94:97]
	v_mfma_f32_16x16x32_bf16 v[86:89], v[164:167], v[180:183], v[86:89]
	v_mfma_f32_16x16x32_bf16 v[78:81], v[156:159], v[202:205], v[78:81]
	v_mfma_f32_16x16x32_bf16 v[74:77], v[164:167], v[202:205], v[74:77]
	v_mfma_f32_16x16x32_bf16 v[70:73], v[156:159], v[210:213], v[70:73]
	v_mfma_f32_16x16x32_bf16 v[66:69], v[164:167], v[210:213], v[66:69]
	v_mfma_f32_16x16x32_bf16 v[110:113], v[160:163], v[176:179], v[110:113]
	v_mfma_f32_16x16x32_bf16 v[102:105], v[168:171], v[176:179], v[102:105]
	v_mfma_f32_16x16x32_bf16 v[94:97], v[160:163], v[184:187], v[94:97]
	v_mfma_f32_16x16x32_bf16 v[86:89], v[168:171], v[184:187], v[86:89]
	v_mfma_f32_16x16x32_bf16 v[78:81], v[160:163], v[206:209], v[78:81]
	v_mfma_f32_16x16x32_bf16 v[74:77], v[168:171], v[206:209], v[74:77]
	v_mfma_f32_16x16x32_bf16 v[70:73], v[160:163], v[214:217], v[70:73]
	v_mfma_f32_16x16x32_bf16 v[66:69], v[168:171], v[214:217], v[66:69]
	s_setprio 0
	s_barrier
; #define PG8_STAGE(bufoff, gbase, voff) do { _Pragma("unroll") for (int _i = 0; _i < 2; ++_i) \
;         __builtin_amdgcn_global_load_lds((const unsigned*)((const char*)(gbase) + (voff)[_i]), (PG8_LAS unsigned*)(lds + (bufoff) + ldsw + _i * 8192), 16, 0, 0); } while (0)
; #define PG8_LDA(dst, b, h) do { _Pragma("unroll") for (int m = 0; m < 4; ++m) _Pragma("unroll") for (int k = 0; k < 2; ++k) dst[m][k] = *(const PG8_LAS bf16x8*)(lds + PG8_SA(b, h) + aoff + m * 2048 + k * 1024); } while (0)
; #define PG8_LDB(dst, b, h) do { _Pragma("unroll") for (int n = 0; n < 2; ++n) _Pragma("unroll") for (int k = 0; k < 2; ++k) dst[n][k] = *(const PG8_LAS bf16x8*)(lds + PG8_SB(b, h) + boff + n * 2048 + k * 1024); } while (0)
; #define PG8_MMA(ai, bj, At, Bt) do { __builtin_amdgcn_s_setprio(1); _Pragma("unroll") for (int m = 0; m < 4; ++m) _Pragma("unroll") for (int n = 0; n < 2; ++n) _Pragma("unroll") for (int k = 0; k < 2; ++k) \
;         acc[ai][bj][m][n] = __builtin_amdgcn_mfma_f32_16x16x32_bf16(Bt[n][k], At[m][k], acc[ai][bj][m][n], 0, 0, 0); __builtin_amdgcn_s_setprio(0); } while (0)
; #define PG8_WAIT_V(n) asm volatile("s_waitcnt vmcnt(" #n ")" ::: "memory")
; #define PG8_WAIT_L(n) asm volatile("s_waitcnt lgkmcnt(" #n ")" ::: "memory")
; #define PG8_BAR __builtin_amdgcn_s_barrier()
; #define PG8_SCHED __builtin_amdgcn_sched_barrier(0)
; template <class Epi, class Sched, bool ALIGN_EPI = false, bool SP2 = false>
; __device__ __forceinline__ void gemm_phase(PG8_LAS unsigned char* lds, const Gemm g, const Sched& S, const Epi& E) {
;     ...
;             PG8_LDB(B0, 1, 0); PG8_LDB(B1, 1, 1); PG8_SCHED; PG8_LDA(At, 1, 0); PG8_STAGE(PG8_SA(0, 1), a2 + hstepA, voffA);
;             PG8_WAIT_V(8); PG8_WAIT_L(0); PG8_BAR; PG8_MMA(0, 0, At, B0); PG8_MMA(0, 1, At, B1); PG8_BAR; PG8_SCHED;
;             PG8_LDA(At, 1, 1); PG8_STAGE(PG8_SB(1, 0), b3, voffB); PG8_STAGE(PG8_SB(1, 1), b3 + hstepB, voffB); PG8_STAGE(PG8_SA(1, 0), a3, voffA);
;             PG8_WAIT_V(8); PG8_WAIT_L(0); PG8_BAR; PG8_MMA(1, 0, At, B0); PG8_MMA(1, 1, At, B1); PG8_BAR; PG8_SCHED;
	s_add_i32 s4, s52, s30
	v_lshl_add_u64 v[188:189], v[188:189], 0, s[88:89]
	s_mov_b32 m0, s4
	ds_read_b128 v[172:175], v243 offset:49152
	ds_read_b128 v[176:179], v243 offset:50176
	ds_read_b128 v[180:183], v243 offset:51200
	ds_read_b128 v[184:187], v243 offset:52224
	ds_read_b128 v[202:205], v243 offset:53248
	ds_read_b128 v[206:209], v243 offset:54272
	ds_read_b128 v[210:213], v243 offset:55296
	ds_read_b128 v[214:217], v243 offset:56320
	global_load_lds_dwordx4 v[188:189], off
	s_add_i32 m0, s4, 0x2000
	s_add_u32 s4, s10, 0xb0080
	v_lshl_add_u64 v[188:189], v[218:219], 0, s[88:89]
	s_addc_u32 s5, s11, 0
	s_add_i32 s10, s53, s30
	global_load_lds_dwordx4 v[188:189], off
	v_lshl_add_u64 v[188:189], s[4:5], 0, v[64:65]
	s_mov_b32 m0, s10
	s_nop 0
	global_load_lds_dwordx4 v[188:189], off
	v_lshl_add_u64 v[188:189], s[4:5], 0, v[130:131]
	s_add_i32 m0, s10, 0x2000
	s_nop 0
	global_load_lds_dwordx4 v[188:189], off
	v_lshl_add_u64 v[188:189], v[220:221], 0, s[88:89]
	s_mov_b32 m0, s43
	s_nop 0
	global_load_lds_dwordx4 v[188:189], off
	v_lshl_add_u64 v[188:189], v[222:223], 0, s[88:89]
	s_mov_b32 m0, s44
	s_nop 0
	global_load_lds_dwordx4 v[188:189], off
	s_waitcnt vmcnt(8)
	s_waitcnt lgkmcnt(0)
	s_barrier
	s_setprio 1
	v_mfma_f32_16x16x32_bf16 v[60:63], v[140:143], v[172:175], v[60:63]
	v_mfma_f32_16x16x32_bf16 v[56:59], v[148:151], v[172:175], v[56:59]
	v_mfma_f32_16x16x32_bf16 v[52:55], v[140:143], v[180:183], v[52:55]
	v_mfma_f32_16x16x32_bf16 v[48:51], v[148:151], v[180:183], v[48:51]
	v_mfma_f32_16x16x32_bf16 v[40:43], v[140:143], v[202:205], v[40:43]
	v_mfma_f32_16x16x32_bf16 v[32:35], v[148:151], v[202:205], v[32:35]
	v_mfma_f32_16x16x32_bf16 v[24:27], v[140:143], v[210:213], v[24:27]
	v_mfma_f32_16x16x32_bf16 v[16:19], v[148:151], v[210:213], v[16:19]
	v_mfma_f32_16x16x32_bf16 v[60:63], v[144:147], v[176:179], v[60:63]
	v_mfma_f32_16x16x32_bf16 v[56:59], v[152:155], v[176:179], v[56:59]
	v_mfma_f32_16x16x32_bf16 v[52:55], v[144:147], v[184:187], v[52:55]
	v_mfma_f32_16x16x32_bf16 v[48:51], v[152:155], v[184:187], v[48:51]
	v_mfma_f32_16x16x32_bf16 v[40:43], v[144:147], v[206:209], v[40:43]
	v_mfma_f32_16x16x32_bf16 v[32:35], v[152:155], v[206:209], v[32:35]
	v_mfma_f32_16x16x32_bf16 v[24:27], v[144:147], v[214:217], v[24:27]
	v_mfma_f32_16x16x32_bf16 v[16:19], v[152:155], v[214:217], v[16:19]
	s_setprio 0
	s_setprio 1
	v_mfma_f32_16x16x32_bf16 v[44:47], v[156:159], v[172:175], v[44:47]
	v_mfma_f32_16x16x32_bf16 v[36:39], v[164:167], v[172:175], v[36:39]
	v_mfma_f32_16x16x32_bf16 v[28:31], v[156:159], v[180:183], v[28:31]
	v_mfma_f32_16x16x32_bf16 v[20:23], v[164:167], v[180:183], v[20:23]
	v_mfma_f32_16x16x32_bf16 v[12:15], v[156:159], v[202:205], v[12:15]
	v_mfma_f32_16x16x32_bf16 v[8:11], v[164:167], v[202:205], v[8:11]
	v_mfma_f32_16x16x32_bf16 v[4:7], v[156:159], v[210:213], v[4:7]
	v_mfma_f32_16x16x32_bf16 v[0:3], v[164:167], v[210:213], v[0:3]
	v_mfma_f32_16x16x32_bf16 v[44:47], v[160:163], v[176:179], v[44:47]
	v_mfma_f32_16x16x32_bf16 v[36:39], v[168:171], v[176:179], v[36:39]
	v_mfma_f32_16x16x32_bf16 v[28:31], v[160:163], v[184:187], v[28:31]
	v_mfma_f32_16x16x32_bf16 v[20:23], v[168:171], v[184:187], v[20:23]
	v_mfma_f32_16x16x32_bf16 v[12:15], v[160:163], v[206:209], v[12:15]
	v_mfma_f32_16x16x32_bf16 v[8:11], v[168:171], v[206:209], v[8:11]
	v_mfma_f32_16x16x32_bf16 v[4:7], v[160:163], v[214:217], v[4:7]
	v_mfma_f32_16x16x32_bf16 v[0:3], v[168:171], v[214:217], v[0:3]
	s_setprio 0
	s_barrier
	s_add_u32 s49, s49, 0x100
	s_addc_u32 s50, s50, 0
	s_cmp_ge_i32 s51, s41
	s_mov_b64 s[4:5], s[8:9]
	s_mov_b32 s10, s51
	s_cbranch_scc0 .LBB0_278
;     __device__ __forceinline__ void operator()(const f32x4 (&acc)[2][2][4][2], const Unit& u, int wr, int wc, int fr, int fq, const float (&)[8]) const {
;     ...
; #pragma unroll
;         for (int ai = 0; ai < 2; ++ai)
; #pragma unroll
;             for (int m = 0; m < 4; ++m) {
;                 const int row = u.pm * BM + ai * HALF + wr * 64 + m * 16 + fr; float sq = 0.f;
; #pragma unroll
;                 for (int bj = 0; bj < 2; ++bj) {
;                     const size_t off = off0 + (size_t)ai * (HALF * 1024) + (size_t)m * (16 * 1024) + bj * HALF;
;                     f32x4 b0, b1;
;                     if (xf) { b0 = *(const f32x4*)(xf + off); b1 = *(const f32x4*)(xf + off + 4); }
;                     else { const u32x4 w = raw[ai * 4 + m][bj];
;                         b0[0] = __uint_as_float(w.x << 16); b0[1] = __uint_as_float(w.x & 0xffff0000u); b0[2] = __uint_as_float(w.y << 16); b0[3] = __uint_as_float(w.y & 0xffff0000u);
;                         b1[0] = __uint_as_float(w.z << 16); b1[1] = __uint_as_float(w.z & 0xffff0000u); b1[2] = __uint_as_float(w.w << 16); b1[3] = __uint_as_float(w.w & 0xffff0000u); }
;                     const f32x4 o0 = b0 + acc[ai][bj][m][0] * alpha, o1 = b1 + acc[ai][bj][m][1] * alpha;
	v_pk_mul_f32 v[128:129], v[128:129], 0.5 op_sel_hi:[1,0]
	v_pk_mul_f32 v[218:219], v[126:127], 0.5 op_sel_hi:[1,0]
	v_pk_mul_f32 v[222:223], v[124:125], 0.5 op_sel_hi:[1,0]
	v_pk_mul_f32 v[226:227], v[122:123], 0.5 op_sel_hi:[1,0]
	v_pk_mul_f32 v[224:225], v[112:113], 0.5 op_sel_hi:[1,0]
	v_pk_mul_f32 v[220:221], v[110:111], 0.5 op_sel_hi:[1,0]
	v_pk_mul_f32 v[216:217], v[104:105], 0.5 op_sel_hi:[1,0]
	v_pk_mul_f32 v[214:215], v[102:103], 0.5 op_sel_hi:[1,0]
	v_pk_mul_f32 v[212:213], v[120:121], 0.5 op_sel_hi:[1,0]
	v_pk_mul_f32 v[210:211], v[118:119], 0.5 op_sel_hi:[1,0]
	v_pk_mul_f32 v[208:209], v[116:117], 0.5 op_sel_hi:[1,0]
	v_pk_mul_f32 v[206:207], v[114:115], 0.5 op_sel_hi:[1,0]
	v_pk_mul_f32 v[204:205], v[96:97], 0.5 op_sel_hi:[1,0]
	v_pk_mul_f32 v[202:203], v[94:95], 0.5 op_sel_hi:[1,0]
	v_pk_mul_f32 v[188:189], v[88:89], 0.5 op_sel_hi:[1,0]
	v_pk_mul_f32 v[186:187], v[86:87], 0.5 op_sel_hi:[1,0]
	v_pk_mul_f32 v[184:185], v[108:109], 0.5 op_sel_hi:[1,0]
	v_pk_mul_f32 v[182:183], v[106:107], 0.5 op_sel_hi:[1,0]
	v_pk_mul_f32 v[180:181], v[100:101], 0.5 op_sel_hi:[1,0]
	v_pk_mul_f32 v[178:179], v[98:99], 0.5 op_sel_hi:[1,0]
	v_pk_mul_f32 v[176:177], v[80:81], 0.5 op_sel_hi:[1,0]
	v_pk_mul_f32 v[174:175], v[78:79], 0.5 op_sel_hi:[1,0]
	v_pk_mul_f32 v[172:173], v[76:77], 0.5 op_sel_hi:[1,0]
	v_pk_mul_f32 v[170:171], v[74:75], 0.5 op_sel_hi:[1,0]
	v_pk_mul_f32 v[168:169], v[92:93], 0.5 op_sel_hi:[1,0]
	v_pk_mul_f32 v[166:167], v[90:91], 0.5 op_sel_hi:[1,0]
	v_pk_mul_f32 v[164:165], v[84:85], 0.5 op_sel_hi:[1,0]
	v_pk_mul_f32 v[162:163], v[82:83], 0.5 op_sel_hi:[1,0]
	v_pk_mul_f32 v[160:161], v[72:73], 0.5 op_sel_hi:[1,0]
	v_pk_mul_f32 v[158:159], v[70:71], 0.5 op_sel_hi:[1,0]
	v_pk_mul_f32 v[156:157], v[68:69], 0.5 op_sel_hi:[1,0]
	v_pk_mul_f32 v[154:155], v[66:67], 0.5 op_sel_hi:[1,0]
	v_pk_mul_f32 v[152:153], v[62:63], 0.5 op_sel_hi:[1,0]
	v_pk_mul_f32 v[150:151], v[60:61], 0.5 op_sel_hi:[1,0]
	v_pk_mul_f32 v[148:149], v[58:59], 0.5 op_sel_hi:[1,0]
	v_pk_mul_f32 v[146:147], v[56:57], 0.5 op_sel_hi:[1,0]
	v_pk_mul_f32 v[144:145], v[46:47], 0.5 op_sel_hi:[1,0]
	v_pk_mul_f32 v[142:143], v[44:45], 0.5 op_sel_hi:[1,0]
	v_pk_mul_f32 v[140:141], v[38:39], 0.5 op_sel_hi:[1,0]
	v_pk_mul_f32 v[126:127], v[36:37], 0.5 op_sel_hi:[1,0]
	v_pk_mul_f32 v[122:123], v[54:55], 0.5 op_sel_hi:[1,0]
	v_pk_mul_f32 v[120:121], v[52:53], 0.5 op_sel_hi:[1,0]
	v_pk_mul_f32 v[118:119], v[50:51], 0.5 op_sel_hi:[1,0]
	v_pk_mul_f32 v[116:117], v[48:49], 0.5 op_sel_hi:[1,0]
	v_pk_mul_f32 v[114:115], v[30:31], 0.5 op_sel_hi:[1,0]
	v_pk_mul_f32 v[112:113], v[28:29], 0.5 op_sel_hi:[1,0]
	v_pk_mul_f32 v[110:111], v[22:23], 0.5 op_sel_hi:[1,0]
	v_pk_mul_f32 v[108:109], v[20:21], 0.5 op_sel_hi:[1,0]
	v_pk_mul_f32 v[104:105], v[42:43], 0.5 op_sel_hi:[1,0]
	v_pk_mul_f32 v[102:103], v[40:41], 0.5 op_sel_hi:[1,0]
	v_pk_mul_f32 v[100:101], v[34:35], 0.5 op_sel_hi:[1,0]
	v_pk_mul_f32 v[98:99], v[32:33], 0.5 op_sel_hi:[1,0]
	v_pk_mul_f32 v[96:97], v[14:15], 0.5 op_sel_hi:[1,0]
	v_pk_mul_f32 v[94:95], v[12:13], 0.5 op_sel_hi:[1,0]
	v_pk_mul_f32 v[92:93], v[10:11], 0.5 op_sel_hi:[1,0]
	v_pk_mul_f32 v[90:91], v[8:9], 0.5 op_sel_hi:[1,0]
	v_pk_mul_f32 v[88:89], v[26:27], 0.5 op_sel_hi:[1,0]
	v_pk_mul_f32 v[86:87], v[24:25], 0.5 op_sel_hi:[1,0]
	v_pk_mul_f32 v[84:85], v[18:19], 0.5 op_sel_hi:[1,0]
	v_pk_mul_f32 v[82:83], v[16:17], 0.5 op_sel_hi:[1,0]
	v_pk_mul_f32 v[80:81], v[6:7], 0.5 op_sel_hi:[1,0]
	v_pk_mul_f32 v[78:79], v[4:5], 0.5 op_sel_hi:[1,0]
	v_pk_mul_f32 v[76:77], v[2:3], 0.5 op_sel_hi:[1,0]
	v_pk_mul_f32 v[74:75], v[0:1], 0.5 op_sel_hi:[1,0]

; #define PG8_STAGE(bufoff, gbase, voff) do { _Pragma("unroll") for (int _i = 0; _i < 2; ++_i) \
;         __builtin_amdgcn_global_load_lds((const unsigned*)((const char*)(gbase) + (voff)[_i]), (PG8_LAS unsigned*)(lds + (bufoff) + ldsw + _i * 8192), 16, 0, 0); } while (0)
; #define PG8_LDA(dst, b, h) do { _Pragma("unroll") for (int m = 0; m < 4; ++m) _Pragma("unroll") for (int k = 0; k < 2; ++k) dst[m][k] = *(const PG8_LAS bf16x8*)(lds + PG8_SA(b, h) + aoff + m * 2048 + k * 1024); } while (0)
; #define PG8_LDB(dst, b, h) do { _Pragma("unroll") for (int n = 0; n < 2; ++n) _Pragma("unroll") for (int k = 0; k < 2; ++k) dst[n][k] = *(const PG8_LAS bf16x8*)(lds + PG8_SB(b, h) + boff + n * 2048 + k * 1024); } while (0)
; #define PG8_MMA(ai, bj, At, Bt) do { __builtin_amdgcn_s_setprio(1); _Pragma("unroll") for (int m = 0; m < 4; ++m) _Pragma("unroll") for (int n = 0; n < 2; ++n) _Pragma("unroll") for (int k = 0; k < 2; ++k) \
;         acc[ai][bj][m][n] = __builtin_amdgcn_mfma_f32_16x16x32_bf16(Bt[n][k], At[m][k], acc[ai][bj][m][n], 0, 0, 0); __builtin_amdgcn_s_setprio(0); } while (0)
; #define PG8_WAIT_V(n) asm volatile("s_waitcnt vmcnt(" #n ")" ::: "memory")
; #define PG8_WAIT_L(n) asm volatile("s_waitcnt lgkmcnt(" #n ")" ::: "memory")
; #define PG8_BAR __builtin_amdgcn_s_barrier()
; #define PG8_SCHED __builtin_amdgcn_sched_barrier(0)
; template <class Epi, class Sched, bool ALIGN_EPI = false, bool SP2 = false>
; __device__ __forceinline__ void gemm_phase(PG8_LAS unsigned char* lds, const Gemm g, const Sched& S, const Epi& E) {
;     ...
;             PG8_LDB(B0, 0, 0); PG8_LDB(B1, 0, 1); PG8_SCHED; PG8_LDA(At, 0, 0); PG8_STAGE(PG8_SA(1, 1), a1 + hstepA, voffA);
;             PG8_WAIT_V(8); PG8_WAIT_L(0); PG8_BAR; PG8_MMA(0, 0, At, B0); PG8_MMA(0, 1, At, B1); PG8_BAR; PG8_SCHED;
;             PG8_LDA(At, 0, 1); PG8_STAGE(PG8_SB(0, 0), b2, voffB); PG8_STAGE(PG8_SB(0, 1), b2 + hstepB, voffB); PG8_STAGE(PG8_SA(0, 0), a2, voffA);
;             PG8_WAIT_V(8); PG8_WAIT_L(0); PG8_BAR; PG8_MMA(1, 0, At, B0); PG8_MMA(1, 1, At, B1); PG8_BAR; PG8_SCHED;
.LBB0_404:
	s_add_i32 s47, s24, 2
	s_add_u32 s25, s4, 0xfffc0080
	s_addc_u32 s26, s5, -1
	s_add_i32 s48, 0, 0x10000
	s_cmp_eq_u32 s39, s24
	s_cselect_b32 s27, s17, s26
	s_cselect_b32 s26, s19, s25
	s_cselect_b32 s25, s43, s46
	s_cselect_b32 s24, s44, s45
	s_add_i32 s50, 0, 0x14000
	v_add_u32_e32 v60, s48, v177
	v_add_u32_e32 v86, s50, v177
	ds_read_b128 v[48:51], v60
	ds_read_b128 v[52:55], v60 offset:1024
	ds_read_b128 v[56:59], v60 offset:2048
	ds_read_b128 v[60:63], v60 offset:3072
	ds_read_b128 v[66:69], v86
	ds_read_b128 v[78:81], v86 offset:1024
	ds_read_b128 v[82:85], v86 offset:2048
	ds_read_b128 v[86:89], v86 offset:3072
	v_lshl_add_u64 v[186:187], s[4:5], 0, v[168:169]
	s_add_i32 m0, s30, 0xc000
	ds_read_b128 v[202:205], v179
	ds_read_b128 v[206:209], v179 offset:1024
	ds_read_b128 v[210:213], v179 offset:2048
	ds_read_b128 v[214:217], v179 offset:3072
	ds_read_b128 v[218:221], v179 offset:4096
	ds_read_b128 v[222:225], v179 offset:5120
	ds_read_b128 v[240:243], v179 offset:6144
	ds_read_b128 v[244:247], v179 offset:7168
	global_load_lds_dwordx4 v[186:187], off
	v_lshl_add_u64 v[186:187], s[4:5], 0, v[170:171]
	s_add_i32 m0, s30, 0xe000
	s_nop 0
	global_load_lds_dwordx4 v[186:187], off
	s_waitcnt vmcnt(8)
	s_waitcnt lgkmcnt(0)
	s_barrier
	s_setprio 1
	v_mfma_f32_16x16x32_bf16 v[158:161], v[48:51], v[202:205], v[158:161]
	v_mfma_f32_16x16x32_bf16 v[154:157], v[56:59], v[202:205], v[154:157]
	v_mfma_f32_16x16x32_bf16 v[142:145], v[48:51], v[210:213], v[142:145]
	v_mfma_f32_16x16x32_bf16 v[138:141], v[56:59], v[210:213], v[138:141]
	v_mfma_f32_16x16x32_bf16 v[126:129], v[48:51], v[218:221], v[126:129]
	v_mfma_f32_16x16x32_bf16 v[122:125], v[56:59], v[218:221], v[122:125]
	v_mfma_f32_16x16x32_bf16 v[110:113], v[48:51], v[240:243], v[110:113]
	v_mfma_f32_16x16x32_bf16 v[106:109], v[56:59], v[240:243], v[106:109]
	v_mfma_f32_16x16x32_bf16 v[158:161], v[52:55], v[206:209], v[158:161]
	v_mfma_f32_16x16x32_bf16 v[154:157], v[60:63], v[206:209], v[154:157]
	v_mfma_f32_16x16x32_bf16 v[142:145], v[52:55], v[214:217], v[142:145]
	v_mfma_f32_16x16x32_bf16 v[138:141], v[60:63], v[214:217], v[138:141]
	v_mfma_f32_16x16x32_bf16 v[126:129], v[52:55], v[222:225], v[126:129]
	v_mfma_f32_16x16x32_bf16 v[122:125], v[60:63], v[222:225], v[122:125]
	v_mfma_f32_16x16x32_bf16 v[110:113], v[52:55], v[244:247], v[110:113]
	v_mfma_f32_16x16x32_bf16 v[106:109], v[60:63], v[244:247], v[106:109]
	s_setprio 0
	s_setprio 1
	v_mfma_f32_16x16x32_bf16 v[150:153], v[66:69], v[202:205], v[150:153]
	v_mfma_f32_16x16x32_bf16 v[146:149], v[82:85], v[202:205], v[146:149]
	v_mfma_f32_16x16x32_bf16 v[134:137], v[66:69], v[210:213], v[134:137]
	v_mfma_f32_16x16x32_bf16 v[130:133], v[82:85], v[210:213], v[130:133]
	v_mfma_f32_16x16x32_bf16 v[118:121], v[66:69], v[218:221], v[118:121]
	v_mfma_f32_16x16x32_bf16 v[114:117], v[82:85], v[218:221], v[114:117]
	v_mfma_f32_16x16x32_bf16 v[102:105], v[66:69], v[240:243], v[102:105]
	v_mfma_f32_16x16x32_bf16 v[98:101], v[82:85], v[240:243], v[98:101]
	v_mfma_f32_16x16x32_bf16 v[150:153], v[78:81], v[206:209], v[150:153]
	v_mfma_f32_16x16x32_bf16 v[146:149], v[86:89], v[206:209], v[146:149]
	v_mfma_f32_16x16x32_bf16 v[134:137], v[78:81], v[214:217], v[134:137]
	v_mfma_f32_16x16x32_bf16 v[130:133], v[86:89], v[214:217], v[130:133]
	v_mfma_f32_16x16x32_bf16 v[118:121], v[78:81], v[222:225], v[118:121]
	v_mfma_f32_16x16x32_bf16 v[114:117], v[86:89], v[222:225], v[114:117]
	v_mfma_f32_16x16x32_bf16 v[102:105], v[78:81], v[244:247], v[102:105]
	v_mfma_f32_16x16x32_bf16 v[98:101], v[86:89], v[244:247], v[98:101]
	s_setprio 0
	s_barrier
	s_add_i32 s48, s48, s28
	v_lshl_add_u64 v[186:187], s[24:25], 0, v[64:65]
	s_mov_b32 m0, s48
	ds_read_b128 v[202:205], v179 offset:16384
	ds_read_b128 v[206:209], v179 offset:17408
	ds_read_b128 v[210:213], v179 offset:18432
	ds_read_b128 v[214:217], v179 offset:19456
	ds_read_b128 v[218:221], v179 offset:20480
	ds_read_b128 v[222:225], v179 offset:21504
	ds_read_b128 v[240:243], v179 offset:22528
	ds_read_b128 v[244:247], v179 offset:23552
	global_load_lds_dwordx4 v[186:187], off
	s_add_i32 m0, s48, 0x2000
	s_add_u32 s48, s24, 0x40000
	v_lshl_add_u64 v[226:227], s[24:25], 0, v[162:163]
	s_addc_u32 s49, s25, 0
	s_add_i32 s50, s50, s28
	global_load_lds_dwordx4 v[226:227], off
	v_lshl_add_u64 v[248:249], s[48:49], 0, v[64:65]
	s_mov_b32 m0, s50
	v_lshl_add_u64 v[252:253], s[26:27], 0, v[166:167]
	global_load_lds_dwordx4 v[248:249], off
	v_lshl_add_u64 v[248:249], s[48:49], 0, v[162:163]
	s_add_i32 m0, s50, 0x2000
	v_lshl_add_u64 v[234:235], s[26:27], 0, v[164:165]
	global_load_lds_dwordx4 v[248:249], off
	s_mov_b32 m0, s30
	s_nop 0
	global_load_lds_dwordx4 v[252:253], off
	s_mov_b32 m0, s31
	s_nop 0
	global_load_lds_dwordx4 v[234:235], off
	s_waitcnt vmcnt(8)
	s_waitcnt lgkmcnt(0)
	s_barrier
; #define PG8_STAGE(bufoff, gbase, voff) do { _Pragma("unroll") for (int _i = 0; _i < 2; ++_i) \
;         __builtin_amdgcn_global_load_lds((const unsigned*)((const char*)(gbase) + (voff)[_i]), (PG8_LAS unsigned*)(lds + (bufoff) + ldsw + _i * 8192), 16, 0, 0); } while (0)
; #define PG8_LDA(dst, b, h) do { _Pragma("unroll") for (int m = 0; m < 4; ++m) _Pragma("unroll") for (int k = 0; k < 2; ++k) dst[m][k] = *(const PG8_LAS bf16x8*)(lds + PG8_SA(b, h) + aoff + m * 2048 + k * 1024); } while (0)
; #define PG8_LDB(dst, b, h) do { _Pragma("unroll") for (int n = 0; n < 2; ++n) _Pragma("unroll") for (int k = 0; k < 2; ++k) dst[n][k] = *(const PG8_LAS bf16x8*)(lds + PG8_SB(b, h) + boff + n * 2048 + k * 1024); } while (0)
; #define PG8_MMA(ai, bj, At, Bt) do { __builtin_amdgcn_s_setprio(1); _Pragma("unroll") for (int m = 0; m < 4; ++m) _Pragma("unroll") for (int n = 0; n < 2; ++n) _Pragma("unroll") for (int k = 0; k < 2; ++k) \
;         acc[ai][bj][m][n] = __builtin_amdgcn_mfma_f32_16x16x32_bf16(Bt[n][k], At[m][k], acc[ai][bj][m][n], 0, 0, 0); __builtin_amdgcn_s_setprio(0); } while (0)
; #define PG8_WAIT_V(n) asm volatile("s_waitcnt vmcnt(" #n ")" ::: "memory")
; #define PG8_WAIT_L(n) asm volatile("s_waitcnt lgkmcnt(" #n ")" ::: "memory")
; #define PG8_BAR __builtin_amdgcn_s_barrier()
; #define PG8_SCHED __builtin_amdgcn_sched_barrier(0)
; template <class Epi, class Sched, bool ALIGN_EPI = false, bool SP2 = false>
; __device__ __forceinline__ void gemm_phase(PG8_LAS unsigned char* lds, const Gemm g, const Sched& S, const Epi& E) {
;     ...
;             PG8_WAIT_V(8); PG8_WAIT_L(0); PG8_BAR; PG8_MMA(1, 0, At, B0); PG8_MMA(1, 1, At, B1); PG8_BAR; PG8_SCHED;
;             PG8_LDB(B0, 1, 0); PG8_LDB(B1, 1, 1); PG8_SCHED; PG8_LDA(At, 1, 0); PG8_STAGE(PG8_SA(0, 1), a2 + hstepA, voffA);
;             PG8_WAIT_V(8); PG8_WAIT_L(0); PG8_BAR; PG8_MMA(0, 0, At, B0); PG8_MMA(0, 1, At, B1); PG8_BAR; PG8_SCHED;
	s_setprio 1
	v_mfma_f32_16x16x32_bf16 v[94:97], v[48:51], v[202:205], v[94:97]
	v_mfma_f32_16x16x32_bf16 v[90:93], v[56:59], v[202:205], v[90:93]
	v_mfma_f32_16x16x32_bf16 v[44:47], v[48:51], v[210:213], v[44:47]
	v_mfma_f32_16x16x32_bf16 v[40:43], v[56:59], v[210:213], v[40:43]
	v_mfma_f32_16x16x32_bf16 v[28:31], v[48:51], v[218:221], v[28:31]
	v_mfma_f32_16x16x32_bf16 v[24:27], v[56:59], v[218:221], v[24:27]
	v_mfma_f32_16x16x32_bf16 v[12:15], v[48:51], v[240:243], v[12:15]
	v_mfma_f32_16x16x32_bf16 v[8:11], v[56:59], v[240:243], v[8:11]
	v_mfma_f32_16x16x32_bf16 v[94:97], v[52:55], v[206:209], v[94:97]
	v_mfma_f32_16x16x32_bf16 v[90:93], v[60:63], v[206:209], v[90:93]
	v_mfma_f32_16x16x32_bf16 v[44:47], v[52:55], v[214:217], v[44:47]
	v_mfma_f32_16x16x32_bf16 v[40:43], v[60:63], v[214:217], v[40:43]
	v_mfma_f32_16x16x32_bf16 v[28:31], v[52:55], v[222:225], v[28:31]
	v_mfma_f32_16x16x32_bf16 v[24:27], v[60:63], v[222:225], v[24:27]
	v_mfma_f32_16x16x32_bf16 v[12:15], v[52:55], v[244:247], v[12:15]
	v_mfma_f32_16x16x32_bf16 v[8:11], v[60:63], v[244:247], v[8:11]
	s_setprio 0
	s_setprio 1
	v_mfma_f32_16x16x32_bf16 v[36:39], v[66:69], v[210:213], v[36:39]
	v_mfma_f32_16x16x32_bf16 v[32:35], v[82:85], v[210:213], v[32:35]
	v_mfma_f32_16x16x32_bf16 v[20:23], v[66:69], v[218:221], v[20:23]
	v_mfma_f32_16x16x32_bf16 v[16:19], v[82:85], v[218:221], v[16:19]
	v_mfma_f32_16x16x32_bf16 v[4:7], v[66:69], v[240:243], v[4:7]
	v_mfma_f32_16x16x32_bf16 v[0:3], v[82:85], v[240:243], v[0:3]
	v_mfma_f32_16x16x32_bf16 v[48:51], v[66:69], v[202:205], v[74:77]
	v_mfma_f32_16x16x32_bf16 v[52:55], v[82:85], v[202:205], v[70:73]
	v_mfma_f32_16x16x32_bf16 v[36:39], v[78:81], v[214:217], v[36:39]
	v_mfma_f32_16x16x32_bf16 v[32:35], v[86:89], v[214:217], v[32:35]
	v_mfma_f32_16x16x32_bf16 v[20:23], v[78:81], v[222:225], v[20:23]
	v_mfma_f32_16x16x32_bf16 v[16:19], v[86:89], v[222:225], v[16:19]
	v_mfma_f32_16x16x32_bf16 v[4:7], v[78:81], v[244:247], v[4:7]
	v_mfma_f32_16x16x32_bf16 v[0:3], v[86:89], v[244:247], v[0:3]
	v_mfma_f32_16x16x32_bf16 v[48:51], v[78:81], v[206:209], v[48:51]
	v_mfma_f32_16x16x32_bf16 v[52:55], v[86:89], v[206:209], v[52:55]
	s_setprio 0
	s_barrier
	s_add_i32 s48, 0, 0x18000
	s_add_i32 s49, 0, 0x1c000
	v_add_u32_e32 v70, s48, v177
	v_add_u32_e32 v74, s49, v177
	ds_read_b128 v[56:59], v70
	ds_read_b128 v[60:63], v70 offset:1024
	ds_read_b128 v[66:69], v70 offset:2048
	ds_read_b128 v[70:73], v70 offset:3072
	ds_read_b128 v[78:81], v74
	ds_read_b128 v[82:85], v74 offset:1024
	ds_read_b128 v[86:89], v74 offset:2048
	ds_read_b128 v[202:205], v74 offset:3072
	s_add_u32 s26, s26, 0x40000
	s_addc_u32 s27, s27, 0
	s_mov_b32 m0, s34
	v_lshl_add_u64 v[248:249], s[26:27], 0, v[166:167]
	ds_read_b128 v[74:77], v179 offset:32768
	ds_read_b128 v[206:209], v179 offset:33792
	ds_read_b128 v[210:213], v179 offset:34816
	ds_read_b128 v[214:217], v179 offset:35840
	ds_read_b128 v[218:221], v179 offset:36864
	ds_read_b128 v[222:225], v179 offset:37888
	ds_read_b128 v[240:243], v179 offset:38912
	ds_read_b128 v[244:247], v179 offset:39936
	global_load_lds_dwordx4 v[248:249], off
	v_lshl_add_u64 v[248:249], s[26:27], 0, v[164:165]
	s_mov_b32 m0, s35
	s_nop 0
	global_load_lds_dwordx4 v[248:249], off
	s_waitcnt vmcnt(8)
	s_waitcnt lgkmcnt(0)
	s_barrier
	s_setprio 1
	v_mfma_f32_16x16x32_bf16 v[158:161], v[56:59], v[74:77], v[158:161]
	v_mfma_f32_16x16x32_bf16 v[154:157], v[66:69], v[74:77], v[154:157]
	v_mfma_f32_16x16x32_bf16 v[142:145], v[56:59], v[210:213], v[142:145]
	v_mfma_f32_16x16x32_bf16 v[138:141], v[66:69], v[210:213], v[138:141]
	v_mfma_f32_16x16x32_bf16 v[126:129], v[56:59], v[218:221], v[126:129]
	v_mfma_f32_16x16x32_bf16 v[122:125], v[66:69], v[218:221], v[122:125]
	v_mfma_f32_16x16x32_bf16 v[110:113], v[56:59], v[240:243], v[110:113]
	v_mfma_f32_16x16x32_bf16 v[106:109], v[66:69], v[240:243], v[106:109]
	v_mfma_f32_16x16x32_bf16 v[158:161], v[60:63], v[206:209], v[158:161]
	v_mfma_f32_16x16x32_bf16 v[154:157], v[70:73], v[206:209], v[154:157]
	v_mfma_f32_16x16x32_bf16 v[142:145], v[60:63], v[214:217], v[142:145]
	v_mfma_f32_16x16x32_bf16 v[138:141], v[70:73], v[214:217], v[138:141]
	v_mfma_f32_16x16x32_bf16 v[126:129], v[60:63], v[222:225], v[126:129]
	v_mfma_f32_16x16x32_bf16 v[122:125], v[70:73], v[222:225], v[122:125]
	v_mfma_f32_16x16x32_bf16 v[110:113], v[60:63], v[244:247], v[110:113]
	v_mfma_f32_16x16x32_bf16 v[106:109], v[70:73], v[244:247], v[106:109]
	s_setprio 0
	s_setprio 1
	v_mfma_f32_16x16x32_bf16 v[150:153], v[78:81], v[74:77], v[150:153]
	v_mfma_f32_16x16x32_bf16 v[74:77], v[86:89], v[74:77], v[146:149]
	v_mfma_f32_16x16x32_bf16 v[146:149], v[202:205], v[206:209], v[74:77]
	v_mfma_f32_16x16x32_bf16 v[74:77], v[78:81], v[210:213], v[134:137]
	v_mfma_f32_16x16x32_bf16 v[134:137], v[82:85], v[214:217], v[74:77]
	v_mfma_f32_16x16x32_bf16 v[74:77], v[86:89], v[210:213], v[130:133]
	v_mfma_f32_16x16x32_bf16 v[130:133], v[202:205], v[214:217], v[74:77]
	v_mfma_f32_16x16x32_bf16 v[74:77], v[78:81], v[218:221], v[118:121]
	v_mfma_f32_16x16x32_bf16 v[118:121], v[82:85], v[222:225], v[74:77]
	v_mfma_f32_16x16x32_bf16 v[74:77], v[86:89], v[218:221], v[114:117]
	v_mfma_f32_16x16x32_bf16 v[114:117], v[202:205], v[222:225], v[74:77]
	v_mfma_f32_16x16x32_bf16 v[74:77], v[78:81], v[240:243], v[102:105]
	v_mfma_f32_16x16x32_bf16 v[102:105], v[82:85], v[244:247], v[74:77]
	v_mfma_f32_16x16x32_bf16 v[74:77], v[86:89], v[240:243], v[98:101]
	v_mfma_f32_16x16x32_bf16 v[150:153], v[82:85], v[206:209], v[150:153]
	v_mfma_f32_16x16x32_bf16 v[98:101], v[202:205], v[244:247], v[74:77]
	s_setprio 0
	s_barrier
; #define PG8_STAGE(bufoff, gbase, voff) do { _Pragma("unroll") for (int _i = 0; _i < 2; ++_i) \
;         __builtin_amdgcn_global_load_lds((const unsigned*)((const char*)(gbase) + (voff)[_i]), (PG8_LAS unsigned*)(lds + (bufoff) + ldsw + _i * 8192), 16, 0, 0); } while (0)
; #define PG8_LDA(dst, b, h) do { _Pragma("unroll") for (int m = 0; m < 4; ++m) _Pragma("unroll") for (int k = 0; k < 2; ++k) dst[m][k] = *(const PG8_LAS bf16x8*)(lds + PG8_SA(b, h) + aoff + m * 2048 + k * 1024); } while (0)
; #define PG8_MMA(ai, bj, At, Bt) do { __builtin_amdgcn_s_setprio(1); _Pragma("unroll") for (int m = 0; m < 4; ++m) _Pragma("unroll") for (int n = 0; n < 2; ++n) _Pragma("unroll") for (int k = 0; k < 2; ++k) \
;         acc[ai][bj][m][n] = __builtin_amdgcn_mfma_f32_16x16x32_bf16(Bt[n][k], At[m][k], acc[ai][bj][m][n], 0, 0, 0); __builtin_amdgcn_s_setprio(0); } while (0)
; #define PG8_WAIT_V(n) asm volatile("s_waitcnt vmcnt(" #n ")" ::: "memory")
; #define PG8_WAIT_L(n) asm volatile("s_waitcnt lgkmcnt(" #n ")" ::: "memory")
; #define PG8_BAR __builtin_amdgcn_s_barrier()
; #define PG8_SCHED __builtin_amdgcn_sched_barrier(0)
; template <class Epi, class Sched, bool ALIGN_EPI = false, bool SP2 = false>
; __device__ __forceinline__ void gemm_phase(PG8_LAS unsigned char* lds, const Gemm g, const Sched& S, const Epi& E) {
;     ...
;         for (int t = 0; t < ntc; t += 2) {
;     ...
;             PG8_LDA(At, 1, 1); PG8_STAGE(PG8_SB(1, 0), b3, voffB); PG8_STAGE(PG8_SB(1, 1), b3 + hstepB, voffB); PG8_STAGE(PG8_SA(1, 0), a3, voffA);
;             PG8_WAIT_V(8); PG8_WAIT_L(0); PG8_BAR; PG8_MMA(1, 0, At, B0); PG8_MMA(1, 1, At, B1); PG8_BAR; PG8_SCHED;
	s_add_i32 s26, s48, s28
	s_nop 2
	v_lshl_add_u64 v[74:75], v[186:187], 0, s[88:89]
	s_mov_b32 m0, s26
	ds_read_b128 v[206:209], v179 offset:49152
	ds_read_b128 v[210:213], v179 offset:50176
	ds_read_b128 v[214:217], v179 offset:51200
	ds_read_b128 v[218:221], v179 offset:52224
	ds_read_b128 v[222:225], v179 offset:53248
	ds_read_b128 v[240:243], v179 offset:54272
	ds_read_b128 v[244:247], v179 offset:55296
	ds_read_b128 v[248:251], v179 offset:56320
	global_load_lds_dwordx4 v[74:75], off
	s_add_i32 m0, s26, 0x2000
	s_add_u32 s24, s24, 0x40080
	v_lshl_add_u64 v[74:75], v[226:227], 0, s[88:89]
	s_addc_u32 s25, s25, 0
	s_add_i32 s26, s49, s28
	global_load_lds_dwordx4 v[74:75], off
	v_lshl_add_u64 v[74:75], s[24:25], 0, v[64:65]
	s_mov_b32 m0, s26
	s_nop 0
	global_load_lds_dwordx4 v[74:75], off
	v_lshl_add_u64 v[74:75], s[24:25], 0, v[162:163]
	s_add_i32 m0, s26, 0x2000
	s_nop 0
	global_load_lds_dwordx4 v[74:75], off
	v_lshl_add_u64 v[74:75], v[252:253], 0, s[88:89]
	s_mov_b32 m0, s37
	s_nop 0
	global_load_lds_dwordx4 v[74:75], off
	v_lshl_add_u64 v[74:75], v[234:235], 0, s[88:89]
	s_mov_b32 m0, s38
	s_nop 0
	global_load_lds_dwordx4 v[74:75], off
	s_waitcnt vmcnt(8)
	s_waitcnt lgkmcnt(0)
	s_barrier
	s_setprio 1
	v_mfma_f32_16x16x32_bf16 v[74:77], v[56:59], v[206:209], v[94:97]
	v_mfma_f32_16x16x32_bf16 v[94:97], v[60:63], v[210:213], v[74:77]
	v_mfma_f32_16x16x32_bf16 v[74:77], v[66:69], v[206:209], v[90:93]
	v_mfma_f32_16x16x32_bf16 v[44:47], v[56:59], v[214:217], v[44:47]
	v_mfma_f32_16x16x32_bf16 v[40:43], v[66:69], v[214:217], v[40:43]
	v_mfma_f32_16x16x32_bf16 v[28:31], v[56:59], v[222:225], v[28:31]
	v_mfma_f32_16x16x32_bf16 v[24:27], v[66:69], v[222:225], v[24:27]
	v_mfma_f32_16x16x32_bf16 v[12:15], v[56:59], v[244:247], v[12:15]
	v_mfma_f32_16x16x32_bf16 v[8:11], v[66:69], v[244:247], v[8:11]
	v_mfma_f32_16x16x32_bf16 v[90:93], v[70:73], v[210:213], v[74:77]
	v_mfma_f32_16x16x32_bf16 v[44:47], v[60:63], v[218:221], v[44:47]
	v_mfma_f32_16x16x32_bf16 v[40:43], v[70:73], v[218:221], v[40:43]
	v_mfma_f32_16x16x32_bf16 v[28:31], v[60:63], v[240:243], v[28:31]
	v_mfma_f32_16x16x32_bf16 v[24:27], v[70:73], v[240:243], v[24:27]
	v_mfma_f32_16x16x32_bf16 v[12:15], v[60:63], v[248:251], v[12:15]
	v_mfma_f32_16x16x32_bf16 v[8:11], v[70:73], v[248:251], v[8:11]
	s_setprio 0
	s_setprio 1
	v_mfma_f32_16x16x32_bf16 v[48:51], v[78:81], v[206:209], v[48:51]
	v_mfma_f32_16x16x32_bf16 v[74:77], v[82:85], v[210:213], v[48:51]
	v_mfma_f32_16x16x32_bf16 v[48:51], v[86:89], v[206:209], v[52:55]
	v_mfma_f32_16x16x32_bf16 v[36:39], v[78:81], v[214:217], v[36:39]
	v_mfma_f32_16x16x32_bf16 v[32:35], v[86:89], v[214:217], v[32:35]
	v_mfma_f32_16x16x32_bf16 v[20:23], v[78:81], v[222:225], v[20:23]
	v_mfma_f32_16x16x32_bf16 v[16:19], v[86:89], v[222:225], v[16:19]
	v_mfma_f32_16x16x32_bf16 v[4:7], v[78:81], v[244:247], v[4:7]
	v_mfma_f32_16x16x32_bf16 v[0:3], v[86:89], v[244:247], v[0:3]
	v_mfma_f32_16x16x32_bf16 v[70:73], v[202:205], v[210:213], v[48:51]
	v_mfma_f32_16x16x32_bf16 v[36:39], v[82:85], v[218:221], v[36:39]
	v_mfma_f32_16x16x32_bf16 v[32:35], v[202:205], v[218:221], v[32:35]
	v_mfma_f32_16x16x32_bf16 v[20:23], v[82:85], v[240:243], v[20:23]
	v_mfma_f32_16x16x32_bf16 v[16:19], v[202:205], v[240:243], v[16:19]
	v_mfma_f32_16x16x32_bf16 v[4:7], v[82:85], v[248:251], v[4:7]
	v_mfma_f32_16x16x32_bf16 v[0:3], v[202:205], v[248:251], v[0:3]
	s_setprio 0
	s_barrier
	s_add_u32 s4, s4, 0x100
	s_addc_u32 s5, s5, 0
	s_add_u32 s45, s45, 0x100
	s_addc_u32 s46, s46, 0
	s_cmp_ge_i32 s47, s36
	s_mov_b32 s24, s47
	s_cbranch_scc0 .LBB0_404

; #define PG8_STAGE(bufoff, gbase, voff) do { _Pragma("unroll") for (int _i = 0; _i < 2; ++_i) \
;         __builtin_amdgcn_global_load_lds((const unsigned*)((const char*)(gbase) + (voff)[_i]), (PG8_LAS unsigned*)(lds + (bufoff) + ldsw + _i * 8192), 16, 0, 0); } while (0)
; #define PG8_LDA(dst, b, h) do { _Pragma("unroll") for (int m = 0; m < 4; ++m) _Pragma("unroll") for (int k = 0; k < 2; ++k) dst[m][k] = *(const PG8_LAS bf16x8*)(lds + PG8_SA(b, h) + aoff + m * 2048 + k * 1024); } while (0)
; #define PG8_LDB(dst, b, h) do { _Pragma("unroll") for (int n = 0; n < 2; ++n) _Pragma("unroll") for (int k = 0; k < 2; ++k) dst[n][k] = *(const PG8_LAS bf16x8*)(lds + PG8_SB(b, h) + boff + n * 2048 + k * 1024); } while (0)
; #define PG8_MMA(ai, bj, At, Bt) do { __builtin_amdgcn_s_setprio(1); _Pragma("unroll") for (int m = 0; m < 4; ++m) _Pragma("unroll") for (int n = 0; n < 2; ++n) _Pragma("unroll") for (int k = 0; k < 2; ++k) \
;         acc[ai][bj][m][n] = __builtin_amdgcn_mfma_f32_16x16x32_bf16(Bt[n][k], At[m][k], acc[ai][bj][m][n], 0, 0, 0); __builtin_amdgcn_s_setprio(0); } while (0)
; #define PG8_WAIT_V(n) asm volatile("s_waitcnt vmcnt(" #n ")" ::: "memory")
; #define PG8_WAIT_L(n) asm volatile("s_waitcnt lgkmcnt(" #n ")" ::: "memory")
; #define PG8_BAR __builtin_amdgcn_s_barrier()
; #define PG8_SCHED __builtin_amdgcn_sched_barrier(0)
; template <class Epi, class Sched, bool ALIGN_EPI = false, bool SP2 = false>
; __device__ __forceinline__ void gemm_phase(PG8_LAS unsigned char* lds, const Gemm g, const Sched& S, const Epi& E) {
;     ...
;         for (int t = 0; t < ntc; t += 2) {
;             const bool last = (t == ntc - 2);
;             const char* a1 = cA + (size_t)(t + 1) * kstep;
;             const char* a2 = last ? nA : cA + (size_t)(t + 2) * kstep; const char* b2 = last ? nB : cB + (size_t)(t + 2) * kstep;
;             const char* a3 = a2 + kstep; const char* b3 = b2 + kstep;
;             if (last && has_next) S.a_ready(nxt);
;             if constexpr (SP2) {
;             PG8_LDB(B0, 0, 0); PG8_LDB(B1, 0, 1); PG8_SCHED; PG8_LDA(At, 0, 0); PG8_STAGE(PG8_SA(1, 1), a1 + hstepA, voffA);
;             PG8_WAIT_V(8); PG8_WAIT_L(0); PG8_BAR; PG8_MMA(0, 0, At, B0); PG8_MMA(0, 1, At, B1); PG8_BAR; PG8_SCHED;
;             PG8_LDA(At, 0, 1); PG8_STAGE(PG8_SB(0, 0), b2, voffB); PG8_STAGE(PG8_SB(0, 1), b2 + hstepB, voffB); PG8_STAGE(PG8_SA(0, 0), a2, voffA);
.LBB0_425:
	s_add_i32 s51, s28, 2
	s_add_u32 s29, s26, 0xfffc0080
	s_addc_u32 s30, s27, -1
	s_add_i32 s52, 0, 0x10000
	s_cmp_eq_u32 s46, s28
	s_cselect_b32 s31, s2, s30
	s_cselect_b32 s30, s5, s29
	v_add_u32_e32 v64, s52, v168
	s_cselect_b32 s29, s17, s50
	s_cselect_b32 s28, s19, s25
	s_add_i32 s54, 0, 0x14000
	ds_read_b128 v[142:145], v64
	ds_read_b128 v[146:149], v64 offset:1024
	ds_read_b128 v[150:153], v64 offset:2048
	ds_read_b128 v[154:157], v64 offset:3072
	v_add_u32_e32 v64, s54, v168
	ds_read_b128 v[158:161], v64
	ds_read_b128 v[162:165], v64 offset:1024
	ds_read_b128 v[170:173], v64 offset:2048
	ds_read_b128 v[174:177], v64 offset:3072
	v_lshl_add_u64 v[222:223], s[26:27], 0, v[138:139]
	s_add_i32 m0, s37, 0xc000
	ds_read_b128 v[178:181], v169
	ds_read_b128 v[182:185], v169 offset:1024
	ds_read_b128 v[186:189], v169 offset:2048
	ds_read_b128 v[202:205], v169 offset:3072
	ds_read_b128 v[206:209], v169 offset:4096
	ds_read_b128 v[210:213], v169 offset:5120
	ds_read_b128 v[214:217], v169 offset:6144
	ds_read_b128 v[218:221], v169 offset:7168
	global_load_lds_dwordx4 v[222:223], off
	v_lshl_add_u64 v[222:223], s[26:27], 0, v[140:141]
	s_add_i32 m0, s37, 0xe000
	s_nop 0
	global_load_lds_dwordx4 v[222:223], off
	s_waitcnt vmcnt(8)
	s_waitcnt lgkmcnt(0)
	s_barrier
	s_setprio 1
	v_mfma_f32_16x16x32_bf16 v[126:129], v[142:145], v[178:181], v[126:129]
	v_mfma_f32_16x16x32_bf16 v[122:125], v[150:153], v[178:181], v[122:125]
	v_mfma_f32_16x16x32_bf16 v[118:121], v[142:145], v[186:189], v[118:121]
	v_mfma_f32_16x16x32_bf16 v[114:117], v[150:153], v[186:189], v[114:117]
	v_mfma_f32_16x16x32_bf16 v[110:113], v[142:145], v[206:209], v[110:113]
	v_mfma_f32_16x16x32_bf16 v[106:109], v[150:153], v[206:209], v[106:109]
	v_mfma_f32_16x16x32_bf16 v[102:105], v[142:145], v[214:217], v[102:105]
	v_mfma_f32_16x16x32_bf16 v[98:101], v[150:153], v[214:217], v[98:101]
	v_mfma_f32_16x16x32_bf16 v[126:129], v[146:149], v[182:185], v[126:129]
	v_mfma_f32_16x16x32_bf16 v[122:125], v[154:157], v[182:185], v[122:125]
	v_mfma_f32_16x16x32_bf16 v[118:121], v[146:149], v[202:205], v[118:121]
	v_mfma_f32_16x16x32_bf16 v[114:117], v[154:157], v[202:205], v[114:117]
	v_mfma_f32_16x16x32_bf16 v[110:113], v[146:149], v[210:213], v[110:113]
	v_mfma_f32_16x16x32_bf16 v[106:109], v[154:157], v[210:213], v[106:109]
	v_mfma_f32_16x16x32_bf16 v[102:105], v[146:149], v[218:221], v[102:105]
	v_mfma_f32_16x16x32_bf16 v[98:101], v[154:157], v[218:221], v[98:101]
	s_setprio 0
	s_setprio 1
	v_mfma_f32_16x16x32_bf16 v[60:63], v[158:161], v[178:181], v[60:63]
	v_mfma_f32_16x16x32_bf16 v[56:59], v[170:173], v[178:181], v[56:59]
	v_mfma_f32_16x16x32_bf16 v[52:55], v[158:161], v[186:189], v[52:55]
	v_mfma_f32_16x16x32_bf16 v[48:51], v[170:173], v[186:189], v[48:51]
	v_mfma_f32_16x16x32_bf16 v[44:47], v[158:161], v[206:209], v[44:47]
	v_mfma_f32_16x16x32_bf16 v[40:43], v[170:173], v[206:209], v[40:43]
	v_mfma_f32_16x16x32_bf16 v[36:39], v[158:161], v[214:217], v[36:39]
	v_mfma_f32_16x16x32_bf16 v[32:35], v[170:173], v[214:217], v[32:35]
	v_mfma_f32_16x16x32_bf16 v[60:63], v[162:165], v[182:185], v[60:63]
	v_mfma_f32_16x16x32_bf16 v[56:59], v[174:177], v[182:185], v[56:59]
	v_mfma_f32_16x16x32_bf16 v[52:55], v[162:165], v[202:205], v[52:55]
	v_mfma_f32_16x16x32_bf16 v[48:51], v[174:177], v[202:205], v[48:51]
	v_mfma_f32_16x16x32_bf16 v[44:47], v[162:165], v[210:213], v[44:47]
	v_mfma_f32_16x16x32_bf16 v[40:43], v[174:177], v[210:213], v[40:43]
	v_mfma_f32_16x16x32_bf16 v[36:39], v[162:165], v[218:221], v[36:39]
	v_mfma_f32_16x16x32_bf16 v[32:35], v[174:177], v[218:221], v[32:35]
	s_setprio 0
	s_barrier
	s_add_i32 s52, s52, s34
	v_lshl_add_u64 v[222:223], s[28:29], 0, v[134:135]
	s_mov_b32 m0, s52
	ds_read_b128 v[178:181], v169 offset:16384
	ds_read_b128 v[182:185], v169 offset:17408
	ds_read_b128 v[186:189], v169 offset:18432
	ds_read_b128 v[202:205], v169 offset:19456
	ds_read_b128 v[206:209], v169 offset:20480
	ds_read_b128 v[210:213], v169 offset:21504
	ds_read_b128 v[214:217], v169 offset:22528
	ds_read_b128 v[218:221], v169 offset:23552
	global_load_lds_dwordx4 v[222:223], off
	s_add_i32 m0, s52, 0x2000
	s_add_u32 s52, s28, 0x40000
	v_lshl_add_u64 v[224:225], s[28:29], 0, v[130:131]
	s_addc_u32 s53, s29, 0
	s_add_i32 s54, s54, s34
	global_load_lds_dwordx4 v[224:225], off
	v_lshl_add_u64 v[226:227], s[52:53], 0, v[134:135]
	s_mov_b32 m0, s54
	v_lshl_add_u64 v[234:235], s[30:31], 0, v[132:133]
	global_load_lds_dwordx4 v[226:227], off
	v_lshl_add_u64 v[226:227], s[52:53], 0, v[130:131]
	s_add_i32 m0, s54, 0x2000
	s_nop 0
	global_load_lds_dwordx4 v[226:227], off
	v_lshl_add_u64 v[226:227], s[30:31], 0, v[136:137]
	s_mov_b32 m0, s37
	s_nop 0
	global_load_lds_dwordx4 v[226:227], off
	s_mov_b32 m0, s38
	s_nop 0
	global_load_lds_dwordx4 v[234:235], off
	s_waitcnt vmcnt(8)
	s_waitcnt lgkmcnt(0)
	s_barrier
; #define PG8_STAGE(bufoff, gbase, voff) do { _Pragma("unroll") for (int _i = 0; _i < 2; ++_i) \
;         __builtin_amdgcn_global_load_lds((const unsigned*)((const char*)(gbase) + (voff)[_i]), (PG8_LAS unsigned*)(lds + (bufoff) + ldsw + _i * 8192), 16, 0, 0); } while (0)
; #define PG8_LDA(dst, b, h) do { _Pragma("unroll") for (int m = 0; m < 4; ++m) _Pragma("unroll") for (int k = 0; k < 2; ++k) dst[m][k] = *(const PG8_LAS bf16x8*)(lds + PG8_SA(b, h) + aoff + m * 2048 + k * 1024); } while (0)
; #define PG8_LDB(dst, b, h) do { _Pragma("unroll") for (int n = 0; n < 2; ++n) _Pragma("unroll") for (int k = 0; k < 2; ++k) dst[n][k] = *(const PG8_LAS bf16x8*)(lds + PG8_SB(b, h) + boff + n * 2048 + k * 1024); } while (0)
; #define PG8_MMA(ai, bj, At, Bt) do { __builtin_amdgcn_s_setprio(1); _Pragma("unroll") for (int m = 0; m < 4; ++m) _Pragma("unroll") for (int n = 0; n < 2; ++n) _Pragma("unroll") for (int k = 0; k < 2; ++k) \
;         acc[ai][bj][m][n] = __builtin_amdgcn_mfma_f32_16x16x32_bf16(Bt[n][k], At[m][k], acc[ai][bj][m][n], 0, 0, 0); __builtin_amdgcn_s_setprio(0); } while (0)
; #define PG8_WAIT_V(n) asm volatile("s_waitcnt vmcnt(" #n ")" ::: "memory")
; #define PG8_WAIT_L(n) asm volatile("s_waitcnt lgkmcnt(" #n ")" ::: "memory")
; #define PG8_BAR __builtin_amdgcn_s_barrier()
; #define PG8_SCHED __builtin_amdgcn_sched_barrier(0)
; template <class Epi, class Sched, bool ALIGN_EPI = false, bool SP2 = false>
; __device__ __forceinline__ void gemm_phase(PG8_LAS unsigned char* lds, const Gemm g, const Sched& S, const Epi& E) {
;     ...
;             PG8_WAIT_V(8); PG8_WAIT_L(0); PG8_BAR; PG8_MMA(1, 0, At, B0); PG8_MMA(1, 1, At, B1); PG8_BAR; PG8_SCHED;
;             PG8_LDB(B0, 1, 0); PG8_LDB(B1, 1, 1); PG8_SCHED; PG8_LDA(At, 1, 0); PG8_STAGE(PG8_SA(0, 1), a2 + hstepA, voffA);
;             PG8_WAIT_V(8); PG8_WAIT_L(0); PG8_BAR; PG8_MMA(0, 0, At, B0); PG8_MMA(0, 1, At, B1); PG8_BAR; PG8_SCHED;
	s_setprio 1
	v_mfma_f32_16x16x32_bf16 v[94:97], v[142:145], v[178:181], v[94:97]
	v_mfma_f32_16x16x32_bf16 v[90:93], v[150:153], v[178:181], v[90:93]
	v_mfma_f32_16x16x32_bf16 v[86:89], v[142:145], v[186:189], v[86:89]
	v_mfma_f32_16x16x32_bf16 v[82:85], v[150:153], v[186:189], v[82:85]
	v_mfma_f32_16x16x32_bf16 v[78:81], v[142:145], v[206:209], v[78:81]
	v_mfma_f32_16x16x32_bf16 v[74:77], v[150:153], v[206:209], v[74:77]
	v_mfma_f32_16x16x32_bf16 v[70:73], v[142:145], v[214:217], v[70:73]
	v_mfma_f32_16x16x32_bf16 v[66:69], v[150:153], v[214:217], v[66:69]
	v_mfma_f32_16x16x32_bf16 v[94:97], v[146:149], v[182:185], v[94:97]
	v_mfma_f32_16x16x32_bf16 v[90:93], v[154:157], v[182:185], v[90:93]
	v_mfma_f32_16x16x32_bf16 v[86:89], v[146:149], v[202:205], v[86:89]
	v_mfma_f32_16x16x32_bf16 v[82:85], v[154:157], v[202:205], v[82:85]
	v_mfma_f32_16x16x32_bf16 v[78:81], v[146:149], v[210:213], v[78:81]
	v_mfma_f32_16x16x32_bf16 v[74:77], v[154:157], v[210:213], v[74:77]
	v_mfma_f32_16x16x32_bf16 v[70:73], v[146:149], v[218:221], v[70:73]
	v_mfma_f32_16x16x32_bf16 v[66:69], v[154:157], v[218:221], v[66:69]
	s_setprio 0
	s_setprio 1
	v_mfma_f32_16x16x32_bf16 v[28:31], v[158:161], v[178:181], v[28:31]
	v_mfma_f32_16x16x32_bf16 v[24:27], v[170:173], v[178:181], v[24:27]
	v_mfma_f32_16x16x32_bf16 v[20:23], v[158:161], v[186:189], v[20:23]
	v_mfma_f32_16x16x32_bf16 v[16:19], v[170:173], v[186:189], v[16:19]
	v_mfma_f32_16x16x32_bf16 v[12:15], v[158:161], v[206:209], v[12:15]
	v_mfma_f32_16x16x32_bf16 v[8:11], v[170:173], v[206:209], v[8:11]
	v_mfma_f32_16x16x32_bf16 v[4:7], v[158:161], v[214:217], v[4:7]
	v_mfma_f32_16x16x32_bf16 v[0:3], v[170:173], v[214:217], v[0:3]
	v_mfma_f32_16x16x32_bf16 v[28:31], v[162:165], v[182:185], v[28:31]
	v_mfma_f32_16x16x32_bf16 v[24:27], v[174:177], v[182:185], v[24:27]
	v_mfma_f32_16x16x32_bf16 v[20:23], v[162:165], v[202:205], v[20:23]
	v_mfma_f32_16x16x32_bf16 v[16:19], v[174:177], v[202:205], v[16:19]
	v_mfma_f32_16x16x32_bf16 v[12:15], v[162:165], v[210:213], v[12:15]
	v_mfma_f32_16x16x32_bf16 v[8:11], v[174:177], v[210:213], v[8:11]
	v_mfma_f32_16x16x32_bf16 v[4:7], v[162:165], v[218:221], v[4:7]
	v_mfma_f32_16x16x32_bf16 v[0:3], v[174:177], v[218:221], v[0:3]
	s_setprio 0
	s_barrier
	s_add_i32 s52, 0, 0x18000
	v_add_u32_e32 v64, s52, v168
	s_add_i32 s53, 0, 0x1c000
	ds_read_b128 v[142:145], v64
	ds_read_b128 v[146:149], v64 offset:1024
	ds_read_b128 v[150:153], v64 offset:2048
	ds_read_b128 v[154:157], v64 offset:3072
	v_add_u32_e32 v64, s53, v168
	ds_read_b128 v[158:161], v64
	ds_read_b128 v[162:165], v64 offset:1024
	ds_read_b128 v[170:173], v64 offset:2048
	ds_read_b128 v[174:177], v64 offset:3072
	s_add_u32 s30, s30, 0x40000
	s_addc_u32 s31, s31, 0
	s_mov_b32 m0, s39
	v_lshl_add_u64 v[240:241], s[30:31], 0, v[136:137]
	ds_read_b128 v[178:181], v169 offset:32768
	ds_read_b128 v[182:185], v169 offset:33792
	ds_read_b128 v[186:189], v169 offset:34816
	ds_read_b128 v[202:205], v169 offset:35840
	ds_read_b128 v[206:209], v169 offset:36864
	ds_read_b128 v[210:213], v169 offset:37888
	ds_read_b128 v[214:217], v169 offset:38912
	ds_read_b128 v[218:221], v169 offset:39936
	global_load_lds_dwordx4 v[240:241], off
	v_lshl_add_u64 v[240:241], s[30:31], 0, v[132:133]
	s_mov_b32 m0, s40
	s_nop 0
	global_load_lds_dwordx4 v[240:241], off
	s_waitcnt vmcnt(8)
	s_waitcnt lgkmcnt(0)
	s_barrier
	s_setprio 1
	v_mfma_f32_16x16x32_bf16 v[126:129], v[142:145], v[178:181], v[126:129]
	v_mfma_f32_16x16x32_bf16 v[122:125], v[150:153], v[178:181], v[122:125]
	v_mfma_f32_16x16x32_bf16 v[118:121], v[142:145], v[186:189], v[118:121]
	v_mfma_f32_16x16x32_bf16 v[114:117], v[150:153], v[186:189], v[114:117]
	v_mfma_f32_16x16x32_bf16 v[110:113], v[142:145], v[206:209], v[110:113]
	v_mfma_f32_16x16x32_bf16 v[106:109], v[150:153], v[206:209], v[106:109]
	v_mfma_f32_16x16x32_bf16 v[102:105], v[142:145], v[214:217], v[102:105]
	v_mfma_f32_16x16x32_bf16 v[98:101], v[150:153], v[214:217], v[98:101]
	v_mfma_f32_16x16x32_bf16 v[126:129], v[146:149], v[182:185], v[126:129]
	v_mfma_f32_16x16x32_bf16 v[122:125], v[154:157], v[182:185], v[122:125]
	v_mfma_f32_16x16x32_bf16 v[118:121], v[146:149], v[202:205], v[118:121]
	v_mfma_f32_16x16x32_bf16 v[114:117], v[154:157], v[202:205], v[114:117]
	v_mfma_f32_16x16x32_bf16 v[110:113], v[146:149], v[210:213], v[110:113]
	v_mfma_f32_16x16x32_bf16 v[106:109], v[154:157], v[210:213], v[106:109]
	v_mfma_f32_16x16x32_bf16 v[102:105], v[146:149], v[218:221], v[102:105]
	v_mfma_f32_16x16x32_bf16 v[98:101], v[154:157], v[218:221], v[98:101]
	s_setprio 0
	s_setprio 1
	v_mfma_f32_16x16x32_bf16 v[60:63], v[158:161], v[178:181], v[60:63]
	v_mfma_f32_16x16x32_bf16 v[56:59], v[170:173], v[178:181], v[56:59]
	v_mfma_f32_16x16x32_bf16 v[52:55], v[158:161], v[186:189], v[52:55]
	v_mfma_f32_16x16x32_bf16 v[48:51], v[170:173], v[186:189], v[48:51]
	v_mfma_f32_16x16x32_bf16 v[44:47], v[158:161], v[206:209], v[44:47]
	v_mfma_f32_16x16x32_bf16 v[40:43], v[170:173], v[206:209], v[40:43]
	v_mfma_f32_16x16x32_bf16 v[36:39], v[158:161], v[214:217], v[36:39]
	v_mfma_f32_16x16x32_bf16 v[32:35], v[170:173], v[214:217], v[32:35]
	v_mfma_f32_16x16x32_bf16 v[60:63], v[162:165], v[182:185], v[60:63]
	v_mfma_f32_16x16x32_bf16 v[56:59], v[174:177], v[182:185], v[56:59]
	v_mfma_f32_16x16x32_bf16 v[52:55], v[162:165], v[202:205], v[52:55]
	v_mfma_f32_16x16x32_bf16 v[48:51], v[174:177], v[202:205], v[48:51]
	v_mfma_f32_16x16x32_bf16 v[44:47], v[162:165], v[210:213], v[44:47]
	v_mfma_f32_16x16x32_bf16 v[40:43], v[174:177], v[210:213], v[40:43]
	v_mfma_f32_16x16x32_bf16 v[36:39], v[162:165], v[218:221], v[36:39]
	v_mfma_f32_16x16x32_bf16 v[32:35], v[174:177], v[218:221], v[32:35]
	s_setprio 0
	s_barrier
; #define PG8_STAGE(bufoff, gbase, voff) do { _Pragma("unroll") for (int _i = 0; _i < 2; ++_i) \
;         __builtin_amdgcn_global_load_lds((const unsigned*)((const char*)(gbase) + (voff)[_i]), (PG8_LAS unsigned*)(lds + (bufoff) + ldsw + _i * 8192), 16, 0, 0); } while (0)
; #define PG8_LDA(dst, b, h) do { _Pragma("unroll") for (int m = 0; m < 4; ++m) _Pragma("unroll") for (int k = 0; k < 2; ++k) dst[m][k] = *(const PG8_LAS bf16x8*)(lds + PG8_SA(b, h) + aoff + m * 2048 + k * 1024); } while (0)
; #define PG8_MMA(ai, bj, At, Bt) do { __builtin_amdgcn_s_setprio(1); _Pragma("unroll") for (int m = 0; m < 4; ++m) _Pragma("unroll") for (int n = 0; n < 2; ++n) _Pragma("unroll") for (int k = 0; k < 2; ++k) \
;         acc[ai][bj][m][n] = __builtin_amdgcn_mfma_f32_16x16x32_bf16(Bt[n][k], At[m][k], acc[ai][bj][m][n], 0, 0, 0); __builtin_amdgcn_s_setprio(0); } while (0)
; #define PG8_WAIT_V(n) asm volatile("s_waitcnt vmcnt(" #n ")" ::: "memory")
; #define PG8_WAIT_L(n) asm volatile("s_waitcnt lgkmcnt(" #n ")" ::: "memory")
; #define PG8_BAR __builtin_amdgcn_s_barrier()
; #define PG8_SCHED __builtin_amdgcn_sched_barrier(0)
; template <class Epi, class Sched, bool ALIGN_EPI = false, bool SP2 = false>
; __device__ __forceinline__ void gemm_phase(PG8_LAS unsigned char* lds, const Gemm g, const Sched& S, const Epi& E) {
;     ...
;         for (int t = 0; t < ntc; t += 2) {
;     ...
;             PG8_LDA(At, 1, 1); PG8_STAGE(PG8_SB(1, 0), b3, voffB); PG8_STAGE(PG8_SB(1, 1), b3 + hstepB, voffB); PG8_STAGE(PG8_SA(1, 0), a3, voffA);
;             PG8_WAIT_V(8); PG8_WAIT_L(0); PG8_BAR; PG8_MMA(1, 0, At, B0); PG8_MMA(1, 1, At, B1); PG8_BAR; PG8_SCHED;
	s_add_i32 s30, s52, s34
	v_lshl_add_u64 v[222:223], v[222:223], 0, s[88:89]
	s_mov_b32 m0, s30
	ds_read_b128 v[178:181], v169 offset:49152
	ds_read_b128 v[182:185], v169 offset:50176
	ds_read_b128 v[186:189], v169 offset:51200
	ds_read_b128 v[202:205], v169 offset:52224
	ds_read_b128 v[206:209], v169 offset:53248
	ds_read_b128 v[210:213], v169 offset:54272
	ds_read_b128 v[214:217], v169 offset:55296
	ds_read_b128 v[218:221], v169 offset:56320
	global_load_lds_dwordx4 v[222:223], off
	s_add_i32 m0, s30, 0x2000
	s_add_u32 s28, s28, 0x40080
	v_lshl_add_u64 v[222:223], v[224:225], 0, s[88:89]
	s_addc_u32 s29, s29, 0
	s_add_i32 s30, s53, s34
	global_load_lds_dwordx4 v[222:223], off
	v_lshl_add_u64 v[222:223], s[28:29], 0, v[134:135]
	s_mov_b32 m0, s30
	s_nop 0
	global_load_lds_dwordx4 v[222:223], off
	v_lshl_add_u64 v[222:223], s[28:29], 0, v[130:131]
	s_add_i32 m0, s30, 0x2000
	s_nop 0
	global_load_lds_dwordx4 v[222:223], off
	v_lshl_add_u64 v[222:223], v[226:227], 0, s[88:89]
	s_mov_b32 m0, s44
	s_nop 0
	global_load_lds_dwordx4 v[222:223], off
	v_lshl_add_u64 v[222:223], v[234:235], 0, s[88:89]
	s_mov_b32 m0, s45
	s_nop 0
	global_load_lds_dwordx4 v[222:223], off
	s_waitcnt vmcnt(8)
	s_waitcnt lgkmcnt(0)
	s_barrier
	s_setprio 1
	v_mfma_f32_16x16x32_bf16 v[94:97], v[142:145], v[178:181], v[94:97]
	v_mfma_f32_16x16x32_bf16 v[90:93], v[150:153], v[178:181], v[90:93]
	v_mfma_f32_16x16x32_bf16 v[86:89], v[142:145], v[186:189], v[86:89]
	v_mfma_f32_16x16x32_bf16 v[82:85], v[150:153], v[186:189], v[82:85]
	v_mfma_f32_16x16x32_bf16 v[78:81], v[142:145], v[206:209], v[78:81]
	v_mfma_f32_16x16x32_bf16 v[74:77], v[150:153], v[206:209], v[74:77]
	v_mfma_f32_16x16x32_bf16 v[70:73], v[142:145], v[214:217], v[70:73]
	v_mfma_f32_16x16x32_bf16 v[66:69], v[150:153], v[214:217], v[66:69]
	v_mfma_f32_16x16x32_bf16 v[94:97], v[146:149], v[182:185], v[94:97]
	v_mfma_f32_16x16x32_bf16 v[90:93], v[154:157], v[182:185], v[90:93]
	v_mfma_f32_16x16x32_bf16 v[86:89], v[146:149], v[202:205], v[86:89]
	v_mfma_f32_16x16x32_bf16 v[82:85], v[154:157], v[202:205], v[82:85]
	v_mfma_f32_16x16x32_bf16 v[78:81], v[146:149], v[210:213], v[78:81]
	v_mfma_f32_16x16x32_bf16 v[74:77], v[154:157], v[210:213], v[74:77]
	v_mfma_f32_16x16x32_bf16 v[70:73], v[146:149], v[218:221], v[70:73]
	v_mfma_f32_16x16x32_bf16 v[66:69], v[154:157], v[218:221], v[66:69]
	s_setprio 0
	s_setprio 1
	v_mfma_f32_16x16x32_bf16 v[28:31], v[158:161], v[178:181], v[28:31]
	v_mfma_f32_16x16x32_bf16 v[24:27], v[170:173], v[178:181], v[24:27]
	v_mfma_f32_16x16x32_bf16 v[20:23], v[158:161], v[186:189], v[20:23]
	v_mfma_f32_16x16x32_bf16 v[16:19], v[170:173], v[186:189], v[16:19]
	v_mfma_f32_16x16x32_bf16 v[12:15], v[158:161], v[206:209], v[12:15]
	v_mfma_f32_16x16x32_bf16 v[8:11], v[170:173], v[206:209], v[8:11]
	v_mfma_f32_16x16x32_bf16 v[4:7], v[158:161], v[214:217], v[4:7]
	v_mfma_f32_16x16x32_bf16 v[0:3], v[170:173], v[214:217], v[0:3]
	v_mfma_f32_16x16x32_bf16 v[28:31], v[162:165], v[182:185], v[28:31]
	v_mfma_f32_16x16x32_bf16 v[24:27], v[174:177], v[182:185], v[24:27]
	v_mfma_f32_16x16x32_bf16 v[20:23], v[162:165], v[202:205], v[20:23]
	v_mfma_f32_16x16x32_bf16 v[16:19], v[174:177], v[202:205], v[16:19]
	v_mfma_f32_16x16x32_bf16 v[12:15], v[162:165], v[210:213], v[12:15]
	v_mfma_f32_16x16x32_bf16 v[8:11], v[174:177], v[210:213], v[8:11]
	v_mfma_f32_16x16x32_bf16 v[4:7], v[162:165], v[218:221], v[4:7]
	v_mfma_f32_16x16x32_bf16 v[0:3], v[174:177], v[218:221], v[0:3]
	s_setprio 0
	s_barrier
	s_add_u32 s26, s26, 0x100
	s_addc_u32 s27, s27, 0
	s_add_u32 s25, s25, 0x100
	s_addc_u32 s50, s50, 0
	s_cmp_ge_i32 s51, s41
	s_mov_b32 s28, s51
	s_cbranch_scc0 .LBB0_425

; #define PG8_STAGE(bufoff, gbase, voff) do { _Pragma("unroll") for (int _i = 0; _i < 2; ++_i) \
;         __builtin_amdgcn_global_load_lds((const unsigned*)((const char*)(gbase) + (voff)[_i]), (PG8_LAS unsigned*)(lds + (bufoff) + ldsw + _i * 8192), 16, 0, 0); } while (0)
; #define PG8_LDA(dst, b, h) do { _Pragma("unroll") for (int m = 0; m < 4; ++m) _Pragma("unroll") for (int k = 0; k < 2; ++k) dst[m][k] = *(const PG8_LAS bf16x8*)(lds + PG8_SA(b, h) + aoff + m * 2048 + k * 1024); } while (0)
; #define PG8_LDB(dst, b, h) do { _Pragma("unroll") for (int n = 0; n < 2; ++n) _Pragma("unroll") for (int k = 0; k < 2; ++k) dst[n][k] = *(const PG8_LAS bf16x8*)(lds + PG8_SB(b, h) + boff + n * 2048 + k * 1024); } while (0)
; #define PG8_MMA(ai, bj, At, Bt) do { __builtin_amdgcn_s_setprio(1); _Pragma("unroll") for (int m = 0; m < 4; ++m) _Pragma("unroll") for (int n = 0; n < 2; ++n) _Pragma("unroll") for (int k = 0; k < 2; ++k) \
;         acc[ai][bj][m][n] = __builtin_amdgcn_mfma_f32_16x16x32_bf16(Bt[n][k], At[m][k], acc[ai][bj][m][n], 0, 0, 0); __builtin_amdgcn_s_setprio(0); } while (0)
; #define PG8_WAIT_V(n) asm volatile("s_waitcnt vmcnt(" #n ")" ::: "memory")
; #define PG8_WAIT_L(n) asm volatile("s_waitcnt lgkmcnt(" #n ")" ::: "memory")
; #define PG8_BAR __builtin_amdgcn_s_barrier()
; #define PG8_SCHED __builtin_amdgcn_sched_barrier(0)
; template <class Epi, class Sched, bool ALIGN_EPI = false, bool SP2 = false>
; __device__ __forceinline__ void gemm_phase(PG8_LAS unsigned char* lds, const Gemm g, const Sched& S, const Epi& E) {
;     ...
;         for (int t = 0; t < ntc; t += 2) {
;             const bool last = (t == ntc - 2);
;             const char* a1 = cA + (size_t)(t + 1) * kstep;
;             const char* a2 = last ? nA : cA + (size_t)(t + 2) * kstep; const char* b2 = last ? nB : cB + (size_t)(t + 2) * kstep;
;             const char* a3 = a2 + kstep; const char* b3 = b2 + kstep;
;             if (last && has_next) S.a_ready(nxt);
;             if constexpr (SP2) {
;             PG8_LDB(B0, 0, 0); PG8_LDB(B1, 0, 1); PG8_SCHED; PG8_LDA(At, 0, 0); PG8_STAGE(PG8_SA(1, 1), a1 + hstepA, voffA);
;             PG8_WAIT_V(8); PG8_WAIT_L(0); PG8_BAR; PG8_MMA(0, 0, At, B0); PG8_MMA(0, 1, At, B1); PG8_BAR; PG8_SCHED;
;             PG8_LDA(At, 0, 1); PG8_STAGE(PG8_SB(0, 0), b2, voffB); PG8_STAGE(PG8_SB(0, 1), b2 + hstepB, voffB); PG8_STAGE(PG8_SA(0, 0), a2, voffA);
.LBB0_654:
	s_add_i32 s49, s22, 2
	s_add_u32 s23, s4, 0xfffc0080
	s_addc_u32 s24, s5, -1
	s_add_i32 s50, 0, 0x10000
	s_cmp_eq_u32 s40, s22
	s_cselect_b32 s25, s15, s24
	s_cselect_b32 s24, s17, s23
	s_cselect_b32 s23, s45, s48
	s_cselect_b32 s22, s46, s47
	s_add_i32 s52, 0, 0x14000
	v_add_u32_e32 v142, s50, v218
	v_add_u32_e32 v158, s52, v218
	ds_read_b128 v[130:133], v142
	ds_read_b128 v[134:137], v142 offset:1024
	ds_read_b128 v[138:141], v142 offset:2048
	ds_read_b128 v[142:145], v142 offset:3072
	ds_read_b128 v[146:149], v158
	ds_read_b128 v[150:153], v158 offset:1024
	ds_read_b128 v[154:157], v158 offset:2048
	ds_read_b128 v[158:161], v158 offset:3072
	v_lshl_add_u64 v[220:221], s[4:5], 0, v[208:209]
	s_add_i32 m0, s29, 0xc000
	ds_read_b128 v[162:165], v219
	ds_read_b128 v[166:169], v219 offset:1024
	ds_read_b128 v[170:173], v219 offset:2048
	ds_read_b128 v[174:177], v219 offset:3072
	ds_read_b128 v[178:181], v219 offset:4096
	ds_read_b128 v[182:185], v219 offset:5120
	ds_read_b128 v[186:189], v219 offset:6144
	ds_read_b128 v[212:215], v219 offset:7168
	global_load_lds_dwordx4 v[220:221], off
	v_lshl_add_u64 v[220:221], s[4:5], 0, v[210:211]
	s_add_i32 m0, s29, 0xe000
	s_nop 0
	global_load_lds_dwordx4 v[220:221], off
	s_waitcnt vmcnt(8)
	s_waitcnt lgkmcnt(0)
	s_barrier
	s_setprio 1
	v_mfma_f32_16x16x32_bf16 v[122:125], v[130:133], v[162:165], v[122:125]
	v_mfma_f32_16x16x32_bf16 v[126:129], v[138:141], v[162:165], v[126:129]
	v_mfma_f32_16x16x32_bf16 v[110:113], v[130:133], v[170:173], v[110:113]
	v_mfma_f32_16x16x32_bf16 v[106:109], v[138:141], v[170:173], v[106:109]
	v_mfma_f32_16x16x32_bf16 v[94:97], v[130:133], v[178:181], v[94:97]
	v_mfma_f32_16x16x32_bf16 v[90:93], v[138:141], v[178:181], v[90:93]
	v_mfma_f32_16x16x32_bf16 v[78:81], v[130:133], v[186:189], v[78:81]
	v_mfma_f32_16x16x32_bf16 v[74:77], v[138:141], v[186:189], v[74:77]
	v_mfma_f32_16x16x32_bf16 v[122:125], v[134:137], v[166:169], v[122:125]
	v_mfma_f32_16x16x32_bf16 v[126:129], v[142:145], v[166:169], v[126:129]
	v_mfma_f32_16x16x32_bf16 v[110:113], v[134:137], v[174:177], v[110:113]
	v_mfma_f32_16x16x32_bf16 v[106:109], v[142:145], v[174:177], v[106:109]
	v_mfma_f32_16x16x32_bf16 v[94:97], v[134:137], v[182:185], v[94:97]
	v_mfma_f32_16x16x32_bf16 v[90:93], v[142:145], v[182:185], v[90:93]
	v_mfma_f32_16x16x32_bf16 v[78:81], v[134:137], v[212:215], v[78:81]
	v_mfma_f32_16x16x32_bf16 v[74:77], v[142:145], v[212:215], v[74:77]
	s_setprio 0
	s_setprio 1
	v_mfma_f32_16x16x32_bf16 v[118:121], v[146:149], v[162:165], v[118:121]
	v_mfma_f32_16x16x32_bf16 v[114:117], v[154:157], v[162:165], v[114:117]
	v_mfma_f32_16x16x32_bf16 v[102:105], v[146:149], v[170:173], v[102:105]
	v_mfma_f32_16x16x32_bf16 v[98:101], v[154:157], v[170:173], v[98:101]
	v_mfma_f32_16x16x32_bf16 v[86:89], v[146:149], v[178:181], v[86:89]
	v_mfma_f32_16x16x32_bf16 v[82:85], v[154:157], v[178:181], v[82:85]
	v_mfma_f32_16x16x32_bf16 v[70:73], v[146:149], v[186:189], v[70:73]
	v_mfma_f32_16x16x32_bf16 v[66:69], v[154:157], v[186:189], v[66:69]
	v_mfma_f32_16x16x32_bf16 v[118:121], v[150:153], v[166:169], v[118:121]
	v_mfma_f32_16x16x32_bf16 v[114:117], v[158:161], v[166:169], v[114:117]
	v_mfma_f32_16x16x32_bf16 v[102:105], v[150:153], v[174:177], v[102:105]
	v_mfma_f32_16x16x32_bf16 v[98:101], v[158:161], v[174:177], v[98:101]
	v_mfma_f32_16x16x32_bf16 v[86:89], v[150:153], v[182:185], v[86:89]
	v_mfma_f32_16x16x32_bf16 v[82:85], v[158:161], v[182:185], v[82:85]
	v_mfma_f32_16x16x32_bf16 v[70:73], v[150:153], v[212:215], v[70:73]
	v_mfma_f32_16x16x32_bf16 v[66:69], v[158:161], v[212:215], v[66:69]
	s_setprio 0
	s_barrier
	s_add_i32 s50, s50, s26
	v_lshl_add_u64 v[220:221], s[22:23], 0, v[64:65]
	s_mov_b32 m0, s50
	ds_read_b128 v[162:165], v219 offset:16384
	ds_read_b128 v[166:169], v219 offset:17408
	ds_read_b128 v[170:173], v219 offset:18432
	ds_read_b128 v[174:177], v219 offset:19456
	ds_read_b128 v[178:181], v219 offset:20480
	ds_read_b128 v[182:185], v219 offset:21504
	ds_read_b128 v[186:189], v219 offset:22528
	ds_read_b128 v[212:215], v219 offset:23552
	global_load_lds_dwordx4 v[220:221], off
	s_add_i32 m0, s50, 0x2000
	s_add_u32 s50, s22, 0x40000
	v_lshl_add_u64 v[222:223], s[22:23], 0, v[202:203]
	s_addc_u32 s51, s23, 0
	s_add_i32 s52, s52, s26
	global_load_lds_dwordx4 v[222:223], off
	v_lshl_add_u64 v[224:225], s[50:51], 0, v[64:65]
	s_mov_b32 m0, s52
	v_lshl_add_u64 v[226:227], s[24:25], 0, v[204:205]
	global_load_lds_dwordx4 v[224:225], off
	v_lshl_add_u64 v[224:225], s[50:51], 0, v[202:203]
	s_add_i32 m0, s52, 0x2000
	s_nop 0
	global_load_lds_dwordx4 v[224:225], off
	v_lshl_add_u64 v[224:225], s[24:25], 0, v[206:207]
	s_mov_b32 m0, s29
	s_nop 0
	global_load_lds_dwordx4 v[224:225], off
	s_mov_b32 m0, s30
	s_nop 0
	global_load_lds_dwordx4 v[226:227], off
	s_waitcnt vmcnt(8)
	s_waitcnt lgkmcnt(0)
	s_barrier
; #define PG8_STAGE(bufoff, gbase, voff) do { _Pragma("unroll") for (int _i = 0; _i < 2; ++_i) \
;         __builtin_amdgcn_global_load_lds((const unsigned*)((const char*)(gbase) + (voff)[_i]), (PG8_LAS unsigned*)(lds + (bufoff) + ldsw + _i * 8192), 16, 0, 0); } while (0)
; #define PG8_LDA(dst, b, h) do { _Pragma("unroll") for (int m = 0; m < 4; ++m) _Pragma("unroll") for (int k = 0; k < 2; ++k) dst[m][k] = *(const PG8_LAS bf16x8*)(lds + PG8_SA(b, h) + aoff + m * 2048 + k * 1024); } while (0)
; #define PG8_LDB(dst, b, h) do { _Pragma("unroll") for (int n = 0; n < 2; ++n) _Pragma("unroll") for (int k = 0; k < 2; ++k) dst[n][k] = *(const PG8_LAS bf16x8*)(lds + PG8_SB(b, h) + boff + n * 2048 + k * 1024); } while (0)
; #define PG8_MMA(ai, bj, At, Bt) do { __builtin_amdgcn_s_setprio(1); _Pragma("unroll") for (int m = 0; m < 4; ++m) _Pragma("unroll") for (int n = 0; n < 2; ++n) _Pragma("unroll") for (int k = 0; k < 2; ++k) \
;         acc[ai][bj][m][n] = __builtin_amdgcn_mfma_f32_16x16x32_bf16(Bt[n][k], At[m][k], acc[ai][bj][m][n], 0, 0, 0); __builtin_amdgcn_s_setprio(0); } while (0)
; #define PG8_WAIT_V(n) asm volatile("s_waitcnt vmcnt(" #n ")" ::: "memory")
; #define PG8_WAIT_L(n) asm volatile("s_waitcnt lgkmcnt(" #n ")" ::: "memory")
; #define PG8_BAR __builtin_amdgcn_s_barrier()
; #define PG8_SCHED __builtin_amdgcn_sched_barrier(0)
; template <class Epi, class Sched, bool ALIGN_EPI = false, bool SP2 = false>
; __device__ __forceinline__ void gemm_phase(PG8_LAS unsigned char* lds, const Gemm g, const Sched& S, const Epi& E) {
;     ...
;             PG8_WAIT_V(8); PG8_WAIT_L(0); PG8_BAR; PG8_MMA(1, 0, At, B0); PG8_MMA(1, 1, At, B1); PG8_BAR; PG8_SCHED;
;             PG8_LDB(B0, 1, 0); PG8_LDB(B1, 1, 1); PG8_SCHED; PG8_LDA(At, 1, 0); PG8_STAGE(PG8_SA(0, 1), a2 + hstepA, voffA);
;             PG8_WAIT_V(8); PG8_WAIT_L(0); PG8_BAR; PG8_MMA(0, 0, At, B0); PG8_MMA(0, 1, At, B1); PG8_BAR; PG8_SCHED;
	s_setprio 1
	v_mfma_f32_16x16x32_bf16 v[60:63], v[130:133], v[162:165], v[60:63]
	v_mfma_f32_16x16x32_bf16 v[56:59], v[138:141], v[162:165], v[56:59]
	v_mfma_f32_16x16x32_bf16 v[44:47], v[130:133], v[170:173], v[44:47]
	v_mfma_f32_16x16x32_bf16 v[40:43], v[138:141], v[170:173], v[40:43]
	v_mfma_f32_16x16x32_bf16 v[28:31], v[130:133], v[178:181], v[28:31]
	v_mfma_f32_16x16x32_bf16 v[24:27], v[138:141], v[178:181], v[24:27]
	v_mfma_f32_16x16x32_bf16 v[12:15], v[130:133], v[186:189], v[12:15]
	v_mfma_f32_16x16x32_bf16 v[8:11], v[138:141], v[186:189], v[8:11]
	v_mfma_f32_16x16x32_bf16 v[60:63], v[134:137], v[166:169], v[60:63]
	v_mfma_f32_16x16x32_bf16 v[56:59], v[142:145], v[166:169], v[56:59]
	v_mfma_f32_16x16x32_bf16 v[44:47], v[134:137], v[174:177], v[44:47]
	v_mfma_f32_16x16x32_bf16 v[40:43], v[142:145], v[174:177], v[40:43]
	v_mfma_f32_16x16x32_bf16 v[28:31], v[134:137], v[182:185], v[28:31]
	v_mfma_f32_16x16x32_bf16 v[24:27], v[142:145], v[182:185], v[24:27]
	v_mfma_f32_16x16x32_bf16 v[12:15], v[134:137], v[212:215], v[12:15]
	v_mfma_f32_16x16x32_bf16 v[8:11], v[142:145], v[212:215], v[8:11]
	s_setprio 0
	s_setprio 1
	v_mfma_f32_16x16x32_bf16 v[52:55], v[146:149], v[162:165], v[52:55]
	v_mfma_f32_16x16x32_bf16 v[48:51], v[154:157], v[162:165], v[48:51]
	v_mfma_f32_16x16x32_bf16 v[36:39], v[146:149], v[170:173], v[36:39]
	v_mfma_f32_16x16x32_bf16 v[32:35], v[154:157], v[170:173], v[32:35]
	v_mfma_f32_16x16x32_bf16 v[20:23], v[146:149], v[178:181], v[20:23]
	v_mfma_f32_16x16x32_bf16 v[16:19], v[154:157], v[178:181], v[16:19]
	v_mfma_f32_16x16x32_bf16 v[4:7], v[146:149], v[186:189], v[4:7]
	v_mfma_f32_16x16x32_bf16 v[0:3], v[154:157], v[186:189], v[0:3]
	v_mfma_f32_16x16x32_bf16 v[52:55], v[150:153], v[166:169], v[52:55]
	v_mfma_f32_16x16x32_bf16 v[48:51], v[158:161], v[166:169], v[48:51]
	v_mfma_f32_16x16x32_bf16 v[36:39], v[150:153], v[174:177], v[36:39]
	v_mfma_f32_16x16x32_bf16 v[32:35], v[158:161], v[174:177], v[32:35]
	v_mfma_f32_16x16x32_bf16 v[20:23], v[150:153], v[182:185], v[20:23]
	v_mfma_f32_16x16x32_bf16 v[16:19], v[158:161], v[182:185], v[16:19]
	v_mfma_f32_16x16x32_bf16 v[4:7], v[150:153], v[212:215], v[4:7]
	v_mfma_f32_16x16x32_bf16 v[0:3], v[158:161], v[212:215], v[0:3]
	s_setprio 0
	s_barrier
	s_add_i32 s50, 0, 0x18000
	s_add_i32 s51, 0, 0x1c000
	v_add_u32_e32 v142, s50, v218
	v_add_u32_e32 v158, s51, v218
	ds_read_b128 v[130:133], v142
	ds_read_b128 v[134:137], v142 offset:1024
	ds_read_b128 v[138:141], v142 offset:2048
	ds_read_b128 v[142:145], v142 offset:3072
	ds_read_b128 v[146:149], v158
	ds_read_b128 v[150:153], v158 offset:1024
	ds_read_b128 v[154:157], v158 offset:2048
	ds_read_b128 v[158:161], v158 offset:3072
	s_add_u32 s24, s24, 0x40000
	s_addc_u32 s25, s25, 0
	s_mov_b32 m0, s31
	v_lshl_add_u64 v[234:235], s[24:25], 0, v[206:207]
	ds_read_b128 v[162:165], v219 offset:32768
	ds_read_b128 v[166:169], v219 offset:33792
	ds_read_b128 v[170:173], v219 offset:34816
	ds_read_b128 v[174:177], v219 offset:35840
	ds_read_b128 v[178:181], v219 offset:36864
	ds_read_b128 v[182:185], v219 offset:37888
	ds_read_b128 v[186:189], v219 offset:38912
	ds_read_b128 v[212:215], v219 offset:39936
	global_load_lds_dwordx4 v[234:235], off
	v_lshl_add_u64 v[234:235], s[24:25], 0, v[204:205]
	s_mov_b32 m0, s34
	s_nop 0
	global_load_lds_dwordx4 v[234:235], off
	s_waitcnt vmcnt(8)
	s_waitcnt lgkmcnt(0)
	s_barrier
	s_setprio 1
	v_mfma_f32_16x16x32_bf16 v[122:125], v[130:133], v[162:165], v[122:125]
	v_mfma_f32_16x16x32_bf16 v[126:129], v[138:141], v[162:165], v[126:129]
	v_mfma_f32_16x16x32_bf16 v[110:113], v[130:133], v[170:173], v[110:113]
	v_mfma_f32_16x16x32_bf16 v[106:109], v[138:141], v[170:173], v[106:109]
	v_mfma_f32_16x16x32_bf16 v[94:97], v[130:133], v[178:181], v[94:97]
	v_mfma_f32_16x16x32_bf16 v[90:93], v[138:141], v[178:181], v[90:93]
	v_mfma_f32_16x16x32_bf16 v[78:81], v[130:133], v[186:189], v[78:81]
	v_mfma_f32_16x16x32_bf16 v[74:77], v[138:141], v[186:189], v[74:77]
	v_mfma_f32_16x16x32_bf16 v[122:125], v[134:137], v[166:169], v[122:125]
	v_mfma_f32_16x16x32_bf16 v[126:129], v[142:145], v[166:169], v[126:129]
	v_mfma_f32_16x16x32_bf16 v[110:113], v[134:137], v[174:177], v[110:113]
	v_mfma_f32_16x16x32_bf16 v[106:109], v[142:145], v[174:177], v[106:109]
	v_mfma_f32_16x16x32_bf16 v[94:97], v[134:137], v[182:185], v[94:97]
	v_mfma_f32_16x16x32_bf16 v[90:93], v[142:145], v[182:185], v[90:93]
	v_mfma_f32_16x16x32_bf16 v[78:81], v[134:137], v[212:215], v[78:81]
	v_mfma_f32_16x16x32_bf16 v[74:77], v[142:145], v[212:215], v[74:77]
	s_setprio 0
	s_setprio 1
	v_mfma_f32_16x16x32_bf16 v[118:121], v[146:149], v[162:165], v[118:121]
	v_mfma_f32_16x16x32_bf16 v[114:117], v[154:157], v[162:165], v[114:117]
	v_mfma_f32_16x16x32_bf16 v[102:105], v[146:149], v[170:173], v[102:105]
	v_mfma_f32_16x16x32_bf16 v[98:101], v[154:157], v[170:173], v[98:101]
	v_mfma_f32_16x16x32_bf16 v[86:89], v[146:149], v[178:181], v[86:89]
	v_mfma_f32_16x16x32_bf16 v[82:85], v[154:157], v[178:181], v[82:85]
	v_mfma_f32_16x16x32_bf16 v[70:73], v[146:149], v[186:189], v[70:73]
	v_mfma_f32_16x16x32_bf16 v[66:69], v[154:157], v[186:189], v[66:69]
	v_mfma_f32_16x16x32_bf16 v[118:121], v[150:153], v[166:169], v[118:121]
	v_mfma_f32_16x16x32_bf16 v[114:117], v[158:161], v[166:169], v[114:117]
	v_mfma_f32_16x16x32_bf16 v[102:105], v[150:153], v[174:177], v[102:105]
	v_mfma_f32_16x16x32_bf16 v[98:101], v[158:161], v[174:177], v[98:101]
	v_mfma_f32_16x16x32_bf16 v[86:89], v[150:153], v[182:185], v[86:89]
	v_mfma_f32_16x16x32_bf16 v[82:85], v[158:161], v[182:185], v[82:85]
	v_mfma_f32_16x16x32_bf16 v[70:73], v[150:153], v[212:215], v[70:73]
	v_mfma_f32_16x16x32_bf16 v[66:69], v[158:161], v[212:215], v[66:69]
	s_setprio 0
	s_barrier
; #define PG8_STAGE(bufoff, gbase, voff) do { _Pragma("unroll") for (int _i = 0; _i < 2; ++_i) \
;         __builtin_amdgcn_global_load_lds((const unsigned*)((const char*)(gbase) + (voff)[_i]), (PG8_LAS unsigned*)(lds + (bufoff) + ldsw + _i * 8192), 16, 0, 0); } while (0)
; #define PG8_LDA(dst, b, h) do { _Pragma("unroll") for (int m = 0; m < 4; ++m) _Pragma("unroll") for (int k = 0; k < 2; ++k) dst[m][k] = *(const PG8_LAS bf16x8*)(lds + PG8_SA(b, h) + aoff + m * 2048 + k * 1024); } while (0)
; #define PG8_MMA(ai, bj, At, Bt) do { __builtin_amdgcn_s_setprio(1); _Pragma("unroll") for (int m = 0; m < 4; ++m) _Pragma("unroll") for (int n = 0; n < 2; ++n) _Pragma("unroll") for (int k = 0; k < 2; ++k) \
;         acc[ai][bj][m][n] = __builtin_amdgcn_mfma_f32_16x16x32_bf16(Bt[n][k], At[m][k], acc[ai][bj][m][n], 0, 0, 0); __builtin_amdgcn_s_setprio(0); } while (0)
; #define PG8_WAIT_V(n) asm volatile("s_waitcnt vmcnt(" #n ")" ::: "memory")
; #define PG8_WAIT_L(n) asm volatile("s_waitcnt lgkmcnt(" #n ")" ::: "memory")
; #define PG8_BAR __builtin_amdgcn_s_barrier()
; #define PG8_SCHED __builtin_amdgcn_sched_barrier(0)
; template <class Epi, class Sched, bool ALIGN_EPI = false, bool SP2 = false>
; __device__ __forceinline__ void gemm_phase(PG8_LAS unsigned char* lds, const Gemm g, const Sched& S, const Epi& E) {
;     ...
;         for (int t = 0; t < ntc; t += 2) {
;     ...
;             PG8_LDA(At, 1, 1); PG8_STAGE(PG8_SB(1, 0), b3, voffB); PG8_STAGE(PG8_SB(1, 1), b3 + hstepB, voffB); PG8_STAGE(PG8_SA(1, 0), a3, voffA);
;             PG8_WAIT_V(8); PG8_WAIT_L(0); PG8_BAR; PG8_MMA(1, 0, At, B0); PG8_MMA(1, 1, At, B1); PG8_BAR; PG8_SCHED;
	s_add_i32 s24, s50, s26
	v_lshl_add_u64 v[220:221], v[220:221], 0, s[88:89]
	s_mov_b32 m0, s24
	ds_read_b128 v[162:165], v219 offset:49152
	ds_read_b128 v[166:169], v219 offset:50176
	ds_read_b128 v[170:173], v219 offset:51200
	ds_read_b128 v[174:177], v219 offset:52224
	ds_read_b128 v[178:181], v219 offset:53248
	ds_read_b128 v[182:185], v219 offset:54272
	ds_read_b128 v[186:189], v219 offset:55296
	ds_read_b128 v[212:215], v219 offset:56320
	global_load_lds_dwordx4 v[220:221], off
	s_add_i32 m0, s24, 0x2000
	s_add_u32 s22, s22, 0x40080
	v_lshl_add_u64 v[220:221], v[222:223], 0, s[88:89]
	s_addc_u32 s23, s23, 0
	s_add_i32 s24, s51, s26
	global_load_lds_dwordx4 v[220:221], off
	v_lshl_add_u64 v[220:221], s[22:23], 0, v[64:65]
	s_mov_b32 m0, s24
	s_nop 0
	global_load_lds_dwordx4 v[220:221], off
	v_lshl_add_u64 v[220:221], s[22:23], 0, v[202:203]
	s_add_i32 m0, s24, 0x2000
	s_nop 0
	global_load_lds_dwordx4 v[220:221], off
	v_lshl_add_u64 v[220:221], v[224:225], 0, s[88:89]
	s_mov_b32 m0, s38
	s_nop 0
	global_load_lds_dwordx4 v[220:221], off
	v_lshl_add_u64 v[220:221], v[226:227], 0, s[88:89]
	s_mov_b32 m0, s39
	s_nop 0
	global_load_lds_dwordx4 v[220:221], off
	s_waitcnt vmcnt(8)
	s_waitcnt lgkmcnt(0)
	s_barrier
	s_setprio 1
	v_mfma_f32_16x16x32_bf16 v[60:63], v[130:133], v[162:165], v[60:63]
	v_mfma_f32_16x16x32_bf16 v[56:59], v[138:141], v[162:165], v[56:59]
	v_mfma_f32_16x16x32_bf16 v[44:47], v[130:133], v[170:173], v[44:47]
	v_mfma_f32_16x16x32_bf16 v[40:43], v[138:141], v[170:173], v[40:43]
	v_mfma_f32_16x16x32_bf16 v[28:31], v[130:133], v[178:181], v[28:31]
	v_mfma_f32_16x16x32_bf16 v[24:27], v[138:141], v[178:181], v[24:27]
	v_mfma_f32_16x16x32_bf16 v[12:15], v[130:133], v[186:189], v[12:15]
	v_mfma_f32_16x16x32_bf16 v[8:11], v[138:141], v[186:189], v[8:11]
	v_mfma_f32_16x16x32_bf16 v[60:63], v[134:137], v[166:169], v[60:63]
	v_mfma_f32_16x16x32_bf16 v[56:59], v[142:145], v[166:169], v[56:59]
	v_mfma_f32_16x16x32_bf16 v[44:47], v[134:137], v[174:177], v[44:47]
	v_mfma_f32_16x16x32_bf16 v[40:43], v[142:145], v[174:177], v[40:43]
	v_mfma_f32_16x16x32_bf16 v[28:31], v[134:137], v[182:185], v[28:31]
	v_mfma_f32_16x16x32_bf16 v[24:27], v[142:145], v[182:185], v[24:27]
	v_mfma_f32_16x16x32_bf16 v[12:15], v[134:137], v[212:215], v[12:15]
	v_mfma_f32_16x16x32_bf16 v[8:11], v[142:145], v[212:215], v[8:11]
	s_setprio 0
	s_setprio 1
	v_mfma_f32_16x16x32_bf16 v[52:55], v[146:149], v[162:165], v[52:55]
	v_mfma_f32_16x16x32_bf16 v[48:51], v[154:157], v[162:165], v[48:51]
	v_mfma_f32_16x16x32_bf16 v[36:39], v[146:149], v[170:173], v[36:39]
	v_mfma_f32_16x16x32_bf16 v[32:35], v[154:157], v[170:173], v[32:35]
	v_mfma_f32_16x16x32_bf16 v[20:23], v[146:149], v[178:181], v[20:23]
	v_mfma_f32_16x16x32_bf16 v[16:19], v[154:157], v[178:181], v[16:19]
	v_mfma_f32_16x16x32_bf16 v[4:7], v[146:149], v[186:189], v[4:7]
	v_mfma_f32_16x16x32_bf16 v[0:3], v[154:157], v[186:189], v[0:3]
	v_mfma_f32_16x16x32_bf16 v[52:55], v[150:153], v[166:169], v[52:55]
	v_mfma_f32_16x16x32_bf16 v[48:51], v[158:161], v[166:169], v[48:51]
	v_mfma_f32_16x16x32_bf16 v[36:39], v[150:153], v[174:177], v[36:39]
	v_mfma_f32_16x16x32_bf16 v[32:35], v[158:161], v[174:177], v[32:35]
	v_mfma_f32_16x16x32_bf16 v[20:23], v[150:153], v[182:185], v[20:23]
	v_mfma_f32_16x16x32_bf16 v[16:19], v[158:161], v[182:185], v[16:19]
	v_mfma_f32_16x16x32_bf16 v[4:7], v[150:153], v[212:215], v[4:7]
	v_mfma_f32_16x16x32_bf16 v[0:3], v[158:161], v[212:215], v[0:3]
	s_setprio 0
	s_barrier
	s_add_u32 s4, s4, 0x100
	s_addc_u32 s5, s5, 0
	s_add_u32 s47, s47, 0x100
	s_addc_u32 s48, s48, 0
	s_cmp_ge_i32 s49, s36
	s_mov_b32 s22, s49
	s_cbranch_scc0 .LBB0_654

; #define PG8_STAGE(bufoff, gbase, voff) do { _Pragma("unroll") for (int _i = 0; _i < 2; ++_i) \
;         __builtin_amdgcn_global_load_lds((const unsigned*)((const char*)(gbase) + (voff)[_i]), (PG8_LAS unsigned*)(lds + (bufoff) + ldsw + _i * 8192), 16, 0, 0); } while (0)
; #define PG8_LDA(dst, b, h) do { _Pragma("unroll") for (int m = 0; m < 4; ++m) _Pragma("unroll") for (int k = 0; k < 2; ++k) dst[m][k] = *(const PG8_LAS bf16x8*)(lds + PG8_SA(b, h) + aoff + m * 2048 + k * 1024); } while (0)
; #define PG8_LDB(dst, b, h) do { _Pragma("unroll") for (int n = 0; n < 2; ++n) _Pragma("unroll") for (int k = 0; k < 2; ++k) dst[n][k] = *(const PG8_LAS bf16x8*)(lds + PG8_SB(b, h) + boff + n * 2048 + k * 1024); } while (0)
; #define PG8_MMA(ai, bj, At, Bt) do { __builtin_amdgcn_s_setprio(1); _Pragma("unroll") for (int m = 0; m < 4; ++m) _Pragma("unroll") for (int n = 0; n < 2; ++n) _Pragma("unroll") for (int k = 0; k < 2; ++k) \
;         acc[ai][bj][m][n] = __builtin_amdgcn_mfma_f32_16x16x32_bf16(Bt[n][k], At[m][k], acc[ai][bj][m][n], 0, 0, 0); __builtin_amdgcn_s_setprio(0); } while (0)
; #define PG8_WAIT_V(n) asm volatile("s_waitcnt vmcnt(" #n ")" ::: "memory")
; #define PG8_WAIT_L(n) asm volatile("s_waitcnt lgkmcnt(" #n ")" ::: "memory")
; #define PG8_BAR __builtin_amdgcn_s_barrier()
; #define PG8_SCHED __builtin_amdgcn_sched_barrier(0)
; template <class Epi, class Sched, bool ALIGN_EPI = false, bool SP2 = false>
; __device__ __forceinline__ void gemm_phase(PG8_LAS unsigned char* lds, const Gemm g, const Sched& S, const Epi& E) {
;     ...
;         for (int t = 0; t < ntc; t += 2) {
;             const bool last = (t == ntc - 2);
;             const char* a1 = cA + (size_t)(t + 1) * kstep;
;             const char* a2 = last ? nA : cA + (size_t)(t + 2) * kstep; const char* b2 = last ? nB : cB + (size_t)(t + 2) * kstep;
;             const char* a3 = a2 + kstep; const char* b3 = b2 + kstep;
;             if (last && has_next) S.a_ready(nxt);
;             if constexpr (SP2) {
;             PG8_LDB(B0, 0, 0); PG8_LDB(B1, 0, 1); PG8_SCHED; PG8_LDA(At, 0, 0); PG8_STAGE(PG8_SA(1, 1), a1 + hstepA, voffA);
;             PG8_WAIT_V(8); PG8_WAIT_L(0); PG8_BAR; PG8_MMA(0, 0, At, B0); PG8_MMA(0, 1, At, B1); PG8_BAR; PG8_SCHED;
;             PG8_LDA(At, 0, 1); PG8_STAGE(PG8_SB(0, 0), b2, voffB); PG8_STAGE(PG8_SB(0, 1), b2 + hstepB, voffB); PG8_STAGE(PG8_SA(0, 0), a2, voffA);
.LBB0_746:
	s_add_i32 s31, s8, 2
	s_add_u32 s9, s4, 0xfffc0080
	s_addc_u32 s10, s5, -1
	s_add_i32 s34, 0, 0x10000
	s_cmp_eq_u32 s47, s8
	s_cselect_b32 s11, s19, s10
	s_cselect_b32 s10, s21, s9
	s_cselect_b32 s9, s27, s30
	s_cselect_b32 s8, s28, s29
	s_add_i32 s50, 0, 0x14000
	v_add_u32_e32 v102, s34, v177
	v_add_u32_e32 v126, s50, v177
	ds_read_b128 v[90:93], v102
	ds_read_b128 v[94:97], v102 offset:1024
	ds_read_b128 v[98:101], v102 offset:2048
	ds_read_b128 v[102:105], v102 offset:3072
	ds_read_b128 v[106:109], v126
	ds_read_b128 v[114:117], v126 offset:1024
	ds_read_b128 v[118:121], v126 offset:2048
	ds_read_b128 v[126:129], v126 offset:3072
	v_lshl_add_u64 v[226:227], s[4:5], 0, v[168:169]
	s_add_i32 m0, s38, 0xc000
	ds_read_b128 v[186:189], v179
	ds_read_b128 v[202:205], v179 offset:1024
	ds_read_b128 v[206:209], v179 offset:2048
	ds_read_b128 v[210:213], v179 offset:3072
	ds_read_b128 v[214:217], v179 offset:4096
	ds_read_b128 v[218:221], v179 offset:5120
	ds_read_b128 v[222:225], v179 offset:6144
	ds_read_b128 v[240:243], v179 offset:7168
	global_load_lds_dwordx4 v[226:227], off
	v_lshl_add_u64 v[226:227], s[4:5], 0, v[170:171]
	s_add_i32 m0, s38, 0xe000
	s_nop 0
	global_load_lds_dwordx4 v[226:227], off
	s_waitcnt vmcnt(8)
	s_waitcnt lgkmcnt(0)
	s_barrier
	s_setprio 1
	v_mfma_f32_16x16x32_bf16 v[158:161], v[90:93], v[186:189], v[158:161]
	v_mfma_f32_16x16x32_bf16 v[154:157], v[98:101], v[186:189], v[154:157]
	v_mfma_f32_16x16x32_bf16 v[142:145], v[90:93], v[206:209], v[142:145]
	v_mfma_f32_16x16x32_bf16 v[138:141], v[98:101], v[206:209], v[138:141]
	v_mfma_f32_16x16x32_bf16 v[122:125], v[90:93], v[214:217], v[122:125]
	v_mfma_f32_16x16x32_bf16 v[110:113], v[98:101], v[214:217], v[110:113]
	v_mfma_f32_16x16x32_bf16 v[78:81], v[90:93], v[222:225], v[78:81]
	v_mfma_f32_16x16x32_bf16 v[74:77], v[98:101], v[222:225], v[74:77]
	v_mfma_f32_16x16x32_bf16 v[158:161], v[94:97], v[202:205], v[158:161]
	v_mfma_f32_16x16x32_bf16 v[154:157], v[102:105], v[202:205], v[154:157]
	v_mfma_f32_16x16x32_bf16 v[142:145], v[94:97], v[210:213], v[142:145]
	v_mfma_f32_16x16x32_bf16 v[138:141], v[102:105], v[210:213], v[138:141]
	v_mfma_f32_16x16x32_bf16 v[122:125], v[94:97], v[218:221], v[122:125]
	v_mfma_f32_16x16x32_bf16 v[110:113], v[102:105], v[218:221], v[110:113]
	v_mfma_f32_16x16x32_bf16 v[78:81], v[94:97], v[240:243], v[78:81]
	v_mfma_f32_16x16x32_bf16 v[74:77], v[102:105], v[240:243], v[74:77]
	s_setprio 0
	s_setprio 1
	v_mfma_f32_16x16x32_bf16 v[150:153], v[106:109], v[186:189], v[150:153]
	v_mfma_f32_16x16x32_bf16 v[146:149], v[118:121], v[186:189], v[146:149]
	v_mfma_f32_16x16x32_bf16 v[134:137], v[106:109], v[206:209], v[134:137]
	v_mfma_f32_16x16x32_bf16 v[130:133], v[118:121], v[206:209], v[130:133]
	v_mfma_f32_16x16x32_bf16 v[86:89], v[106:109], v[214:217], v[86:89]
	v_mfma_f32_16x16x32_bf16 v[82:85], v[118:121], v[214:217], v[82:85]
	v_mfma_f32_16x16x32_bf16 v[70:73], v[106:109], v[222:225], v[70:73]
	v_mfma_f32_16x16x32_bf16 v[66:69], v[118:121], v[222:225], v[66:69]
	v_mfma_f32_16x16x32_bf16 v[150:153], v[114:117], v[202:205], v[150:153]
	v_mfma_f32_16x16x32_bf16 v[146:149], v[126:129], v[202:205], v[146:149]
	v_mfma_f32_16x16x32_bf16 v[134:137], v[114:117], v[210:213], v[134:137]
	v_mfma_f32_16x16x32_bf16 v[130:133], v[126:129], v[210:213], v[130:133]
	v_mfma_f32_16x16x32_bf16 v[86:89], v[114:117], v[218:221], v[86:89]
	v_mfma_f32_16x16x32_bf16 v[82:85], v[126:129], v[218:221], v[82:85]
	v_mfma_f32_16x16x32_bf16 v[70:73], v[114:117], v[240:243], v[70:73]
	v_mfma_f32_16x16x32_bf16 v[66:69], v[126:129], v[240:243], v[66:69]
	s_setprio 0
	s_barrier
	s_add_i32 s34, s34, s36
	v_lshl_add_u64 v[226:227], s[8:9], 0, v[64:65]
	s_mov_b32 m0, s34
	ds_read_b128 v[186:189], v179 offset:16384
	ds_read_b128 v[202:205], v179 offset:17408
	ds_read_b128 v[206:209], v179 offset:18432
	ds_read_b128 v[210:213], v179 offset:19456
	ds_read_b128 v[214:217], v179 offset:20480
	ds_read_b128 v[218:221], v179 offset:21504
	ds_read_b128 v[222:225], v179 offset:22528
	ds_read_b128 v[240:243], v179 offset:23552
	global_load_lds_dwordx4 v[226:227], off
	s_add_i32 m0, s34, 0x2000
	s_add_u32 s34, s8, 0x40000
	v_lshl_add_u64 v[244:245], s[8:9], 0, v[162:163]
	s_addc_u32 s35, s9, 0
	s_add_i32 s50, s50, s36
	global_load_lds_dwordx4 v[244:245], off
	v_lshl_add_u64 v[246:247], s[34:35], 0, v[64:65]
	s_mov_b32 m0, s50
	v_lshl_add_u64 v[248:249], s[10:11], 0, v[164:165]
	global_load_lds_dwordx4 v[246:247], off
	v_lshl_add_u64 v[246:247], s[34:35], 0, v[162:163]
	s_add_i32 m0, s50, 0x2000
	s_nop 0
	global_load_lds_dwordx4 v[246:247], off
	v_lshl_add_u64 v[246:247], s[10:11], 0, v[166:167]
	s_mov_b32 m0, s38
	s_nop 0
	global_load_lds_dwordx4 v[246:247], off
	s_mov_b32 m0, s39
	s_nop 0
	global_load_lds_dwordx4 v[248:249], off
	s_waitcnt vmcnt(8)
	s_waitcnt lgkmcnt(0)
	s_barrier
; #define PG8_STAGE(bufoff, gbase, voff) do { _Pragma("unroll") for (int _i = 0; _i < 2; ++_i) \
;         __builtin_amdgcn_global_load_lds((const unsigned*)((const char*)(gbase) + (voff)[_i]), (PG8_LAS unsigned*)(lds + (bufoff) + ldsw + _i * 8192), 16, 0, 0); } while (0)
; #define PG8_LDA(dst, b, h) do { _Pragma("unroll") for (int m = 0; m < 4; ++m) _Pragma("unroll") for (int k = 0; k < 2; ++k) dst[m][k] = *(const PG8_LAS bf16x8*)(lds + PG8_SA(b, h) + aoff + m * 2048 + k * 1024); } while (0)
; #define PG8_LDB(dst, b, h) do { _Pragma("unroll") for (int n = 0; n < 2; ++n) _Pragma("unroll") for (int k = 0; k < 2; ++k) dst[n][k] = *(const PG8_LAS bf16x8*)(lds + PG8_SB(b, h) + boff + n * 2048 + k * 1024); } while (0)
; #define PG8_MMA(ai, bj, At, Bt) do { __builtin_amdgcn_s_setprio(1); _Pragma("unroll") for (int m = 0; m < 4; ++m) _Pragma("unroll") for (int n = 0; n < 2; ++n) _Pragma("unroll") for (int k = 0; k < 2; ++k) \
;         acc[ai][bj][m][n] = __builtin_amdgcn_mfma_f32_16x16x32_bf16(Bt[n][k], At[m][k], acc[ai][bj][m][n], 0, 0, 0); __builtin_amdgcn_s_setprio(0); } while (0)
; #define PG8_WAIT_V(n) asm volatile("s_waitcnt vmcnt(" #n ")" ::: "memory")
; #define PG8_WAIT_L(n) asm volatile("s_waitcnt lgkmcnt(" #n ")" ::: "memory")
; #define PG8_BAR __builtin_amdgcn_s_barrier()
; #define PG8_SCHED __builtin_amdgcn_sched_barrier(0)
; template <class Epi, class Sched, bool ALIGN_EPI = false, bool SP2 = false>
; __device__ __forceinline__ void gemm_phase(PG8_LAS unsigned char* lds, const Gemm g, const Sched& S, const Epi& E) {
;     ...
;             PG8_WAIT_V(8); PG8_WAIT_L(0); PG8_BAR; PG8_MMA(1, 0, At, B0); PG8_MMA(1, 1, At, B1); PG8_BAR; PG8_SCHED;
;             PG8_LDB(B0, 1, 0); PG8_LDB(B1, 1, 1); PG8_SCHED; PG8_LDA(At, 1, 0); PG8_STAGE(PG8_SA(0, 1), a2 + hstepA, voffA);
;             PG8_WAIT_V(8); PG8_WAIT_L(0); PG8_BAR; PG8_MMA(0, 0, At, B0); PG8_MMA(0, 1, At, B1); PG8_BAR; PG8_SCHED;
	s_setprio 1
	v_mfma_f32_16x16x32_bf16 v[60:63], v[90:93], v[186:189], v[60:63]
	v_mfma_f32_16x16x32_bf16 v[56:59], v[98:101], v[186:189], v[56:59]
	v_mfma_f32_16x16x32_bf16 v[44:47], v[90:93], v[206:209], v[44:47]
	v_mfma_f32_16x16x32_bf16 v[40:43], v[98:101], v[206:209], v[40:43]
	v_mfma_f32_16x16x32_bf16 v[28:31], v[90:93], v[214:217], v[28:31]
	v_mfma_f32_16x16x32_bf16 v[24:27], v[98:101], v[214:217], v[24:27]
	v_mfma_f32_16x16x32_bf16 v[12:15], v[90:93], v[222:225], v[12:15]
	v_mfma_f32_16x16x32_bf16 v[8:11], v[98:101], v[222:225], v[8:11]
	v_mfma_f32_16x16x32_bf16 v[60:63], v[94:97], v[202:205], v[60:63]
	v_mfma_f32_16x16x32_bf16 v[56:59], v[102:105], v[202:205], v[56:59]
	v_mfma_f32_16x16x32_bf16 v[44:47], v[94:97], v[210:213], v[44:47]
	v_mfma_f32_16x16x32_bf16 v[40:43], v[102:105], v[210:213], v[40:43]
	v_mfma_f32_16x16x32_bf16 v[28:31], v[94:97], v[218:221], v[28:31]
	v_mfma_f32_16x16x32_bf16 v[24:27], v[102:105], v[218:221], v[24:27]
	v_mfma_f32_16x16x32_bf16 v[12:15], v[94:97], v[240:243], v[12:15]
	v_mfma_f32_16x16x32_bf16 v[8:11], v[102:105], v[240:243], v[8:11]
	s_setprio 0
	s_setprio 1
	v_mfma_f32_16x16x32_bf16 v[52:55], v[106:109], v[186:189], v[52:55]
	v_mfma_f32_16x16x32_bf16 v[48:51], v[118:121], v[186:189], v[48:51]
	v_mfma_f32_16x16x32_bf16 v[36:39], v[106:109], v[206:209], v[36:39]
	v_mfma_f32_16x16x32_bf16 v[32:35], v[118:121], v[206:209], v[32:35]
	v_mfma_f32_16x16x32_bf16 v[20:23], v[106:109], v[214:217], v[20:23]
	v_mfma_f32_16x16x32_bf16 v[16:19], v[118:121], v[214:217], v[16:19]
	v_mfma_f32_16x16x32_bf16 v[4:7], v[106:109], v[222:225], v[4:7]
	v_mfma_f32_16x16x32_bf16 v[0:3], v[118:121], v[222:225], v[0:3]
	v_mfma_f32_16x16x32_bf16 v[52:55], v[114:117], v[202:205], v[52:55]
	v_mfma_f32_16x16x32_bf16 v[48:51], v[126:129], v[202:205], v[48:51]
	v_mfma_f32_16x16x32_bf16 v[36:39], v[114:117], v[210:213], v[36:39]
	v_mfma_f32_16x16x32_bf16 v[32:35], v[126:129], v[210:213], v[32:35]
	v_mfma_f32_16x16x32_bf16 v[20:23], v[114:117], v[218:221], v[20:23]
	v_mfma_f32_16x16x32_bf16 v[16:19], v[126:129], v[218:221], v[16:19]
	v_mfma_f32_16x16x32_bf16 v[4:7], v[114:117], v[240:243], v[4:7]
	v_mfma_f32_16x16x32_bf16 v[0:3], v[126:129], v[240:243], v[0:3]
	s_setprio 0
	s_barrier
	s_add_i32 s34, 0, 0x18000
	s_add_i32 s35, 0, 0x1c000
	v_add_u32_e32 v102, s34, v177
	v_add_u32_e32 v126, s35, v177
	ds_read_b128 v[90:93], v102
	ds_read_b128 v[94:97], v102 offset:1024
	ds_read_b128 v[98:101], v102 offset:2048
	ds_read_b128 v[102:105], v102 offset:3072
	ds_read_b128 v[106:109], v126
	ds_read_b128 v[114:117], v126 offset:1024
	ds_read_b128 v[118:121], v126 offset:2048
	ds_read_b128 v[126:129], v126 offset:3072
	s_add_u32 s10, s10, 0x40000
	s_addc_u32 s11, s11, 0
	s_mov_b32 m0, s40
	v_lshl_add_u64 v[250:251], s[10:11], 0, v[166:167]
	ds_read_b128 v[186:189], v179 offset:32768
	ds_read_b128 v[202:205], v179 offset:33792
	ds_read_b128 v[206:209], v179 offset:34816
	ds_read_b128 v[210:213], v179 offset:35840
	ds_read_b128 v[214:217], v179 offset:36864
	ds_read_b128 v[218:221], v179 offset:37888
	ds_read_b128 v[222:225], v179 offset:38912
	ds_read_b128 v[240:243], v179 offset:39936
	global_load_lds_dwordx4 v[250:251], off
	v_lshl_add_u64 v[250:251], s[10:11], 0, v[164:165]
	s_mov_b32 m0, s41
	s_nop 0
	global_load_lds_dwordx4 v[250:251], off
	s_waitcnt vmcnt(8)
	s_waitcnt lgkmcnt(0)
	s_barrier
	s_setprio 1
	v_mfma_f32_16x16x32_bf16 v[158:161], v[90:93], v[186:189], v[158:161]
	v_mfma_f32_16x16x32_bf16 v[154:157], v[98:101], v[186:189], v[154:157]
	v_mfma_f32_16x16x32_bf16 v[142:145], v[90:93], v[206:209], v[142:145]
	v_mfma_f32_16x16x32_bf16 v[138:141], v[98:101], v[206:209], v[138:141]
	v_mfma_f32_16x16x32_bf16 v[122:125], v[90:93], v[214:217], v[122:125]
	v_mfma_f32_16x16x32_bf16 v[110:113], v[98:101], v[214:217], v[110:113]
	v_mfma_f32_16x16x32_bf16 v[78:81], v[90:93], v[222:225], v[78:81]
	v_mfma_f32_16x16x32_bf16 v[74:77], v[98:101], v[222:225], v[74:77]
	v_mfma_f32_16x16x32_bf16 v[158:161], v[94:97], v[202:205], v[158:161]
	v_mfma_f32_16x16x32_bf16 v[154:157], v[102:105], v[202:205], v[154:157]
	v_mfma_f32_16x16x32_bf16 v[142:145], v[94:97], v[210:213], v[142:145]
	v_mfma_f32_16x16x32_bf16 v[138:141], v[102:105], v[210:213], v[138:141]
	v_mfma_f32_16x16x32_bf16 v[122:125], v[94:97], v[218:221], v[122:125]
	v_mfma_f32_16x16x32_bf16 v[110:113], v[102:105], v[218:221], v[110:113]
	v_mfma_f32_16x16x32_bf16 v[78:81], v[94:97], v[240:243], v[78:81]
	v_mfma_f32_16x16x32_bf16 v[74:77], v[102:105], v[240:243], v[74:77]
	s_setprio 0
	s_setprio 1
	v_mfma_f32_16x16x32_bf16 v[150:153], v[106:109], v[186:189], v[150:153]
	v_mfma_f32_16x16x32_bf16 v[146:149], v[118:121], v[186:189], v[146:149]
	v_mfma_f32_16x16x32_bf16 v[134:137], v[106:109], v[206:209], v[134:137]
	v_mfma_f32_16x16x32_bf16 v[130:133], v[118:121], v[206:209], v[130:133]
	v_mfma_f32_16x16x32_bf16 v[86:89], v[106:109], v[214:217], v[86:89]
	v_mfma_f32_16x16x32_bf16 v[82:85], v[118:121], v[214:217], v[82:85]
	v_mfma_f32_16x16x32_bf16 v[70:73], v[106:109], v[222:225], v[70:73]
	v_mfma_f32_16x16x32_bf16 v[66:69], v[118:121], v[222:225], v[66:69]
	v_mfma_f32_16x16x32_bf16 v[150:153], v[114:117], v[202:205], v[150:153]
	v_mfma_f32_16x16x32_bf16 v[146:149], v[126:129], v[202:205], v[146:149]
	v_mfma_f32_16x16x32_bf16 v[134:137], v[114:117], v[210:213], v[134:137]
	v_mfma_f32_16x16x32_bf16 v[130:133], v[126:129], v[210:213], v[130:133]
	v_mfma_f32_16x16x32_bf16 v[86:89], v[114:117], v[218:221], v[86:89]
	v_mfma_f32_16x16x32_bf16 v[82:85], v[126:129], v[218:221], v[82:85]
	v_mfma_f32_16x16x32_bf16 v[70:73], v[114:117], v[240:243], v[70:73]
	v_mfma_f32_16x16x32_bf16 v[66:69], v[126:129], v[240:243], v[66:69]
	s_setprio 0
	s_barrier
; #define PG8_STAGE(bufoff, gbase, voff) do { _Pragma("unroll") for (int _i = 0; _i < 2; ++_i) \
;         __builtin_amdgcn_global_load_lds((const unsigned*)((const char*)(gbase) + (voff)[_i]), (PG8_LAS unsigned*)(lds + (bufoff) + ldsw + _i * 8192), 16, 0, 0); } while (0)
; #define PG8_LDA(dst, b, h) do { _Pragma("unroll") for (int m = 0; m < 4; ++m) _Pragma("unroll") for (int k = 0; k < 2; ++k) dst[m][k] = *(const PG8_LAS bf16x8*)(lds + PG8_SA(b, h) + aoff + m * 2048 + k * 1024); } while (0)
; #define PG8_MMA(ai, bj, At, Bt) do { __builtin_amdgcn_s_setprio(1); _Pragma("unroll") for (int m = 0; m < 4; ++m) _Pragma("unroll") for (int n = 0; n < 2; ++n) _Pragma("unroll") for (int k = 0; k < 2; ++k) \
;         acc[ai][bj][m][n] = __builtin_amdgcn_mfma_f32_16x16x32_bf16(Bt[n][k], At[m][k], acc[ai][bj][m][n], 0, 0, 0); __builtin_amdgcn_s_setprio(0); } while (0)
; #define PG8_WAIT_V(n) asm volatile("s_waitcnt vmcnt(" #n ")" ::: "memory")
; #define PG8_WAIT_L(n) asm volatile("s_waitcnt lgkmcnt(" #n ")" ::: "memory")
; #define PG8_BAR __builtin_amdgcn_s_barrier()
; #define PG8_SCHED __builtin_amdgcn_sched_barrier(0)
; template <class Epi, class Sched, bool ALIGN_EPI = false, bool SP2 = false>
; __device__ __forceinline__ void gemm_phase(PG8_LAS unsigned char* lds, const Gemm g, const Sched& S, const Epi& E) {
;     ...
;         for (int t = 0; t < ntc; t += 2) {
;     ...
;             PG8_LDA(At, 1, 1); PG8_STAGE(PG8_SB(1, 0), b3, voffB); PG8_STAGE(PG8_SB(1, 1), b3 + hstepB, voffB); PG8_STAGE(PG8_SA(1, 0), a3, voffA);
;             PG8_WAIT_V(8); PG8_WAIT_L(0); PG8_BAR; PG8_MMA(1, 0, At, B0); PG8_MMA(1, 1, At, B1); PG8_BAR; PG8_SCHED;
	s_add_i32 s10, s34, s36
	v_lshl_add_u64 v[226:227], v[226:227], 0, s[88:89]
	s_mov_b32 m0, s10
	ds_read_b128 v[186:189], v179 offset:49152
	ds_read_b128 v[202:205], v179 offset:50176
	ds_read_b128 v[206:209], v179 offset:51200
	ds_read_b128 v[210:213], v179 offset:52224
	ds_read_b128 v[214:217], v179 offset:53248
	ds_read_b128 v[218:221], v179 offset:54272
	ds_read_b128 v[222:225], v179 offset:55296
	ds_read_b128 v[240:243], v179 offset:56320
	global_load_lds_dwordx4 v[226:227], off
	s_add_i32 m0, s10, 0x2000
	s_add_u32 s8, s8, 0x40080
	v_lshl_add_u64 v[226:227], v[244:245], 0, s[88:89]
	s_addc_u32 s9, s9, 0
	s_add_i32 s10, s35, s36
	global_load_lds_dwordx4 v[226:227], off
	v_lshl_add_u64 v[226:227], s[8:9], 0, v[64:65]
	s_mov_b32 m0, s10
	s_nop 0
	global_load_lds_dwordx4 v[226:227], off
	v_lshl_add_u64 v[226:227], s[8:9], 0, v[162:163]
	s_add_i32 m0, s10, 0x2000
	s_nop 0
	global_load_lds_dwordx4 v[226:227], off
	v_lshl_add_u64 v[226:227], v[246:247], 0, s[88:89]
	s_mov_b32 m0, s45
	s_nop 0
	global_load_lds_dwordx4 v[226:227], off
	v_lshl_add_u64 v[226:227], v[248:249], 0, s[88:89]
	s_mov_b32 m0, s46
	s_nop 0
	global_load_lds_dwordx4 v[226:227], off
	s_waitcnt vmcnt(8)
	s_waitcnt lgkmcnt(0)
	s_barrier
	s_setprio 1
	v_mfma_f32_16x16x32_bf16 v[60:63], v[90:93], v[186:189], v[60:63]
	v_mfma_f32_16x16x32_bf16 v[56:59], v[98:101], v[186:189], v[56:59]
	v_mfma_f32_16x16x32_bf16 v[44:47], v[90:93], v[206:209], v[44:47]
	v_mfma_f32_16x16x32_bf16 v[40:43], v[98:101], v[206:209], v[40:43]
	v_mfma_f32_16x16x32_bf16 v[28:31], v[90:93], v[214:217], v[28:31]
	v_mfma_f32_16x16x32_bf16 v[24:27], v[98:101], v[214:217], v[24:27]
	v_mfma_f32_16x16x32_bf16 v[12:15], v[90:93], v[222:225], v[12:15]
	v_mfma_f32_16x16x32_bf16 v[8:11], v[98:101], v[222:225], v[8:11]
	v_mfma_f32_16x16x32_bf16 v[60:63], v[94:97], v[202:205], v[60:63]
	v_mfma_f32_16x16x32_bf16 v[56:59], v[102:105], v[202:205], v[56:59]
	v_mfma_f32_16x16x32_bf16 v[44:47], v[94:97], v[210:213], v[44:47]
	v_mfma_f32_16x16x32_bf16 v[40:43], v[102:105], v[210:213], v[40:43]
	v_mfma_f32_16x16x32_bf16 v[28:31], v[94:97], v[218:221], v[28:31]
	v_mfma_f32_16x16x32_bf16 v[24:27], v[102:105], v[218:221], v[24:27]
	v_mfma_f32_16x16x32_bf16 v[12:15], v[94:97], v[240:243], v[12:15]
	v_mfma_f32_16x16x32_bf16 v[8:11], v[102:105], v[240:243], v[8:11]
	s_setprio 0
	s_setprio 1
	v_mfma_f32_16x16x32_bf16 v[52:55], v[106:109], v[186:189], v[52:55]
	v_mfma_f32_16x16x32_bf16 v[48:51], v[118:121], v[186:189], v[48:51]
	v_mfma_f32_16x16x32_bf16 v[36:39], v[106:109], v[206:209], v[36:39]
	v_mfma_f32_16x16x32_bf16 v[32:35], v[118:121], v[206:209], v[32:35]
	v_mfma_f32_16x16x32_bf16 v[20:23], v[106:109], v[214:217], v[20:23]
	v_mfma_f32_16x16x32_bf16 v[16:19], v[118:121], v[214:217], v[16:19]
	v_mfma_f32_16x16x32_bf16 v[4:7], v[106:109], v[222:225], v[4:7]
	v_mfma_f32_16x16x32_bf16 v[0:3], v[118:121], v[222:225], v[0:3]
	v_mfma_f32_16x16x32_bf16 v[52:55], v[114:117], v[202:205], v[52:55]
	v_mfma_f32_16x16x32_bf16 v[48:51], v[126:129], v[202:205], v[48:51]
	v_mfma_f32_16x16x32_bf16 v[36:39], v[114:117], v[210:213], v[36:39]
	v_mfma_f32_16x16x32_bf16 v[32:35], v[126:129], v[210:213], v[32:35]
	v_mfma_f32_16x16x32_bf16 v[20:23], v[114:117], v[218:221], v[20:23]
	v_mfma_f32_16x16x32_bf16 v[16:19], v[126:129], v[218:221], v[16:19]
	v_mfma_f32_16x16x32_bf16 v[4:7], v[114:117], v[240:243], v[4:7]
	v_mfma_f32_16x16x32_bf16 v[0:3], v[126:129], v[240:243], v[0:3]
	s_setprio 0
	s_barrier
	s_add_u32 s4, s4, 0x100
	s_addc_u32 s5, s5, 0
	s_add_u32 s29, s29, 0x100
	s_addc_u32 s30, s30, 0
	s_cmp_ge_i32 s31, s43
	s_mov_b32 s8, s31
	s_cbranch_scc0 .LBB0_746

; #define PG8_STAGE(bufoff, gbase, voff) do { _Pragma("unroll") for (int _i = 0; _i < 2; ++_i) \
;         __builtin_amdgcn_global_load_lds((const unsigned*)((const char*)(gbase) + (voff)[_i]), (PG8_LAS unsigned*)(lds + (bufoff) + ldsw + _i * 8192), 16, 0, 0); } while (0)
; #define PG8_LDA(dst, b, h) do { _Pragma("unroll") for (int m = 0; m < 4; ++m) _Pragma("unroll") for (int k = 0; k < 2; ++k) dst[m][k] = *(const PG8_LAS bf16x8*)(lds + PG8_SA(b, h) + aoff + m * 2048 + k * 1024); } while (0)
; #define PG8_LDB(dst, b, h) do { _Pragma("unroll") for (int n = 0; n < 2; ++n) _Pragma("unroll") for (int k = 0; k < 2; ++k) dst[n][k] = *(const PG8_LAS bf16x8*)(lds + PG8_SB(b, h) + boff + n * 2048 + k * 1024); } while (0)
; #define PG8_MMA(ai, bj, At, Bt) do { __builtin_amdgcn_s_setprio(1); _Pragma("unroll") for (int m = 0; m < 4; ++m) _Pragma("unroll") for (int n = 0; n < 2; ++n) _Pragma("unroll") for (int k = 0; k < 2; ++k) \
;         acc[ai][bj][m][n] = __builtin_amdgcn_mfma_f32_16x16x32_bf16(Bt[n][k], At[m][k], acc[ai][bj][m][n], 0, 0, 0); __builtin_amdgcn_s_setprio(0); } while (0)
; #define PG8_WAIT_V(n) asm volatile("s_waitcnt vmcnt(" #n ")" ::: "memory")
; #define PG8_WAIT_L(n) asm volatile("s_waitcnt lgkmcnt(" #n ")" ::: "memory")
; #define PG8_BAR __builtin_amdgcn_s_barrier()
; #define PG8_SCHED __builtin_amdgcn_sched_barrier(0)
; template <class Epi, class Sched, bool ALIGN_EPI = false, bool SP2 = false>
; __device__ __forceinline__ void gemm_phase(PG8_LAS unsigned char* lds, const Gemm g, const Sched& S, const Epi& E) {
;     ...
;         for (int t = 0; t < ntc; t += 2) {
;             const bool last = (t == ntc - 2);
;             const char* a1 = cA + (size_t)(t + 1) * kstep;
;             const char* a2 = last ? nA : cA + (size_t)(t + 2) * kstep; const char* b2 = last ? nB : cB + (size_t)(t + 2) * kstep;
;             const char* a3 = a2 + kstep; const char* b3 = b2 + kstep;
;             if (last && has_next) S.a_ready(nxt);
;             if constexpr (SP2) {
;             PG8_LDB(B0, 0, 0); PG8_LDB(B1, 0, 1); PG8_SCHED; PG8_LDA(At, 0, 0); PG8_STAGE(PG8_SA(1, 1), a1 + hstepA, voffA);
;             PG8_WAIT_V(8); PG8_WAIT_L(0); PG8_BAR; PG8_MMA(0, 0, At, B0); PG8_MMA(0, 1, At, B1); PG8_BAR; PG8_SCHED;
;             PG8_LDA(At, 0, 1); PG8_STAGE(PG8_SB(0, 0), b2, voffB); PG8_STAGE(PG8_SB(0, 1), b2 + hstepB, voffB); PG8_STAGE(PG8_SA(0, 0), a2, voffA);
.LBB0_905:
	s_add_i32 s48, s20, 2
	s_add_u32 s21, s18, 0xfffc0080
	s_addc_u32 s22, s19, -1
	s_add_i32 s49, 0, 0x10000
	s_cmp_eq_u32 s45, s20
	s_cselect_b32 s23, s13, s22
	s_cselect_b32 s22, s44, s21
	v_add_u32_e32 v149, s49, v145
	s_cselect_b32 s21, s15, s47
	s_cselect_b32 s20, s14, s46
	s_add_i32 s52, 0, 0x14000
	ds_read_b128 v[156:159], v149
	ds_read_b128 v[160:163], v149 offset:1024
	ds_read_b128 v[164:167], v149 offset:2048
	ds_read_b128 v[168:171], v149 offset:3072
	v_add_u32_e32 v149, s52, v145
	ds_read_b128 v[172:175], v149
	ds_read_b128 v[176:179], v149 offset:1024
	ds_read_b128 v[180:183], v149 offset:2048
	ds_read_b128 v[184:187], v149 offset:3072
	v_lshl_add_u64 v[188:189], s[18:19], 0, v[136:137]
	s_add_i32 m0, s2, 0xc000
	ds_read_b128 v[202:205], v147
	ds_read_b128 v[206:209], v147 offset:1024
	ds_read_b128 v[210:213], v147 offset:2048
	ds_read_b128 v[214:217], v147 offset:3072
	ds_read_b128 v[218:221], v147 offset:4096
	ds_read_b128 v[222:225], v147 offset:5120
	ds_read_b128 v[240:243], v147 offset:6144
	ds_read_b128 v[244:247], v147 offset:7168
	global_load_lds_dwordx4 v[188:189], off
	v_lshl_add_u64 v[188:189], s[18:19], 0, v[138:139]
	s_add_i32 m0, s2, 0xe000
	s_nop 0
	global_load_lds_dwordx4 v[188:189], off
	s_waitcnt vmcnt(8)
	s_waitcnt lgkmcnt(0)
	s_barrier
	s_setprio 1
	v_mfma_f32_16x16x32_bf16 v[126:129], v[156:159], v[202:205], v[126:129]
	v_mfma_f32_16x16x32_bf16 v[122:125], v[164:167], v[202:205], v[122:125]
	v_mfma_f32_16x16x32_bf16 v[118:121], v[156:159], v[210:213], v[118:121]
	v_mfma_f32_16x16x32_bf16 v[110:113], v[164:167], v[210:213], v[110:113]
	v_mfma_f32_16x16x32_bf16 v[102:105], v[156:159], v[218:221], v[102:105]
	v_mfma_f32_16x16x32_bf16 v[94:97], v[164:167], v[218:221], v[94:97]
	v_mfma_f32_16x16x32_bf16 v[86:89], v[156:159], v[240:243], v[86:89]
	v_mfma_f32_16x16x32_bf16 v[78:81], v[164:167], v[240:243], v[78:81]
	v_mfma_f32_16x16x32_bf16 v[126:129], v[160:163], v[206:209], v[126:129]
	v_mfma_f32_16x16x32_bf16 v[122:125], v[168:171], v[206:209], v[122:125]
	v_mfma_f32_16x16x32_bf16 v[118:121], v[160:163], v[214:217], v[118:121]
	v_mfma_f32_16x16x32_bf16 v[110:113], v[168:171], v[214:217], v[110:113]
	v_mfma_f32_16x16x32_bf16 v[102:105], v[160:163], v[222:225], v[102:105]
	v_mfma_f32_16x16x32_bf16 v[94:97], v[168:171], v[222:225], v[94:97]
	v_mfma_f32_16x16x32_bf16 v[86:89], v[160:163], v[244:247], v[86:89]
	v_mfma_f32_16x16x32_bf16 v[78:81], v[168:171], v[244:247], v[78:81]
	s_setprio 0
	s_setprio 1
	v_mfma_f32_16x16x32_bf16 v[114:117], v[172:175], v[202:205], v[114:117]
	v_mfma_f32_16x16x32_bf16 v[106:109], v[180:183], v[202:205], v[106:109]
	v_mfma_f32_16x16x32_bf16 v[98:101], v[172:175], v[210:213], v[98:101]
	v_mfma_f32_16x16x32_bf16 v[90:93], v[180:183], v[210:213], v[90:93]
	v_mfma_f32_16x16x32_bf16 v[82:85], v[172:175], v[218:221], v[82:85]
	v_mfma_f32_16x16x32_bf16 v[74:77], v[180:183], v[218:221], v[74:77]
	v_mfma_f32_16x16x32_bf16 v[70:73], v[172:175], v[240:243], v[70:73]
	v_mfma_f32_16x16x32_bf16 v[66:69], v[180:183], v[240:243], v[66:69]
	v_mfma_f32_16x16x32_bf16 v[114:117], v[176:179], v[206:209], v[114:117]
	v_mfma_f32_16x16x32_bf16 v[106:109], v[184:187], v[206:209], v[106:109]
	v_mfma_f32_16x16x32_bf16 v[98:101], v[176:179], v[214:217], v[98:101]
	v_mfma_f32_16x16x32_bf16 v[90:93], v[184:187], v[214:217], v[90:93]
	v_mfma_f32_16x16x32_bf16 v[82:85], v[176:179], v[222:225], v[82:85]
	v_mfma_f32_16x16x32_bf16 v[74:77], v[184:187], v[222:225], v[74:77]
	v_mfma_f32_16x16x32_bf16 v[70:73], v[176:179], v[244:247], v[70:73]
	v_mfma_f32_16x16x32_bf16 v[66:69], v[184:187], v[244:247], v[66:69]
	s_setprio 0
	s_barrier
	s_add_i32 s49, s49, s24
	v_lshl_add_u64 v[188:189], s[20:21], 0, v[64:65]
	s_mov_b32 m0, s49
	ds_read_b128 v[202:205], v147 offset:16384
	ds_read_b128 v[206:209], v147 offset:17408
	ds_read_b128 v[210:213], v147 offset:18432
	ds_read_b128 v[214:217], v147 offset:19456
	ds_read_b128 v[218:221], v147 offset:20480
	ds_read_b128 v[222:225], v147 offset:21504
	ds_read_b128 v[240:243], v147 offset:22528
	ds_read_b128 v[244:247], v147 offset:23552
	global_load_lds_dwordx4 v[188:189], off
	s_add_i32 m0, s49, 0x2000
	s_add_u32 s50, s20, 0x18000
	v_lshl_add_u64 v[226:227], s[20:21], 0, v[130:131]
	s_addc_u32 s51, s21, 0
	s_add_i32 s49, s52, s24
	global_load_lds_dwordx4 v[226:227], off
	v_lshl_add_u64 v[248:249], s[50:51], 0, v[64:65]
	s_mov_b32 m0, s49
	v_lshl_add_u64 v[250:251], s[22:23], 0, v[132:133]
	global_load_lds_dwordx4 v[248:249], off
	v_lshl_add_u64 v[248:249], s[50:51], 0, v[130:131]
	s_add_i32 m0, s49, 0x2000
	s_nop 0
	global_load_lds_dwordx4 v[248:249], off
	v_lshl_add_u64 v[248:249], s[22:23], 0, v[134:135]
	s_mov_b32 m0, s2
	s_nop 0
	global_load_lds_dwordx4 v[248:249], off
	s_mov_b32 m0, s34
	s_nop 0
	global_load_lds_dwordx4 v[250:251], off
	s_waitcnt vmcnt(8)
	s_waitcnt lgkmcnt(0)
	s_barrier
; #define PG8_STAGE(bufoff, gbase, voff) do { _Pragma("unroll") for (int _i = 0; _i < 2; ++_i) \
;         __builtin_amdgcn_global_load_lds((const unsigned*)((const char*)(gbase) + (voff)[_i]), (PG8_LAS unsigned*)(lds + (bufoff) + ldsw + _i * 8192), 16, 0, 0); } while (0)
; #define PG8_LDA(dst, b, h) do { _Pragma("unroll") for (int m = 0; m < 4; ++m) _Pragma("unroll") for (int k = 0; k < 2; ++k) dst[m][k] = *(const PG8_LAS bf16x8*)(lds + PG8_SA(b, h) + aoff + m * 2048 + k * 1024); } while (0)
; #define PG8_LDB(dst, b, h) do { _Pragma("unroll") for (int n = 0; n < 2; ++n) _Pragma("unroll") for (int k = 0; k < 2; ++k) dst[n][k] = *(const PG8_LAS bf16x8*)(lds + PG8_SB(b, h) + boff + n * 2048 + k * 1024); } while (0)
; #define PG8_MMA(ai, bj, At, Bt) do { __builtin_amdgcn_s_setprio(1); _Pragma("unroll") for (int m = 0; m < 4; ++m) _Pragma("unroll") for (int n = 0; n < 2; ++n) _Pragma("unroll") for (int k = 0; k < 2; ++k) \
;         acc[ai][bj][m][n] = __builtin_amdgcn_mfma_f32_16x16x32_bf16(Bt[n][k], At[m][k], acc[ai][bj][m][n], 0, 0, 0); __builtin_amdgcn_s_setprio(0); } while (0)
; #define PG8_WAIT_V(n) asm volatile("s_waitcnt vmcnt(" #n ")" ::: "memory")
; #define PG8_WAIT_L(n) asm volatile("s_waitcnt lgkmcnt(" #n ")" ::: "memory")
; #define PG8_BAR __builtin_amdgcn_s_barrier()
; #define PG8_SCHED __builtin_amdgcn_sched_barrier(0)
; template <class Epi, class Sched, bool ALIGN_EPI = false, bool SP2 = false>
; __device__ __forceinline__ void gemm_phase(PG8_LAS unsigned char* lds, const Gemm g, const Sched& S, const Epi& E) {
;     ...
;             PG8_WAIT_V(8); PG8_WAIT_L(0); PG8_BAR; PG8_MMA(1, 0, At, B0); PG8_MMA(1, 1, At, B1); PG8_BAR; PG8_SCHED;
;             PG8_LDB(B0, 1, 0); PG8_LDB(B1, 1, 1); PG8_SCHED; PG8_LDA(At, 1, 0); PG8_STAGE(PG8_SA(0, 1), a2 + hstepA, voffA);
;             PG8_WAIT_V(8); PG8_WAIT_L(0); PG8_BAR; PG8_MMA(0, 0, At, B0); PG8_MMA(0, 1, At, B1); PG8_BAR; PG8_SCHED;
	s_setprio 1
	v_mfma_f32_16x16x32_bf16 v[60:63], v[156:159], v[202:205], v[60:63]
	v_mfma_f32_16x16x32_bf16 v[56:59], v[164:167], v[202:205], v[56:59]
	v_mfma_f32_16x16x32_bf16 v[52:55], v[156:159], v[210:213], v[52:55]
	v_mfma_f32_16x16x32_bf16 v[44:47], v[164:167], v[210:213], v[44:47]
	v_mfma_f32_16x16x32_bf16 v[36:39], v[156:159], v[218:221], v[36:39]
	v_mfma_f32_16x16x32_bf16 v[28:31], v[164:167], v[218:221], v[28:31]
	v_mfma_f32_16x16x32_bf16 v[20:23], v[156:159], v[240:243], v[20:23]
	v_mfma_f32_16x16x32_bf16 v[12:15], v[164:167], v[240:243], v[12:15]
	v_mfma_f32_16x16x32_bf16 v[60:63], v[160:163], v[206:209], v[60:63]
	v_mfma_f32_16x16x32_bf16 v[56:59], v[168:171], v[206:209], v[56:59]
	v_mfma_f32_16x16x32_bf16 v[52:55], v[160:163], v[214:217], v[52:55]
	v_mfma_f32_16x16x32_bf16 v[44:47], v[168:171], v[214:217], v[44:47]
	v_mfma_f32_16x16x32_bf16 v[36:39], v[160:163], v[222:225], v[36:39]
	v_mfma_f32_16x16x32_bf16 v[28:31], v[168:171], v[222:225], v[28:31]
	v_mfma_f32_16x16x32_bf16 v[20:23], v[160:163], v[244:247], v[20:23]
	v_mfma_f32_16x16x32_bf16 v[12:15], v[168:171], v[244:247], v[12:15]
	s_setprio 0
	s_setprio 1
	v_mfma_f32_16x16x32_bf16 v[48:51], v[172:175], v[202:205], v[48:51]
	v_mfma_f32_16x16x32_bf16 v[40:43], v[180:183], v[202:205], v[40:43]
	v_mfma_f32_16x16x32_bf16 v[32:35], v[172:175], v[210:213], v[32:35]
	v_mfma_f32_16x16x32_bf16 v[24:27], v[180:183], v[210:213], v[24:27]
	v_mfma_f32_16x16x32_bf16 v[16:19], v[172:175], v[218:221], v[16:19]
	v_mfma_f32_16x16x32_bf16 v[8:11], v[180:183], v[218:221], v[8:11]
	v_mfma_f32_16x16x32_bf16 v[4:7], v[172:175], v[240:243], v[4:7]
	v_mfma_f32_16x16x32_bf16 v[0:3], v[180:183], v[240:243], v[0:3]
	v_mfma_f32_16x16x32_bf16 v[48:51], v[176:179], v[206:209], v[48:51]
	v_mfma_f32_16x16x32_bf16 v[40:43], v[184:187], v[206:209], v[40:43]
	v_mfma_f32_16x16x32_bf16 v[32:35], v[176:179], v[214:217], v[32:35]
	v_mfma_f32_16x16x32_bf16 v[24:27], v[184:187], v[214:217], v[24:27]
	v_mfma_f32_16x16x32_bf16 v[16:19], v[176:179], v[222:225], v[16:19]
	v_mfma_f32_16x16x32_bf16 v[8:11], v[184:187], v[222:225], v[8:11]
	v_mfma_f32_16x16x32_bf16 v[4:7], v[176:179], v[244:247], v[4:7]
	v_mfma_f32_16x16x32_bf16 v[0:3], v[184:187], v[244:247], v[0:3]
	s_setprio 0
	s_barrier
	s_add_i32 s49, 0, 0x18000
	v_add_u32_e32 v149, s49, v145
	s_add_i32 s50, 0, 0x1c000
	ds_read_b128 v[156:159], v149
	ds_read_b128 v[160:163], v149 offset:1024
	ds_read_b128 v[164:167], v149 offset:2048
	ds_read_b128 v[168:171], v149 offset:3072
	v_add_u32_e32 v149, s50, v145
	ds_read_b128 v[172:175], v149
	ds_read_b128 v[176:179], v149 offset:1024
	ds_read_b128 v[180:183], v149 offset:2048
	ds_read_b128 v[184:187], v149 offset:3072
	s_add_u32 s22, s22, 0x40000
	s_addc_u32 s23, s23, 0
	s_mov_b32 m0, s35
	v_lshl_add_u64 v[252:253], s[22:23], 0, v[134:135]
	ds_read_b128 v[202:205], v147 offset:32768
	ds_read_b128 v[206:209], v147 offset:33792
	ds_read_b128 v[210:213], v147 offset:34816
	ds_read_b128 v[214:217], v147 offset:35840
	ds_read_b128 v[218:221], v147 offset:36864
	ds_read_b128 v[222:225], v147 offset:37888
	ds_read_b128 v[240:243], v147 offset:38912
	ds_read_b128 v[244:247], v147 offset:39936
	global_load_lds_dwordx4 v[252:253], off
	v_lshl_add_u64 v[252:253], s[22:23], 0, v[132:133]
	s_mov_b32 m0, s36
	s_nop 0
	global_load_lds_dwordx4 v[252:253], off
	s_waitcnt vmcnt(8)
	s_waitcnt lgkmcnt(0)
	s_barrier
	s_setprio 1
	v_mfma_f32_16x16x32_bf16 v[126:129], v[156:159], v[202:205], v[126:129]
	v_mfma_f32_16x16x32_bf16 v[122:125], v[164:167], v[202:205], v[122:125]
	v_mfma_f32_16x16x32_bf16 v[118:121], v[156:159], v[210:213], v[118:121]
	v_mfma_f32_16x16x32_bf16 v[110:113], v[164:167], v[210:213], v[110:113]
	v_mfma_f32_16x16x32_bf16 v[102:105], v[156:159], v[218:221], v[102:105]
	v_mfma_f32_16x16x32_bf16 v[94:97], v[164:167], v[218:221], v[94:97]
	v_mfma_f32_16x16x32_bf16 v[86:89], v[156:159], v[240:243], v[86:89]
	v_mfma_f32_16x16x32_bf16 v[78:81], v[164:167], v[240:243], v[78:81]
	v_mfma_f32_16x16x32_bf16 v[126:129], v[160:163], v[206:209], v[126:129]
	v_mfma_f32_16x16x32_bf16 v[122:125], v[168:171], v[206:209], v[122:125]
	v_mfma_f32_16x16x32_bf16 v[118:121], v[160:163], v[214:217], v[118:121]
	v_mfma_f32_16x16x32_bf16 v[110:113], v[168:171], v[214:217], v[110:113]
	v_mfma_f32_16x16x32_bf16 v[102:105], v[160:163], v[222:225], v[102:105]
	v_mfma_f32_16x16x32_bf16 v[94:97], v[168:171], v[222:225], v[94:97]
	v_mfma_f32_16x16x32_bf16 v[86:89], v[160:163], v[244:247], v[86:89]
	v_mfma_f32_16x16x32_bf16 v[78:81], v[168:171], v[244:247], v[78:81]
	s_setprio 0
	s_setprio 1
	v_mfma_f32_16x16x32_bf16 v[114:117], v[172:175], v[202:205], v[114:117]
	v_mfma_f32_16x16x32_bf16 v[106:109], v[180:183], v[202:205], v[106:109]
	v_mfma_f32_16x16x32_bf16 v[98:101], v[172:175], v[210:213], v[98:101]
	v_mfma_f32_16x16x32_bf16 v[90:93], v[180:183], v[210:213], v[90:93]
	v_mfma_f32_16x16x32_bf16 v[82:85], v[172:175], v[218:221], v[82:85]
	v_mfma_f32_16x16x32_bf16 v[74:77], v[180:183], v[218:221], v[74:77]
	v_mfma_f32_16x16x32_bf16 v[70:73], v[172:175], v[240:243], v[70:73]
	v_mfma_f32_16x16x32_bf16 v[66:69], v[180:183], v[240:243], v[66:69]
	v_mfma_f32_16x16x32_bf16 v[114:117], v[176:179], v[206:209], v[114:117]
	v_mfma_f32_16x16x32_bf16 v[106:109], v[184:187], v[206:209], v[106:109]
	v_mfma_f32_16x16x32_bf16 v[98:101], v[176:179], v[214:217], v[98:101]
	v_mfma_f32_16x16x32_bf16 v[90:93], v[184:187], v[214:217], v[90:93]
	v_mfma_f32_16x16x32_bf16 v[82:85], v[176:179], v[222:225], v[82:85]
	v_mfma_f32_16x16x32_bf16 v[74:77], v[184:187], v[222:225], v[74:77]
	v_mfma_f32_16x16x32_bf16 v[70:73], v[176:179], v[244:247], v[70:73]
	v_mfma_f32_16x16x32_bf16 v[66:69], v[184:187], v[244:247], v[66:69]
	s_setprio 0
	s_barrier
; #define PG8_STAGE(bufoff, gbase, voff) do { _Pragma("unroll") for (int _i = 0; _i < 2; ++_i) \
;         __builtin_amdgcn_global_load_lds((const unsigned*)((const char*)(gbase) + (voff)[_i]), (PG8_LAS unsigned*)(lds + (bufoff) + ldsw + _i * 8192), 16, 0, 0); } while (0)
; #define PG8_LDA(dst, b, h) do { _Pragma("unroll") for (int m = 0; m < 4; ++m) _Pragma("unroll") for (int k = 0; k < 2; ++k) dst[m][k] = *(const PG8_LAS bf16x8*)(lds + PG8_SA(b, h) + aoff + m * 2048 + k * 1024); } while (0)
; #define PG8_MMA(ai, bj, At, Bt) do { __builtin_amdgcn_s_setprio(1); _Pragma("unroll") for (int m = 0; m < 4; ++m) _Pragma("unroll") for (int n = 0; n < 2; ++n) _Pragma("unroll") for (int k = 0; k < 2; ++k) \
;         acc[ai][bj][m][n] = __builtin_amdgcn_mfma_f32_16x16x32_bf16(Bt[n][k], At[m][k], acc[ai][bj][m][n], 0, 0, 0); __builtin_amdgcn_s_setprio(0); } while (0)
; #define PG8_WAIT_V(n) asm volatile("s_waitcnt vmcnt(" #n ")" ::: "memory")
; #define PG8_WAIT_L(n) asm volatile("s_waitcnt lgkmcnt(" #n ")" ::: "memory")
; #define PG8_BAR __builtin_amdgcn_s_barrier()
; #define PG8_SCHED __builtin_amdgcn_sched_barrier(0)
; template <class Epi, class Sched, bool ALIGN_EPI = false, bool SP2 = false>
; __device__ __forceinline__ void gemm_phase(PG8_LAS unsigned char* lds, const Gemm g, const Sched& S, const Epi& E) {
;     ...
;             PG8_LDA(At, 1, 1); PG8_STAGE(PG8_SB(1, 0), b3, voffB); PG8_STAGE(PG8_SB(1, 1), b3 + hstepB, voffB); PG8_STAGE(PG8_SA(1, 0), a3, voffA);
;             PG8_WAIT_V(8); PG8_WAIT_L(0); PG8_BAR; PG8_MMA(1, 0, At, B0); PG8_MMA(1, 1, At, B1); PG8_BAR; PG8_SCHED;
;     ...
;         if constexpr (ALIGN_EPI) { if (wr == 0) PG8_BAR; }
	s_add_i32 s22, s49, s24
	v_lshl_add_u64 v[188:189], v[188:189], 0, s[88:89]
	s_mov_b32 m0, s22
	ds_read_b128 v[202:205], v147 offset:49152
	ds_read_b128 v[206:209], v147 offset:50176
	ds_read_b128 v[210:213], v147 offset:51200
	ds_read_b128 v[214:217], v147 offset:52224
	ds_read_b128 v[218:221], v147 offset:53248
	ds_read_b128 v[222:225], v147 offset:54272
	ds_read_b128 v[240:243], v147 offset:55296
	ds_read_b128 v[244:247], v147 offset:56320
	global_load_lds_dwordx4 v[188:189], off
	s_add_i32 m0, s22, 0x2000
	s_add_u32 s20, s20, 0x18080
	v_lshl_add_u64 v[188:189], v[226:227], 0, s[88:89]
	s_addc_u32 s21, s21, 0
	s_add_i32 s22, s50, s24
	global_load_lds_dwordx4 v[188:189], off
	v_lshl_add_u64 v[188:189], s[20:21], 0, v[64:65]
	s_mov_b32 m0, s22
	s_nop 0
	global_load_lds_dwordx4 v[188:189], off
	v_lshl_add_u64 v[188:189], s[20:21], 0, v[130:131]
	s_add_i32 m0, s22, 0x2000
	s_nop 0
	global_load_lds_dwordx4 v[188:189], off
	v_lshl_add_u64 v[188:189], v[248:249], 0, s[88:89]
	s_mov_b32 m0, s37
	s_nop 0
	global_load_lds_dwordx4 v[188:189], off
	v_lshl_add_u64 v[188:189], v[250:251], 0, s[88:89]
	s_mov_b32 m0, s38
	s_nop 0
	global_load_lds_dwordx4 v[188:189], off
	s_waitcnt vmcnt(8)
	s_waitcnt lgkmcnt(0)
	s_barrier
	s_setprio 1
	v_mfma_f32_16x16x32_bf16 v[60:63], v[156:159], v[202:205], v[60:63]
	v_mfma_f32_16x16x32_bf16 v[56:59], v[164:167], v[202:205], v[56:59]
	v_mfma_f32_16x16x32_bf16 v[52:55], v[156:159], v[210:213], v[52:55]
	v_mfma_f32_16x16x32_bf16 v[44:47], v[164:167], v[210:213], v[44:47]
	v_mfma_f32_16x16x32_bf16 v[36:39], v[156:159], v[218:221], v[36:39]
	v_mfma_f32_16x16x32_bf16 v[28:31], v[164:167], v[218:221], v[28:31]
	v_mfma_f32_16x16x32_bf16 v[20:23], v[156:159], v[240:243], v[20:23]
	v_mfma_f32_16x16x32_bf16 v[12:15], v[164:167], v[240:243], v[12:15]
	v_mfma_f32_16x16x32_bf16 v[60:63], v[160:163], v[206:209], v[60:63]
	v_mfma_f32_16x16x32_bf16 v[56:59], v[168:171], v[206:209], v[56:59]
	v_mfma_f32_16x16x32_bf16 v[52:55], v[160:163], v[214:217], v[52:55]
	v_mfma_f32_16x16x32_bf16 v[44:47], v[168:171], v[214:217], v[44:47]
	v_mfma_f32_16x16x32_bf16 v[36:39], v[160:163], v[222:225], v[36:39]
	v_mfma_f32_16x16x32_bf16 v[28:31], v[168:171], v[222:225], v[28:31]
	v_mfma_f32_16x16x32_bf16 v[20:23], v[160:163], v[244:247], v[20:23]
	v_mfma_f32_16x16x32_bf16 v[12:15], v[168:171], v[244:247], v[12:15]
	s_setprio 0
	s_setprio 1
	v_mfma_f32_16x16x32_bf16 v[48:51], v[172:175], v[202:205], v[48:51]
	v_mfma_f32_16x16x32_bf16 v[40:43], v[180:183], v[202:205], v[40:43]
	v_mfma_f32_16x16x32_bf16 v[32:35], v[172:175], v[210:213], v[32:35]
	v_mfma_f32_16x16x32_bf16 v[24:27], v[180:183], v[210:213], v[24:27]
	v_mfma_f32_16x16x32_bf16 v[16:19], v[172:175], v[218:221], v[16:19]
	v_mfma_f32_16x16x32_bf16 v[8:11], v[180:183], v[218:221], v[8:11]
	v_mfma_f32_16x16x32_bf16 v[4:7], v[172:175], v[240:243], v[4:7]
	v_mfma_f32_16x16x32_bf16 v[0:3], v[180:183], v[240:243], v[0:3]
	v_mfma_f32_16x16x32_bf16 v[48:51], v[176:179], v[206:209], v[48:51]
	v_mfma_f32_16x16x32_bf16 v[40:43], v[184:187], v[206:209], v[40:43]
	v_mfma_f32_16x16x32_bf16 v[32:35], v[176:179], v[214:217], v[32:35]
	v_mfma_f32_16x16x32_bf16 v[24:27], v[184:187], v[214:217], v[24:27]
	v_mfma_f32_16x16x32_bf16 v[16:19], v[176:179], v[222:225], v[16:19]
	v_mfma_f32_16x16x32_bf16 v[8:11], v[184:187], v[222:225], v[8:11]
	v_mfma_f32_16x16x32_bf16 v[4:7], v[176:179], v[244:247], v[4:7]
	v_mfma_f32_16x16x32_bf16 v[0:3], v[184:187], v[244:247], v[0:3]
	s_setprio 0
	s_barrier
	s_add_u32 s18, s18, 0x100
	s_addc_u32 s19, s19, 0
	s_add_u32 s46, s46, 0x100
	s_addc_u32 s47, s47, 0
	s_cmp_ge_u32 s48, s43
	s_mov_b32 s20, s48
	s_cbranch_scc0 .LBB0_905
	s_and_b64 vcc, exec, s[10:11]
	s_cbranch_vccz .LBB0_908
	s_barrier

; #define PG8_STAGE(bufoff, gbase, voff) do { _Pragma("unroll") for (int _i = 0; _i < 2; ++_i) \
;         __builtin_amdgcn_global_load_lds((const unsigned*)((const char*)(gbase) + (voff)[_i]), (PG8_LAS unsigned*)(lds + (bufoff) + ldsw + _i * 8192), 16, 0, 0); } while (0)
; #define PG8_LDA(dst, b, h) do { _Pragma("unroll") for (int m = 0; m < 4; ++m) _Pragma("unroll") for (int k = 0; k < 2; ++k) dst[m][k] = *(const PG8_LAS bf16x8*)(lds + PG8_SA(b, h) + aoff + m * 2048 + k * 1024); } while (0)
; #define PG8_LDB(dst, b, h) do { _Pragma("unroll") for (int n = 0; n < 2; ++n) _Pragma("unroll") for (int k = 0; k < 2; ++k) dst[n][k] = *(const PG8_LAS bf16x8*)(lds + PG8_SB(b, h) + boff + n * 2048 + k * 1024); } while (0)
; #define PG8_MMA(ai, bj, At, Bt) do { __builtin_amdgcn_s_setprio(1); _Pragma("unroll") for (int m = 0; m < 4; ++m) _Pragma("unroll") for (int n = 0; n < 2; ++n) _Pragma("unroll") for (int k = 0; k < 2; ++k) \
;         acc[ai][bj][m][n] = __builtin_amdgcn_mfma_f32_16x16x32_bf16(Bt[n][k], At[m][k], acc[ai][bj][m][n], 0, 0, 0); __builtin_amdgcn_s_setprio(0); } while (0)
; #define PG8_WAIT_V(n) asm volatile("s_waitcnt vmcnt(" #n ")" ::: "memory")
; #define PG8_WAIT_L(n) asm volatile("s_waitcnt lgkmcnt(" #n ")" ::: "memory")
; #define PG8_BAR __builtin_amdgcn_s_barrier()
; #define PG8_SCHED __builtin_amdgcn_sched_barrier(0)
; template <class Epi, class Sched, bool ALIGN_EPI = false, bool SP2 = false>
; __device__ __forceinline__ void gemm_phase(PG8_LAS unsigned char* lds, const Gemm g, const Sched& S, const Epi& E) {
;     ...
;         for (int t = 0; t < ntc; t += 2) {
;             const bool last = (t == ntc - 2);
;             const char* a1 = cA + (size_t)(t + 1) * kstep;
;             const char* a2 = last ? nA : cA + (size_t)(t + 2) * kstep; const char* b2 = last ? nB : cB + (size_t)(t + 2) * kstep;
;             const char* a3 = a2 + kstep; const char* b3 = b2 + kstep;
;             if (last && has_next) S.a_ready(nxt);
;             if constexpr (SP2) {
;             PG8_LDB(B0, 0, 0); PG8_LDB(B1, 0, 1); PG8_SCHED; PG8_LDA(At, 0, 0); PG8_STAGE(PG8_SA(1, 1), a1 + hstepA, voffA);
;             PG8_WAIT_V(8); PG8_WAIT_L(0); PG8_BAR; PG8_MMA(0, 0, At, B0); PG8_MMA(0, 1, At, B1); PG8_BAR; PG8_SCHED;
;             PG8_LDA(At, 0, 1); PG8_STAGE(PG8_SB(0, 0), b2, voffB); PG8_STAGE(PG8_SB(0, 1), b2 + hstepB, voffB); PG8_STAGE(PG8_SA(0, 0), a2, voffA);
.LBB0_1187:
	s_add_i32 s49, s22, 2
	s_add_u32 s23, s4, 0xfffc0080
	s_addc_u32 s24, s5, -1
	s_add_i32 s50, 0, 0x10000
	s_cmp_eq_u32 s40, s22
	s_cselect_b32 s25, s13, s24
	s_cselect_b32 s24, s15, s23
	s_cselect_b32 s23, s45, s48
	s_cselect_b32 s22, s46, s47
	s_add_i32 s52, 0, 0x14000
	v_add_u32_e32 v142, s50, v218
	v_add_u32_e32 v158, s52, v218
	ds_read_b128 v[130:133], v142
	ds_read_b128 v[134:137], v142 offset:1024
	ds_read_b128 v[138:141], v142 offset:2048
	ds_read_b128 v[142:145], v142 offset:3072
	ds_read_b128 v[146:149], v158
	ds_read_b128 v[150:153], v158 offset:1024
	ds_read_b128 v[154:157], v158 offset:2048
	ds_read_b128 v[158:161], v158 offset:3072
	v_lshl_add_u64 v[220:221], s[4:5], 0, v[208:209]
	s_add_i32 m0, s29, 0xc000
	ds_read_b128 v[162:165], v219
	ds_read_b128 v[166:169], v219 offset:1024
	ds_read_b128 v[170:173], v219 offset:2048
	ds_read_b128 v[174:177], v219 offset:3072
	ds_read_b128 v[178:181], v219 offset:4096
	ds_read_b128 v[182:185], v219 offset:5120
	ds_read_b128 v[186:189], v219 offset:6144
	ds_read_b128 v[212:215], v219 offset:7168
	global_load_lds_dwordx4 v[220:221], off
	v_lshl_add_u64 v[220:221], s[4:5], 0, v[210:211]
	s_add_i32 m0, s29, 0xe000
	s_nop 0
	global_load_lds_dwordx4 v[220:221], off
	s_waitcnt vmcnt(8)
	s_waitcnt lgkmcnt(0)
	s_barrier
	s_setprio 1
	v_mfma_f32_16x16x32_bf16 v[122:125], v[130:133], v[162:165], v[122:125]
	v_mfma_f32_16x16x32_bf16 v[126:129], v[138:141], v[162:165], v[126:129]
	v_mfma_f32_16x16x32_bf16 v[110:113], v[130:133], v[170:173], v[110:113]
	v_mfma_f32_16x16x32_bf16 v[106:109], v[138:141], v[170:173], v[106:109]
	v_mfma_f32_16x16x32_bf16 v[94:97], v[130:133], v[178:181], v[94:97]
	v_mfma_f32_16x16x32_bf16 v[90:93], v[138:141], v[178:181], v[90:93]
	v_mfma_f32_16x16x32_bf16 v[78:81], v[130:133], v[186:189], v[78:81]
	v_mfma_f32_16x16x32_bf16 v[74:77], v[138:141], v[186:189], v[74:77]
	v_mfma_f32_16x16x32_bf16 v[122:125], v[134:137], v[166:169], v[122:125]
	v_mfma_f32_16x16x32_bf16 v[126:129], v[142:145], v[166:169], v[126:129]
	v_mfma_f32_16x16x32_bf16 v[110:113], v[134:137], v[174:177], v[110:113]
	v_mfma_f32_16x16x32_bf16 v[106:109], v[142:145], v[174:177], v[106:109]
	v_mfma_f32_16x16x32_bf16 v[94:97], v[134:137], v[182:185], v[94:97]
	v_mfma_f32_16x16x32_bf16 v[90:93], v[142:145], v[182:185], v[90:93]
	v_mfma_f32_16x16x32_bf16 v[78:81], v[134:137], v[212:215], v[78:81]
	v_mfma_f32_16x16x32_bf16 v[74:77], v[142:145], v[212:215], v[74:77]
	s_setprio 0
	s_setprio 1
	v_mfma_f32_16x16x32_bf16 v[118:121], v[146:149], v[162:165], v[118:121]
	v_mfma_f32_16x16x32_bf16 v[114:117], v[154:157], v[162:165], v[114:117]
	v_mfma_f32_16x16x32_bf16 v[102:105], v[146:149], v[170:173], v[102:105]
	v_mfma_f32_16x16x32_bf16 v[98:101], v[154:157], v[170:173], v[98:101]
	v_mfma_f32_16x16x32_bf16 v[86:89], v[146:149], v[178:181], v[86:89]
	v_mfma_f32_16x16x32_bf16 v[82:85], v[154:157], v[178:181], v[82:85]
	v_mfma_f32_16x16x32_bf16 v[70:73], v[146:149], v[186:189], v[70:73]
	v_mfma_f32_16x16x32_bf16 v[66:69], v[154:157], v[186:189], v[66:69]
	v_mfma_f32_16x16x32_bf16 v[118:121], v[150:153], v[166:169], v[118:121]
	v_mfma_f32_16x16x32_bf16 v[114:117], v[158:161], v[166:169], v[114:117]
	v_mfma_f32_16x16x32_bf16 v[102:105], v[150:153], v[174:177], v[102:105]
	v_mfma_f32_16x16x32_bf16 v[98:101], v[158:161], v[174:177], v[98:101]
	v_mfma_f32_16x16x32_bf16 v[86:89], v[150:153], v[182:185], v[86:89]
	v_mfma_f32_16x16x32_bf16 v[82:85], v[158:161], v[182:185], v[82:85]
	v_mfma_f32_16x16x32_bf16 v[70:73], v[150:153], v[212:215], v[70:73]
	v_mfma_f32_16x16x32_bf16 v[66:69], v[158:161], v[212:215], v[66:69]
	s_setprio 0
	s_barrier
	s_add_i32 s50, s50, s26
	v_lshl_add_u64 v[220:221], s[22:23], 0, v[64:65]
	s_mov_b32 m0, s50
	ds_read_b128 v[162:165], v219 offset:16384
	ds_read_b128 v[166:169], v219 offset:17408
	ds_read_b128 v[170:173], v219 offset:18432
	ds_read_b128 v[174:177], v219 offset:19456
	ds_read_b128 v[178:181], v219 offset:20480
	ds_read_b128 v[182:185], v219 offset:21504
	ds_read_b128 v[186:189], v219 offset:22528
	ds_read_b128 v[212:215], v219 offset:23552
	global_load_lds_dwordx4 v[220:221], off
	s_add_i32 m0, s50, 0x2000
	s_add_u32 s50, s22, 0x40000
	v_lshl_add_u64 v[222:223], s[22:23], 0, v[202:203]
	s_addc_u32 s51, s23, 0
	s_add_i32 s52, s52, s26
	global_load_lds_dwordx4 v[222:223], off
	v_lshl_add_u64 v[224:225], s[50:51], 0, v[64:65]
	s_mov_b32 m0, s52
	v_lshl_add_u64 v[226:227], s[24:25], 0, v[204:205]
	global_load_lds_dwordx4 v[224:225], off
	v_lshl_add_u64 v[224:225], s[50:51], 0, v[202:203]
	s_add_i32 m0, s52, 0x2000
	s_nop 0
	global_load_lds_dwordx4 v[224:225], off
	v_lshl_add_u64 v[224:225], s[24:25], 0, v[206:207]
	s_mov_b32 m0, s29
	s_nop 0
	global_load_lds_dwordx4 v[224:225], off
	s_mov_b32 m0, s30
	s_nop 0
	global_load_lds_dwordx4 v[226:227], off
	s_waitcnt vmcnt(8)
	s_waitcnt lgkmcnt(0)
	s_barrier
; #define PG8_STAGE(bufoff, gbase, voff) do { _Pragma("unroll") for (int _i = 0; _i < 2; ++_i) \
;         __builtin_amdgcn_global_load_lds((const unsigned*)((const char*)(gbase) + (voff)[_i]), (PG8_LAS unsigned*)(lds + (bufoff) + ldsw + _i * 8192), 16, 0, 0); } while (0)
; #define PG8_LDA(dst, b, h) do { _Pragma("unroll") for (int m = 0; m < 4; ++m) _Pragma("unroll") for (int k = 0; k < 2; ++k) dst[m][k] = *(const PG8_LAS bf16x8*)(lds + PG8_SA(b, h) + aoff + m * 2048 + k * 1024); } while (0)
; #define PG8_LDB(dst, b, h) do { _Pragma("unroll") for (int n = 0; n < 2; ++n) _Pragma("unroll") for (int k = 0; k < 2; ++k) dst[n][k] = *(const PG8_LAS bf16x8*)(lds + PG8_SB(b, h) + boff + n * 2048 + k * 1024); } while (0)
; #define PG8_MMA(ai, bj, At, Bt) do { __builtin_amdgcn_s_setprio(1); _Pragma("unroll") for (int m = 0; m < 4; ++m) _Pragma("unroll") for (int n = 0; n < 2; ++n) _Pragma("unroll") for (int k = 0; k < 2; ++k) \
;         acc[ai][bj][m][n] = __builtin_amdgcn_mfma_f32_16x16x32_bf16(Bt[n][k], At[m][k], acc[ai][bj][m][n], 0, 0, 0); __builtin_amdgcn_s_setprio(0); } while (0)
; #define PG8_WAIT_V(n) asm volatile("s_waitcnt vmcnt(" #n ")" ::: "memory")
; #define PG8_WAIT_L(n) asm volatile("s_waitcnt lgkmcnt(" #n ")" ::: "memory")
; #define PG8_BAR __builtin_amdgcn_s_barrier()
; #define PG8_SCHED __builtin_amdgcn_sched_barrier(0)
; template <class Epi, class Sched, bool ALIGN_EPI = false, bool SP2 = false>
; __device__ __forceinline__ void gemm_phase(PG8_LAS unsigned char* lds, const Gemm g, const Sched& S, const Epi& E) {
;     ...
;             PG8_WAIT_V(8); PG8_WAIT_L(0); PG8_BAR; PG8_MMA(1, 0, At, B0); PG8_MMA(1, 1, At, B1); PG8_BAR; PG8_SCHED;
;             PG8_LDB(B0, 1, 0); PG8_LDB(B1, 1, 1); PG8_SCHED; PG8_LDA(At, 1, 0); PG8_STAGE(PG8_SA(0, 1), a2 + hstepA, voffA);
;             PG8_WAIT_V(8); PG8_WAIT_L(0); PG8_BAR; PG8_MMA(0, 0, At, B0); PG8_MMA(0, 1, At, B1); PG8_BAR; PG8_SCHED;
	s_setprio 1
	v_mfma_f32_16x16x32_bf16 v[60:63], v[130:133], v[162:165], v[60:63]
	v_mfma_f32_16x16x32_bf16 v[56:59], v[138:141], v[162:165], v[56:59]
	v_mfma_f32_16x16x32_bf16 v[44:47], v[130:133], v[170:173], v[44:47]
	v_mfma_f32_16x16x32_bf16 v[40:43], v[138:141], v[170:173], v[40:43]
	v_mfma_f32_16x16x32_bf16 v[28:31], v[130:133], v[178:181], v[28:31]
	v_mfma_f32_16x16x32_bf16 v[24:27], v[138:141], v[178:181], v[24:27]
	v_mfma_f32_16x16x32_bf16 v[12:15], v[130:133], v[186:189], v[12:15]
	v_mfma_f32_16x16x32_bf16 v[8:11], v[138:141], v[186:189], v[8:11]
	v_mfma_f32_16x16x32_bf16 v[60:63], v[134:137], v[166:169], v[60:63]
	v_mfma_f32_16x16x32_bf16 v[56:59], v[142:145], v[166:169], v[56:59]
	v_mfma_f32_16x16x32_bf16 v[44:47], v[134:137], v[174:177], v[44:47]
	v_mfma_f32_16x16x32_bf16 v[40:43], v[142:145], v[174:177], v[40:43]
	v_mfma_f32_16x16x32_bf16 v[28:31], v[134:137], v[182:185], v[28:31]
	v_mfma_f32_16x16x32_bf16 v[24:27], v[142:145], v[182:185], v[24:27]
	v_mfma_f32_16x16x32_bf16 v[12:15], v[134:137], v[212:215], v[12:15]
	v_mfma_f32_16x16x32_bf16 v[8:11], v[142:145], v[212:215], v[8:11]
	s_setprio 0
	s_setprio 1
	v_mfma_f32_16x16x32_bf16 v[52:55], v[146:149], v[162:165], v[52:55]
	v_mfma_f32_16x16x32_bf16 v[48:51], v[154:157], v[162:165], v[48:51]
	v_mfma_f32_16x16x32_bf16 v[36:39], v[146:149], v[170:173], v[36:39]
	v_mfma_f32_16x16x32_bf16 v[32:35], v[154:157], v[170:173], v[32:35]
	v_mfma_f32_16x16x32_bf16 v[20:23], v[146:149], v[178:181], v[20:23]
	v_mfma_f32_16x16x32_bf16 v[16:19], v[154:157], v[178:181], v[16:19]
	v_mfma_f32_16x16x32_bf16 v[4:7], v[146:149], v[186:189], v[4:7]
	v_mfma_f32_16x16x32_bf16 v[0:3], v[154:157], v[186:189], v[0:3]
	v_mfma_f32_16x16x32_bf16 v[52:55], v[150:153], v[166:169], v[52:55]
	v_mfma_f32_16x16x32_bf16 v[48:51], v[158:161], v[166:169], v[48:51]
	v_mfma_f32_16x16x32_bf16 v[36:39], v[150:153], v[174:177], v[36:39]
	v_mfma_f32_16x16x32_bf16 v[32:35], v[158:161], v[174:177], v[32:35]
	v_mfma_f32_16x16x32_bf16 v[20:23], v[150:153], v[182:185], v[20:23]
	v_mfma_f32_16x16x32_bf16 v[16:19], v[158:161], v[182:185], v[16:19]
	v_mfma_f32_16x16x32_bf16 v[4:7], v[150:153], v[212:215], v[4:7]
	v_mfma_f32_16x16x32_bf16 v[0:3], v[158:161], v[212:215], v[0:3]
	s_setprio 0
	s_barrier
	s_add_i32 s50, 0, 0x18000
	s_add_i32 s51, 0, 0x1c000
	v_add_u32_e32 v142, s50, v218
	v_add_u32_e32 v158, s51, v218
	ds_read_b128 v[130:133], v142
	ds_read_b128 v[134:137], v142 offset:1024
	ds_read_b128 v[138:141], v142 offset:2048
	ds_read_b128 v[142:145], v142 offset:3072
	ds_read_b128 v[146:149], v158
	ds_read_b128 v[150:153], v158 offset:1024
	ds_read_b128 v[154:157], v158 offset:2048
	ds_read_b128 v[158:161], v158 offset:3072
	s_add_u32 s24, s24, 0x40000
	s_addc_u32 s25, s25, 0
	s_mov_b32 m0, s31
	v_lshl_add_u64 v[240:241], s[24:25], 0, v[206:207]
	ds_read_b128 v[162:165], v219 offset:32768
	ds_read_b128 v[166:169], v219 offset:33792
	ds_read_b128 v[170:173], v219 offset:34816
	ds_read_b128 v[174:177], v219 offset:35840
	ds_read_b128 v[178:181], v219 offset:36864
	ds_read_b128 v[182:185], v219 offset:37888
	ds_read_b128 v[186:189], v219 offset:38912
	ds_read_b128 v[212:215], v219 offset:39936
	global_load_lds_dwordx4 v[240:241], off
	v_lshl_add_u64 v[240:241], s[24:25], 0, v[204:205]
	s_mov_b32 m0, s34
	s_nop 0
	global_load_lds_dwordx4 v[240:241], off
	s_waitcnt vmcnt(8)
	s_waitcnt lgkmcnt(0)
	s_barrier
	s_setprio 1
	v_mfma_f32_16x16x32_bf16 v[122:125], v[130:133], v[162:165], v[122:125]
	v_mfma_f32_16x16x32_bf16 v[126:129], v[138:141], v[162:165], v[126:129]
	v_mfma_f32_16x16x32_bf16 v[110:113], v[130:133], v[170:173], v[110:113]
	v_mfma_f32_16x16x32_bf16 v[106:109], v[138:141], v[170:173], v[106:109]
	v_mfma_f32_16x16x32_bf16 v[94:97], v[130:133], v[178:181], v[94:97]
	v_mfma_f32_16x16x32_bf16 v[90:93], v[138:141], v[178:181], v[90:93]
	v_mfma_f32_16x16x32_bf16 v[78:81], v[130:133], v[186:189], v[78:81]
	v_mfma_f32_16x16x32_bf16 v[74:77], v[138:141], v[186:189], v[74:77]
	v_mfma_f32_16x16x32_bf16 v[122:125], v[134:137], v[166:169], v[122:125]
	v_mfma_f32_16x16x32_bf16 v[126:129], v[142:145], v[166:169], v[126:129]
	v_mfma_f32_16x16x32_bf16 v[110:113], v[134:137], v[174:177], v[110:113]
	v_mfma_f32_16x16x32_bf16 v[106:109], v[142:145], v[174:177], v[106:109]
	v_mfma_f32_16x16x32_bf16 v[94:97], v[134:137], v[182:185], v[94:97]
	v_mfma_f32_16x16x32_bf16 v[90:93], v[142:145], v[182:185], v[90:93]
	v_mfma_f32_16x16x32_bf16 v[78:81], v[134:137], v[212:215], v[78:81]
	v_mfma_f32_16x16x32_bf16 v[74:77], v[142:145], v[212:215], v[74:77]
	s_setprio 0
	s_setprio 1
	v_mfma_f32_16x16x32_bf16 v[118:121], v[146:149], v[162:165], v[118:121]
	v_mfma_f32_16x16x32_bf16 v[114:117], v[154:157], v[162:165], v[114:117]
	v_mfma_f32_16x16x32_bf16 v[102:105], v[146:149], v[170:173], v[102:105]
	v_mfma_f32_16x16x32_bf16 v[98:101], v[154:157], v[170:173], v[98:101]
	v_mfma_f32_16x16x32_bf16 v[86:89], v[146:149], v[178:181], v[86:89]
	v_mfma_f32_16x16x32_bf16 v[82:85], v[154:157], v[178:181], v[82:85]
	v_mfma_f32_16x16x32_bf16 v[70:73], v[146:149], v[186:189], v[70:73]
	v_mfma_f32_16x16x32_bf16 v[66:69], v[154:157], v[186:189], v[66:69]
	v_mfma_f32_16x16x32_bf16 v[118:121], v[150:153], v[166:169], v[118:121]
	v_mfma_f32_16x16x32_bf16 v[114:117], v[158:161], v[166:169], v[114:117]
	v_mfma_f32_16x16x32_bf16 v[102:105], v[150:153], v[174:177], v[102:105]
	v_mfma_f32_16x16x32_bf16 v[98:101], v[158:161], v[174:177], v[98:101]
	v_mfma_f32_16x16x32_bf16 v[86:89], v[150:153], v[182:185], v[86:89]
	v_mfma_f32_16x16x32_bf16 v[82:85], v[158:161], v[182:185], v[82:85]
	v_mfma_f32_16x16x32_bf16 v[70:73], v[150:153], v[212:215], v[70:73]
	v_mfma_f32_16x16x32_bf16 v[66:69], v[158:161], v[212:215], v[66:69]
	s_setprio 0
	s_barrier
; #define PG8_STAGE(bufoff, gbase, voff) do { _Pragma("unroll") for (int _i = 0; _i < 2; ++_i) \
;         __builtin_amdgcn_global_load_lds((const unsigned*)((const char*)(gbase) + (voff)[_i]), (PG8_LAS unsigned*)(lds + (bufoff) + ldsw + _i * 8192), 16, 0, 0); } while (0)
; #define PG8_LDA(dst, b, h) do { _Pragma("unroll") for (int m = 0; m < 4; ++m) _Pragma("unroll") for (int k = 0; k < 2; ++k) dst[m][k] = *(const PG8_LAS bf16x8*)(lds + PG8_SA(b, h) + aoff + m * 2048 + k * 1024); } while (0)
; #define PG8_MMA(ai, bj, At, Bt) do { __builtin_amdgcn_s_setprio(1); _Pragma("unroll") for (int m = 0; m < 4; ++m) _Pragma("unroll") for (int n = 0; n < 2; ++n) _Pragma("unroll") for (int k = 0; k < 2; ++k) \
;         acc[ai][bj][m][n] = __builtin_amdgcn_mfma_f32_16x16x32_bf16(Bt[n][k], At[m][k], acc[ai][bj][m][n], 0, 0, 0); __builtin_amdgcn_s_setprio(0); } while (0)
; #define PG8_WAIT_V(n) asm volatile("s_waitcnt vmcnt(" #n ")" ::: "memory")
; #define PG8_WAIT_L(n) asm volatile("s_waitcnt lgkmcnt(" #n ")" ::: "memory")
; #define PG8_BAR __builtin_amdgcn_s_barrier()
; #define PG8_SCHED __builtin_amdgcn_sched_barrier(0)
; template <class Epi, class Sched, bool ALIGN_EPI = false, bool SP2 = false>
; __device__ __forceinline__ void gemm_phase(PG8_LAS unsigned char* lds, const Gemm g, const Sched& S, const Epi& E) {
;     ...
;         for (int t = 0; t < ntc; t += 2) {
;     ...
;             PG8_LDA(At, 1, 1); PG8_STAGE(PG8_SB(1, 0), b3, voffB); PG8_STAGE(PG8_SB(1, 1), b3 + hstepB, voffB); PG8_STAGE(PG8_SA(1, 0), a3, voffA);
;             PG8_WAIT_V(8); PG8_WAIT_L(0); PG8_BAR; PG8_MMA(1, 0, At, B0); PG8_MMA(1, 1, At, B1); PG8_BAR; PG8_SCHED;
	s_add_i32 s24, s50, s26
	v_lshl_add_u64 v[220:221], v[220:221], 0, s[88:89]
	s_mov_b32 m0, s24
	ds_read_b128 v[162:165], v219 offset:49152
	ds_read_b128 v[166:169], v219 offset:50176
	ds_read_b128 v[170:173], v219 offset:51200
	ds_read_b128 v[174:177], v219 offset:52224
	ds_read_b128 v[178:181], v219 offset:53248
	ds_read_b128 v[182:185], v219 offset:54272
	ds_read_b128 v[186:189], v219 offset:55296
	ds_read_b128 v[212:215], v219 offset:56320
	global_load_lds_dwordx4 v[220:221], off
	s_add_i32 m0, s24, 0x2000
	s_add_u32 s22, s22, 0x40080
	v_lshl_add_u64 v[220:221], v[222:223], 0, s[88:89]
	s_addc_u32 s23, s23, 0
	s_add_i32 s24, s51, s26
	global_load_lds_dwordx4 v[220:221], off
	v_lshl_add_u64 v[220:221], s[22:23], 0, v[64:65]
	s_mov_b32 m0, s24
	s_nop 0
	global_load_lds_dwordx4 v[220:221], off
	v_lshl_add_u64 v[220:221], s[22:23], 0, v[202:203]
	s_add_i32 m0, s24, 0x2000
	s_nop 0
	global_load_lds_dwordx4 v[220:221], off
	v_lshl_add_u64 v[220:221], v[224:225], 0, s[88:89]
	s_mov_b32 m0, s38
	s_nop 0
	global_load_lds_dwordx4 v[220:221], off
	v_lshl_add_u64 v[220:221], v[226:227], 0, s[88:89]
	s_mov_b32 m0, s39
	s_nop 0
	global_load_lds_dwordx4 v[220:221], off
	s_waitcnt vmcnt(8)
	s_waitcnt lgkmcnt(0)
	s_barrier
	s_setprio 1
	v_mfma_f32_16x16x32_bf16 v[60:63], v[130:133], v[162:165], v[60:63]
	v_mfma_f32_16x16x32_bf16 v[56:59], v[138:141], v[162:165], v[56:59]
	v_mfma_f32_16x16x32_bf16 v[44:47], v[130:133], v[170:173], v[44:47]
	v_mfma_f32_16x16x32_bf16 v[40:43], v[138:141], v[170:173], v[40:43]
	v_mfma_f32_16x16x32_bf16 v[28:31], v[130:133], v[178:181], v[28:31]
	v_mfma_f32_16x16x32_bf16 v[24:27], v[138:141], v[178:181], v[24:27]
	v_mfma_f32_16x16x32_bf16 v[12:15], v[130:133], v[186:189], v[12:15]
	v_mfma_f32_16x16x32_bf16 v[8:11], v[138:141], v[186:189], v[8:11]
	v_mfma_f32_16x16x32_bf16 v[60:63], v[134:137], v[166:169], v[60:63]
	v_mfma_f32_16x16x32_bf16 v[56:59], v[142:145], v[166:169], v[56:59]
	v_mfma_f32_16x16x32_bf16 v[44:47], v[134:137], v[174:177], v[44:47]
	v_mfma_f32_16x16x32_bf16 v[40:43], v[142:145], v[174:177], v[40:43]
	v_mfma_f32_16x16x32_bf16 v[28:31], v[134:137], v[182:185], v[28:31]
	v_mfma_f32_16x16x32_bf16 v[24:27], v[142:145], v[182:185], v[24:27]
	v_mfma_f32_16x16x32_bf16 v[12:15], v[134:137], v[212:215], v[12:15]
	v_mfma_f32_16x16x32_bf16 v[8:11], v[142:145], v[212:215], v[8:11]
	s_setprio 0
	s_setprio 1
	v_mfma_f32_16x16x32_bf16 v[52:55], v[146:149], v[162:165], v[52:55]
	v_mfma_f32_16x16x32_bf16 v[48:51], v[154:157], v[162:165], v[48:51]
	v_mfma_f32_16x16x32_bf16 v[36:39], v[146:149], v[170:173], v[36:39]
	v_mfma_f32_16x16x32_bf16 v[32:35], v[154:157], v[170:173], v[32:35]
	v_mfma_f32_16x16x32_bf16 v[20:23], v[146:149], v[178:181], v[20:23]
	v_mfma_f32_16x16x32_bf16 v[16:19], v[154:157], v[178:181], v[16:19]
	v_mfma_f32_16x16x32_bf16 v[4:7], v[146:149], v[186:189], v[4:7]
	v_mfma_f32_16x16x32_bf16 v[0:3], v[154:157], v[186:189], v[0:3]
	v_mfma_f32_16x16x32_bf16 v[52:55], v[150:153], v[166:169], v[52:55]
	v_mfma_f32_16x16x32_bf16 v[48:51], v[158:161], v[166:169], v[48:51]
	v_mfma_f32_16x16x32_bf16 v[36:39], v[150:153], v[174:177], v[36:39]
	v_mfma_f32_16x16x32_bf16 v[32:35], v[158:161], v[174:177], v[32:35]
	v_mfma_f32_16x16x32_bf16 v[20:23], v[150:153], v[182:185], v[20:23]
	v_mfma_f32_16x16x32_bf16 v[16:19], v[158:161], v[182:185], v[16:19]
	v_mfma_f32_16x16x32_bf16 v[4:7], v[150:153], v[212:215], v[4:7]
	v_mfma_f32_16x16x32_bf16 v[0:3], v[158:161], v[212:215], v[0:3]
	s_setprio 0
	s_barrier
	s_add_u32 s4, s4, 0x100
	s_addc_u32 s5, s5, 0
	s_add_u32 s47, s47, 0x100
	s_addc_u32 s48, s48, 0
	s_cmp_ge_i32 s49, s36
	s_mov_b32 s22, s49
	s_cbranch_scc0 .LBB0_1187
